# wave-specialized overlap: SGU LayerNorm-parameter LDS staging done by wave 1 before the hand-off counter wait (on v25)
# baseline (speedup 1.0000x reference)
.LBB0_391:
	s_cmpk_gt_i32 s64, 0x7f
	s_cselect_b64 s[8:9], -1, 0
	s_and_b64 s[8:9], s[40:41], s[8:9]
	s_andn2_b64 vcc, exec, s[8:9]
	s_cbranch_vccnz .LBB0_419
	v_add_u32_e32 v2, 0xffffffc0, v224
	v_cmp_gt_u32_e32 vcc, 64, v2
	s_and_saveexec_b64 s[90:91], vcc
	s_cbranch_execz .Lsgu_stage_0
	s_load_dwordx4 s[84:87], s[36:37], 0x40
	s_and_b32 s88, s64, 3
	s_lshl_b32 s88, s88, 9
	v_lshlrev_b32_e32 v0, 3, v2
	v_add_u32_e32 v0, s88, v0
	v_lshlrev_b32_e32 v1, 4, v2
	v_add_u32_e32 v1, 0x22800, v1
	s_waitcnt lgkmcnt(0)
	global_load_dwordx2 v[4:5], v0, s[84:85]
	global_load_dwordx2 v[6:7], v0, s[86:87]
	s_waitcnt vmcnt(0)
	ds_write_b128 v1, v[4:7]
	s_waitcnt lgkmcnt(0)
.Lsgu_stage_0:
	s_or_b64 exec, exec, s[90:91]
	s_and_saveexec_b64 s[8:9], s[4:5]
	s_cbranch_execz .LBB0_402
	s_mov_b32 s12, 0x400001
	v_mov_b32_e32 v0, 0
	s_movk_i32 s13, 0xff
	s_movk_i32 s14, 0x100
	s_branch .LBB0_395

.LBB0_402:
	s_or_b64 exec, exec, s[8:9]
	v_mov_b32_e32 v108, v224
	s_waitcnt vmcnt(0)
	s_barrier
	s_load_dwordx8 s[8:15], s[36:37], 0x40
	v_mov_b32_e32 v255, 0x22800
	s_movk_i32 s16, 0x80
	v_readfirstlane_b32 s39, v108
	s_ashr_i32 s41, s39, 7
	s_cmp_eq_u32 s41, 2
	s_cselect_b32 s16, s16, 0x100
	s_cmp_lg_u32 s41, 1
	s_cselect_b32 s16, s16, 0
	s_cmpk_gt_u32 s39, 0x7f
	s_cselect_b32 s16, s16, 0xffffff80
	s_add_i32 s16, s16, s64
	s_mov_b32 s17, 0
	s_lshr_b32 s16, s16, 2
	v_and_b32_e32 v109, 0x7f, v108
	s_lshl_b64 s[18:19], s[16:17], 7
	v_or_b32_e32 v2, s18, v109
	s_movk_i32 s16, 0x1400
	v_mov_b64_e32 v[0:1], s[22:23]
	v_mad_u64_u32 v[0:1], s[26:27], v2, s16, v[0:1]
	s_lshl_b32 s16, s64, 7
	v_mov_b32_e32 v2, 0x1400
	s_and_b32 s37, s16, 0x180
	v_mad_u32_u24 v1, s19, v2, v1
	s_lshl_b32 s16, s37, 1
	v_lshl_add_u64 v[4:5], v[0:1], 0, s[16:17]
	s_movk_i32 s17, 0x1000
	v_add_co_u32_e32 v0, vcc, s17, v4
	s_mov_b32 s38, 0x3d372713
	s_nop 0
	v_addc_co_u32_e32 v1, vcc, 0, v5, vcc
	global_load_dwordx4 v[0:3], v[0:1], off
	s_mov_b32 s36, 0xc0135761
	s_mov_b64 s[26:27], 0x1000
	v_lshl_add_u64 v[4:5], v[4:5], 0, s[26:27]
	global_load_dwordx4 v[172:175], v[4:5], off offset:16
	global_load_dwordx4 v[176:179], v[4:5], off offset:32
	global_load_dwordx4 v[180:183], v[4:5], off offset:48
	global_load_dwordx4 v[184:187], v[4:5], off offset:64
	global_load_dwordx4 v[188:191], v[4:5], off offset:80
	global_load_dwordx4 v[192:195], v[4:5], off offset:96
	global_load_dwordx4 v[196:199], v[4:5], off offset:112
	global_load_dwordx4 v[200:203], v[4:5], off offset:128
	global_load_dwordx4 v[204:207], v[4:5], off offset:144
	global_load_dwordx4 v[208:211], v[4:5], off offset:160
	global_load_dwordx4 v[212:215], v[4:5], off offset:176
	global_load_dwordx4 v[216:219], v[4:5], off offset:192
	global_load_dwordx4 v[220:223], v[4:5], off offset:208
	global_load_dwordx4 v[228:231], v[4:5], off offset:224
	global_load_dwordx4 v[232:235], v[4:5], off offset:240
	s_lshl_b32 s17, s37, 2
	s_brev_b32 s40, 60
	s_waitcnt vmcnt(15)
	v_lshlrev_b32_e32 v6, 16, v0
	v_and_b32_e32 v7, 0xffff0000, v0
	v_lshlrev_b32_e32 v0, 16, v1
	v_and_b32_e32 v1, 0xffff0000, v1
	v_lshlrev_b32_e32 v8, 16, v2
	v_and_b32_e32 v9, 0xffff0000, v2
	v_lshlrev_b32_e32 v2, 16, v3
	v_and_b32_e32 v3, 0xffff0000, v3
	v_pk_mul_f32 v[10:11], v[6:7], v[6:7]
	v_pk_mul_f32 v[12:13], v[0:1], v[0:1]
	v_pk_mul_f32 v[14:15], v[8:9], v[8:9]
	v_pk_mul_f32 v[16:17], v[2:3], v[2:3]
	v_pk_fma_f32 v[10:11], v[10:11], s[38:39], 1.0 op_sel_hi:[1,0,0]
	v_pk_fma_f32 v[12:13], v[12:13], s[38:39], 1.0 op_sel_hi:[1,0,0]
	v_pk_fma_f32 v[14:15], v[14:15], s[38:39], 1.0 op_sel_hi:[1,0,0]
	v_pk_fma_f32 v[16:17], v[16:17], s[38:39], 1.0 op_sel_hi:[1,0,0]
	v_pk_mul_f32 v[10:11], v[10:11], v[6:7]
	v_pk_mul_f32 v[12:13], v[12:13], v[0:1]
	v_pk_mul_f32 v[14:15], v[14:15], v[8:9]
	v_pk_mul_f32 v[16:17], v[16:17], v[2:3]
	v_pk_mul_f32 v[10:11], v[10:11], s[36:37] op_sel_hi:[1,0]
	v_pk_mul_f32 v[12:13], v[12:13], s[36:37] op_sel_hi:[1,0]
	v_pk_mul_f32 v[14:15], v[14:15], s[36:37] op_sel_hi:[1,0]
	v_pk_mul_f32 v[16:17], v[16:17], s[36:37] op_sel_hi:[1,0]
	v_exp_f32_e32 v10, v10
	v_exp_f32_e32 v11, v11
	v_exp_f32_e32 v12, v12
	v_exp_f32_e32 v13, v13
	v_exp_f32_e32 v14, v14
	v_exp_f32_e32 v15, v15
	v_exp_f32_e32 v16, v16
	v_exp_f32_e32 v17, v17
	v_pk_add_f32 v[10:11], v[10:11], 1.0 op_sel_hi:[1,0]
	v_pk_add_f32 v[12:13], v[12:13], 1.0 op_sel_hi:[1,0]
	v_pk_add_f32 v[18:19], v[14:15], 1.0 op_sel_hi:[1,0]
	v_pk_add_f32 v[16:17], v[16:17], 1.0 op_sel_hi:[1,0]
	v_rcp_f32_e32 v14, v10
	v_rcp_f32_e32 v15, v11
	v_rcp_f32_e32 v10, v12
	v_rcp_f32_e32 v11, v13
	v_rcp_f32_e32 v12, v18
	v_rcp_f32_e32 v13, v19
	v_rcp_f32_e32 v18, v16
	v_rcp_f32_e32 v19, v17
	v_pk_mul_f32 v[16:17], v[14:15], v[6:7]
	v_pk_mul_f32 v[10:11], v[10:11], v[0:1]
	v_pk_mul_f32 v[8:9], v[12:13], v[8:9]
	v_pk_mul_f32 v[12:13], v[18:19], v[2:3]
	v_cvt_pk_bf16_f32 v114, v16, v17
	v_cvt_pk_bf16_f32 v112, v10, v11
	v_cvt_pk_bf16_f32 v111, v8, v9
	v_pk_fma_f32 v[6:7], v[14:15], v[6:7], v[16:17] op_sel_hi:[1,1,0]
	v_cvt_pk_bf16_f32 v110, v12, v13
	v_pk_mul_f32 v[14:15], v[16:17], v[16:17]
	v_pk_mul_f32 v[16:17], v[10:11], v[10:11]
	v_mov_b32_e32 v165, v10
	v_mov_b32_e32 v164, v14
	v_mov_b32_e32 v10, v15
	v_mov_b32_e32 v6, v16
	v_mov_b32_e32 v167, v8
	v_pk_add_f32 v[10:11], v[164:165], v[10:11]
	v_pk_mul_f32 v[162:163], v[12:13], v[12:13]
	v_mov_b32_e32 v169, v12
	v_mov_b32_e32 v168, v162
	v_mov_b32_e32 v12, v163
	v_pk_add_f32 v[12:13], v[168:169], v[12:13]
	s_waitcnt vmcnt(14)
	v_mov_b32_e32 v0, v172
	v_mov_b32_e32 v1, v173
	v_mov_b32_e32 v2, v174
	v_mov_b32_e32 v3, v175
	v_lshlrev_b32_e32 v18, 16, v0
	v_and_b32_e32 v19, 0xffff0000, v0
	v_lshlrev_b32_e32 v0, 16, v1
	v_and_b32_e32 v1, 0xffff0000, v1
	v_lshlrev_b32_e32 v24, 16, v2
	v_and_b32_e32 v25, 0xffff0000, v2
	v_lshlrev_b32_e32 v2, 16, v3
	v_and_b32_e32 v3, 0xffff0000, v3
	v_pk_mul_f32 v[20:21], v[18:19], v[18:19]
	v_pk_mul_f32 v[22:23], v[0:1], v[0:1]
	v_pk_mul_f32 v[26:27], v[24:25], v[24:25]
	v_pk_mul_f32 v[28:29], v[2:3], v[2:3]
	v_pk_fma_f32 v[20:21], v[20:21], s[38:39], 1.0 op_sel_hi:[1,0,0]
	v_pk_fma_f32 v[22:23], v[22:23], s[38:39], 1.0 op_sel_hi:[1,0,0]
	v_pk_fma_f32 v[26:27], v[26:27], s[38:39], 1.0 op_sel_hi:[1,0,0]
	v_pk_fma_f32 v[28:29], v[28:29], s[38:39], 1.0 op_sel_hi:[1,0,0]
	v_pk_mul_f32 v[20:21], v[20:21], v[18:19]
	v_pk_mul_f32 v[22:23], v[22:23], v[0:1]
	v_pk_mul_f32 v[26:27], v[26:27], v[24:25]
	v_pk_mul_f32 v[28:29], v[28:29], v[2:3]
	v_pk_mul_f32 v[20:21], v[20:21], s[36:37] op_sel_hi:[1,0]
	v_pk_mul_f32 v[22:23], v[22:23], s[36:37] op_sel_hi:[1,0]
	v_pk_mul_f32 v[26:27], v[26:27], s[36:37] op_sel_hi:[1,0]
	v_pk_mul_f32 v[28:29], v[28:29], s[36:37] op_sel_hi:[1,0]
	v_exp_f32_e32 v20, v20
	v_exp_f32_e32 v21, v21
	v_exp_f32_e32 v22, v22
	v_exp_f32_e32 v23, v23
	v_exp_f32_e32 v26, v26
	v_exp_f32_e32 v27, v27
	v_exp_f32_e32 v28, v28
	v_exp_f32_e32 v29, v29
	v_pk_add_f32 v[20:21], v[20:21], 1.0 op_sel_hi:[1,0]
	v_pk_add_f32 v[22:23], v[22:23], 1.0 op_sel_hi:[1,0]
	v_pk_add_f32 v[26:27], v[26:27], 1.0 op_sel_hi:[1,0]
	v_pk_add_f32 v[28:29], v[28:29], 1.0 op_sel_hi:[1,0]
	v_rcp_f32_e32 v20, v20
	v_rcp_f32_e32 v21, v21
	v_rcp_f32_e32 v30, v22
	v_rcp_f32_e32 v31, v23
	v_rcp_f32_e32 v26, v26
	v_rcp_f32_e32 v27, v27
	v_rcp_f32_e32 v28, v28
	v_rcp_f32_e32 v29, v29
	v_pk_mul_f32 v[22:23], v[20:21], v[18:19]
	v_pk_mul_f32 v[20:21], v[30:31], v[0:1]
	v_pk_mul_f32 v[18:19], v[26:27], v[24:25]
	v_pk_mul_f32 v[24:25], v[28:29], v[2:3]
	v_cvt_pk_bf16_f32 v117, v22, v23
	v_cvt_pk_bf16_f32 v116, v20, v21
	v_cvt_pk_bf16_f32 v115, v18, v19
	v_mov_b32_e32 v163, v18
	v_cvt_pk_bf16_f32 v113, v24, v25
	v_pk_mul_f32 v[14:15], v[24:25], v[24:25]
	v_mov_b32_e32 v165, v24
	v_mov_b32_e32 v164, v14
	v_mov_b32_e32 v24, v15
	v_pk_add_f32 v[14:15], v[164:165], v[24:25]
	s_waitcnt vmcnt(13)
	v_mov_b32_e32 v0, v176
	v_mov_b32_e32 v1, v177
	v_mov_b32_e32 v2, v178
	v_mov_b32_e32 v3, v179
	v_lshlrev_b32_e32 v26, 16, v0
	v_and_b32_e32 v27, 0xffff0000, v0
	v_lshlrev_b32_e32 v0, 16, v1
	v_and_b32_e32 v1, 0xffff0000, v1
	v_lshlrev_b32_e32 v32, 16, v2
	v_and_b32_e32 v33, 0xffff0000, v2
	v_lshlrev_b32_e32 v2, 16, v3
	v_and_b32_e32 v3, 0xffff0000, v3
	v_pk_mul_f32 v[28:29], v[26:27], v[26:27]
	v_pk_mul_f32 v[30:31], v[0:1], v[0:1]
	v_pk_mul_f32 v[34:35], v[32:33], v[32:33]
	v_pk_mul_f32 v[36:37], v[2:3], v[2:3]
	v_pk_fma_f32 v[28:29], v[28:29], s[38:39], 1.0 op_sel_hi:[1,0,0]
	v_pk_fma_f32 v[30:31], v[30:31], s[38:39], 1.0 op_sel_hi:[1,0,0]
	v_pk_fma_f32 v[34:35], v[34:35], s[38:39], 1.0 op_sel_hi:[1,0,0]
	v_pk_fma_f32 v[36:37], v[36:37], s[38:39], 1.0 op_sel_hi:[1,0,0]
	v_pk_mul_f32 v[28:29], v[28:29], v[26:27]
	v_pk_mul_f32 v[30:31], v[30:31], v[0:1]
	v_pk_mul_f32 v[34:35], v[34:35], v[32:33]
	v_pk_mul_f32 v[36:37], v[36:37], v[2:3]
	v_pk_mul_f32 v[28:29], v[28:29], s[36:37] op_sel_hi:[1,0]
	v_pk_mul_f32 v[30:31], v[30:31], s[36:37] op_sel_hi:[1,0]
	v_pk_mul_f32 v[34:35], v[34:35], s[36:37] op_sel_hi:[1,0]
	v_pk_mul_f32 v[36:37], v[36:37], s[36:37] op_sel_hi:[1,0]
	v_exp_f32_e32 v28, v28
	v_exp_f32_e32 v29, v29
	v_exp_f32_e32 v30, v30
	v_exp_f32_e32 v31, v31
	v_exp_f32_e32 v34, v34
	v_exp_f32_e32 v35, v35
	v_exp_f32_e32 v36, v36
	v_exp_f32_e32 v37, v37
	v_pk_add_f32 v[28:29], v[28:29], 1.0 op_sel_hi:[1,0]
	v_pk_add_f32 v[30:31], v[30:31], 1.0 op_sel_hi:[1,0]
	v_pk_add_f32 v[34:35], v[34:35], 1.0 op_sel_hi:[1,0]
	v_pk_add_f32 v[36:37], v[36:37], 1.0 op_sel_hi:[1,0]
	v_rcp_f32_e32 v28, v28
	v_rcp_f32_e32 v29, v29
	v_rcp_f32_e32 v38, v30
	v_rcp_f32_e32 v39, v31
	v_rcp_f32_e32 v34, v34
	v_rcp_f32_e32 v35, v35
	v_rcp_f32_e32 v36, v36
	v_rcp_f32_e32 v37, v37
	v_pk_mul_f32 v[30:31], v[28:29], v[26:27]
	v_pk_mul_f32 v[28:29], v[38:39], v[0:1]
	v_pk_mul_f32 v[26:27], v[34:35], v[32:33]
	v_pk_mul_f32 v[32:33], v[36:37], v[2:3]
	v_cvt_pk_bf16_f32 v122, v30, v31
	v_cvt_pk_bf16_f32 v120, v28, v29
	v_cvt_pk_bf16_f32 v119, v26, v27
	s_nop 0
	v_cvt_pk_bf16_f32 v118, v32, v33
	s_waitcnt vmcnt(12)
	v_mov_b32_e32 v0, v180
	v_mov_b32_e32 v1, v181
	v_mov_b32_e32 v2, v182
	v_mov_b32_e32 v3, v183
	v_lshlrev_b32_e32 v34, 16, v0
	v_and_b32_e32 v35, 0xffff0000, v0
	v_lshlrev_b32_e32 v0, 16, v1
	v_and_b32_e32 v1, 0xffff0000, v1
	v_lshlrev_b32_e32 v40, 16, v2
	v_and_b32_e32 v41, 0xffff0000, v2
	v_lshlrev_b32_e32 v2, 16, v3
	v_and_b32_e32 v3, 0xffff0000, v3
	v_pk_mul_f32 v[36:37], v[34:35], v[34:35]
	v_pk_mul_f32 v[38:39], v[0:1], v[0:1]
	v_pk_mul_f32 v[42:43], v[40:41], v[40:41]
	v_pk_mul_f32 v[44:45], v[2:3], v[2:3]
	v_pk_fma_f32 v[36:37], v[36:37], s[38:39], 1.0 op_sel_hi:[1,0,0]
	v_pk_fma_f32 v[38:39], v[38:39], s[38:39], 1.0 op_sel_hi:[1,0,0]
	v_pk_fma_f32 v[42:43], v[42:43], s[38:39], 1.0 op_sel_hi:[1,0,0]
	v_pk_fma_f32 v[44:45], v[44:45], s[38:39], 1.0 op_sel_hi:[1,0,0]
	v_pk_mul_f32 v[36:37], v[36:37], v[34:35]
	v_pk_mul_f32 v[38:39], v[38:39], v[0:1]
	v_pk_mul_f32 v[42:43], v[42:43], v[40:41]
	v_pk_mul_f32 v[44:45], v[44:45], v[2:3]
	v_pk_mul_f32 v[36:37], v[36:37], s[36:37] op_sel_hi:[1,0]
	v_pk_mul_f32 v[38:39], v[38:39], s[36:37] op_sel_hi:[1,0]
	v_pk_mul_f32 v[42:43], v[42:43], s[36:37] op_sel_hi:[1,0]
	v_pk_mul_f32 v[44:45], v[44:45], s[36:37] op_sel_hi:[1,0]
	v_exp_f32_e32 v36, v36
	v_exp_f32_e32 v37, v37
	v_exp_f32_e32 v38, v38
	v_exp_f32_e32 v39, v39
	v_exp_f32_e32 v42, v42
	v_exp_f32_e32 v43, v43
	v_exp_f32_e32 v44, v44
	v_exp_f32_e32 v45, v45
	v_pk_add_f32 v[36:37], v[36:37], 1.0 op_sel_hi:[1,0]
	v_pk_add_f32 v[38:39], v[38:39], 1.0 op_sel_hi:[1,0]
	v_pk_add_f32 v[42:43], v[42:43], 1.0 op_sel_hi:[1,0]
	v_pk_add_f32 v[44:45], v[44:45], 1.0 op_sel_hi:[1,0]
	v_rcp_f32_e32 v36, v36
	v_rcp_f32_e32 v37, v37
	v_rcp_f32_e32 v46, v38
	v_rcp_f32_e32 v47, v39
	v_rcp_f32_e32 v42, v42
	v_rcp_f32_e32 v43, v43
	v_rcp_f32_e32 v44, v44
	v_rcp_f32_e32 v45, v45
	v_pk_mul_f32 v[38:39], v[36:37], v[34:35]
	v_pk_mul_f32 v[36:37], v[46:47], v[0:1]
	v_pk_mul_f32 v[34:35], v[42:43], v[40:41]
	v_pk_mul_f32 v[40:41], v[44:45], v[2:3]
	v_cvt_pk_bf16_f32 v126, v38, v39
	v_cvt_pk_bf16_f32 v124, v36, v37
	v_cvt_pk_bf16_f32 v123, v34, v35
	v_pk_mul_f32 v[24:25], v[36:37], v[36:37]
	v_cvt_pk_bf16_f32 v121, v40, v41
	s_waitcnt vmcnt(11)
	v_mov_b32_e32 v0, v184
	v_mov_b32_e32 v1, v185
	v_mov_b32_e32 v2, v186
	v_mov_b32_e32 v3, v187
	v_lshlrev_b32_e32 v42, 16, v0
	v_and_b32_e32 v43, 0xffff0000, v0
	v_lshlrev_b32_e32 v0, 16, v1
	v_and_b32_e32 v1, 0xffff0000, v1
	v_lshlrev_b32_e32 v48, 16, v2
	v_and_b32_e32 v49, 0xffff0000, v2
	v_lshlrev_b32_e32 v2, 16, v3
	v_and_b32_e32 v3, 0xffff0000, v3
	v_pk_mul_f32 v[44:45], v[42:43], v[42:43]
	v_pk_mul_f32 v[46:47], v[0:1], v[0:1]
	v_pk_mul_f32 v[50:51], v[48:49], v[48:49]
	v_pk_mul_f32 v[52:53], v[2:3], v[2:3]
	v_pk_fma_f32 v[44:45], v[44:45], s[38:39], 1.0 op_sel_hi:[1,0,0]
	v_pk_fma_f32 v[46:47], v[46:47], s[38:39], 1.0 op_sel_hi:[1,0,0]
	v_pk_fma_f32 v[50:51], v[50:51], s[38:39], 1.0 op_sel_hi:[1,0,0]
	v_pk_fma_f32 v[52:53], v[52:53], s[38:39], 1.0 op_sel_hi:[1,0,0]
	v_pk_mul_f32 v[44:45], v[44:45], v[42:43]
	v_pk_mul_f32 v[46:47], v[46:47], v[0:1]
	v_pk_mul_f32 v[50:51], v[50:51], v[48:49]
	v_pk_mul_f32 v[52:53], v[52:53], v[2:3]
	v_pk_mul_f32 v[44:45], v[44:45], s[36:37] op_sel_hi:[1,0]
	v_pk_mul_f32 v[46:47], v[46:47], s[36:37] op_sel_hi:[1,0]
	v_pk_mul_f32 v[50:51], v[50:51], s[36:37] op_sel_hi:[1,0]
	v_pk_mul_f32 v[52:53], v[52:53], s[36:37] op_sel_hi:[1,0]
	v_exp_f32_e32 v44, v44
	v_exp_f32_e32 v45, v45
	v_exp_f32_e32 v46, v46
	v_exp_f32_e32 v47, v47
	v_exp_f32_e32 v50, v50
	v_exp_f32_e32 v51, v51
	v_exp_f32_e32 v52, v52
	v_exp_f32_e32 v53, v53
	v_pk_add_f32 v[44:45], v[44:45], 1.0 op_sel_hi:[1,0]
	v_pk_add_f32 v[46:47], v[46:47], 1.0 op_sel_hi:[1,0]
	v_pk_add_f32 v[50:51], v[50:51], 1.0 op_sel_hi:[1,0]
	v_pk_add_f32 v[52:53], v[52:53], 1.0 op_sel_hi:[1,0]
	v_rcp_f32_e32 v44, v44
	v_rcp_f32_e32 v45, v45
	v_rcp_f32_e32 v54, v46
	v_rcp_f32_e32 v55, v47
	v_rcp_f32_e32 v50, v50
	v_rcp_f32_e32 v51, v51
	v_rcp_f32_e32 v52, v52
	v_rcp_f32_e32 v53, v53
	v_pk_mul_f32 v[46:47], v[44:45], v[42:43]
	v_pk_mul_f32 v[44:45], v[54:55], v[0:1]
	v_pk_mul_f32 v[42:43], v[50:51], v[48:49]
	v_pk_mul_f32 v[48:49], v[52:53], v[2:3]
	v_cvt_pk_bf16_f32 v129, v46, v47
	v_cvt_pk_bf16_f32 v128, v44, v45
	v_cvt_pk_bf16_f32 v127, v42, v43
	s_nop 0
	v_cvt_pk_bf16_f32 v125, v48, v49
	s_waitcnt vmcnt(10)
	v_mov_b32_e32 v0, v188
	v_mov_b32_e32 v1, v189
	v_mov_b32_e32 v2, v190
	v_mov_b32_e32 v3, v191
	v_lshlrev_b32_e32 v50, 16, v0
	v_and_b32_e32 v51, 0xffff0000, v0
	v_lshlrev_b32_e32 v0, 16, v1
	v_and_b32_e32 v1, 0xffff0000, v1
	v_lshlrev_b32_e32 v56, 16, v2
	v_and_b32_e32 v57, 0xffff0000, v2
	v_lshlrev_b32_e32 v2, 16, v3
	v_and_b32_e32 v3, 0xffff0000, v3
	v_pk_mul_f32 v[52:53], v[50:51], v[50:51]
	v_pk_mul_f32 v[54:55], v[0:1], v[0:1]
	v_pk_mul_f32 v[58:59], v[56:57], v[56:57]
	v_pk_mul_f32 v[60:61], v[2:3], v[2:3]
	v_pk_fma_f32 v[52:53], v[52:53], s[38:39], 1.0 op_sel_hi:[1,0,0]
	v_pk_fma_f32 v[54:55], v[54:55], s[38:39], 1.0 op_sel_hi:[1,0,0]
	v_pk_fma_f32 v[58:59], v[58:59], s[38:39], 1.0 op_sel_hi:[1,0,0]
	v_pk_fma_f32 v[60:61], v[60:61], s[38:39], 1.0 op_sel_hi:[1,0,0]
	v_pk_mul_f32 v[52:53], v[52:53], v[50:51]
	v_pk_mul_f32 v[54:55], v[54:55], v[0:1]
	v_pk_mul_f32 v[58:59], v[58:59], v[56:57]
	v_pk_mul_f32 v[60:61], v[60:61], v[2:3]
	v_pk_mul_f32 v[52:53], v[52:53], s[36:37] op_sel_hi:[1,0]
	v_pk_mul_f32 v[54:55], v[54:55], s[36:37] op_sel_hi:[1,0]
	v_pk_mul_f32 v[58:59], v[58:59], s[36:37] op_sel_hi:[1,0]
	v_pk_mul_f32 v[60:61], v[60:61], s[36:37] op_sel_hi:[1,0]
	v_exp_f32_e32 v52, v52
	v_exp_f32_e32 v53, v53
	v_exp_f32_e32 v54, v54
	v_exp_f32_e32 v55, v55
	v_exp_f32_e32 v58, v58
	v_exp_f32_e32 v59, v59
	v_exp_f32_e32 v60, v60
	v_exp_f32_e32 v61, v61
	v_pk_add_f32 v[52:53], v[52:53], 1.0 op_sel_hi:[1,0]
	v_pk_add_f32 v[54:55], v[54:55], 1.0 op_sel_hi:[1,0]
	v_pk_add_f32 v[58:59], v[58:59], 1.0 op_sel_hi:[1,0]
	v_pk_add_f32 v[60:61], v[60:61], 1.0 op_sel_hi:[1,0]
	v_rcp_f32_e32 v52, v52
	v_rcp_f32_e32 v53, v53
	v_rcp_f32_e32 v62, v54
	v_rcp_f32_e32 v63, v55
	v_rcp_f32_e32 v58, v58
	v_rcp_f32_e32 v59, v59
	v_rcp_f32_e32 v60, v60
	v_rcp_f32_e32 v61, v61
	v_pk_mul_f32 v[54:55], v[52:53], v[50:51]
	v_pk_mul_f32 v[52:53], v[62:63], v[0:1]
	v_pk_mul_f32 v[50:51], v[58:59], v[56:57]
	v_pk_mul_f32 v[56:57], v[60:61], v[2:3]
	v_cvt_pk_bf16_f32 v134, v54, v55
	v_cvt_pk_bf16_f32 v132, v52, v53
	v_cvt_pk_bf16_f32 v131, v50, v51
	s_nop 0
	v_cvt_pk_bf16_f32 v130, v56, v57
	s_waitcnt vmcnt(9)
	v_mov_b32_e32 v0, v192
	v_mov_b32_e32 v1, v193
	v_mov_b32_e32 v2, v194
	v_mov_b32_e32 v3, v195
	v_lshlrev_b32_e32 v58, 16, v0
	v_and_b32_e32 v59, 0xffff0000, v0
	v_lshlrev_b32_e32 v0, 16, v1
	v_and_b32_e32 v1, 0xffff0000, v1
	v_lshlrev_b32_e32 v64, 16, v2
	v_and_b32_e32 v65, 0xffff0000, v2
	v_lshlrev_b32_e32 v2, 16, v3
	v_and_b32_e32 v3, 0xffff0000, v3
	v_pk_mul_f32 v[60:61], v[58:59], v[58:59]
	v_pk_mul_f32 v[62:63], v[0:1], v[0:1]
	v_pk_mul_f32 v[66:67], v[64:65], v[64:65]
	v_pk_mul_f32 v[68:69], v[2:3], v[2:3]
	v_pk_fma_f32 v[60:61], v[60:61], s[38:39], 1.0 op_sel_hi:[1,0,0]
	v_pk_fma_f32 v[62:63], v[62:63], s[38:39], 1.0 op_sel_hi:[1,0,0]
	v_pk_fma_f32 v[66:67], v[66:67], s[38:39], 1.0 op_sel_hi:[1,0,0]
	v_pk_fma_f32 v[68:69], v[68:69], s[38:39], 1.0 op_sel_hi:[1,0,0]
	v_pk_mul_f32 v[60:61], v[60:61], v[58:59]
	v_pk_mul_f32 v[62:63], v[62:63], v[0:1]
	v_pk_mul_f32 v[66:67], v[66:67], v[64:65]
	v_pk_mul_f32 v[68:69], v[68:69], v[2:3]
	v_pk_mul_f32 v[60:61], v[60:61], s[36:37] op_sel_hi:[1,0]
	v_pk_mul_f32 v[62:63], v[62:63], s[36:37] op_sel_hi:[1,0]
	v_pk_mul_f32 v[66:67], v[66:67], s[36:37] op_sel_hi:[1,0]
	v_pk_mul_f32 v[68:69], v[68:69], s[36:37] op_sel_hi:[1,0]
	v_exp_f32_e32 v60, v60
	v_exp_f32_e32 v61, v61
	v_exp_f32_e32 v62, v62
	v_exp_f32_e32 v63, v63
	v_exp_f32_e32 v66, v66
	v_exp_f32_e32 v67, v67
	v_exp_f32_e32 v68, v68
	v_exp_f32_e32 v69, v69
	v_pk_add_f32 v[60:61], v[60:61], 1.0 op_sel_hi:[1,0]
	v_pk_add_f32 v[62:63], v[62:63], 1.0 op_sel_hi:[1,0]
	v_pk_add_f32 v[66:67], v[66:67], 1.0 op_sel_hi:[1,0]
	v_pk_add_f32 v[68:69], v[68:69], 1.0 op_sel_hi:[1,0]
	v_rcp_f32_e32 v60, v60
	v_rcp_f32_e32 v61, v61
	v_rcp_f32_e32 v70, v62
	v_rcp_f32_e32 v71, v63
	v_rcp_f32_e32 v66, v66
	v_rcp_f32_e32 v67, v67
	v_rcp_f32_e32 v68, v68
	v_rcp_f32_e32 v69, v69
	v_pk_mul_f32 v[62:63], v[60:61], v[58:59]
	v_pk_mul_f32 v[60:61], v[70:71], v[0:1]
	v_pk_mul_f32 v[58:59], v[66:67], v[64:65]
	v_pk_mul_f32 v[64:65], v[68:69], v[2:3]
	v_cvt_pk_bf16_f32 v137, v62, v63
	v_cvt_pk_bf16_f32 v136, v60, v61
	v_cvt_pk_bf16_f32 v135, v58, v59
	s_nop 0
	v_cvt_pk_bf16_f32 v133, v64, v65
	s_waitcnt vmcnt(8)
	v_mov_b32_e32 v0, v196
	v_mov_b32_e32 v1, v197
	v_mov_b32_e32 v2, v198
	v_mov_b32_e32 v3, v199
	v_lshlrev_b32_e32 v66, 16, v0
	v_and_b32_e32 v67, 0xffff0000, v0
	v_lshlrev_b32_e32 v0, 16, v1
	v_and_b32_e32 v1, 0xffff0000, v1
	v_lshlrev_b32_e32 v72, 16, v2
	v_and_b32_e32 v73, 0xffff0000, v2
	v_lshlrev_b32_e32 v2, 16, v3
	v_and_b32_e32 v3, 0xffff0000, v3
	v_pk_mul_f32 v[68:69], v[66:67], v[66:67]
	v_pk_mul_f32 v[70:71], v[0:1], v[0:1]
	v_pk_mul_f32 v[74:75], v[72:73], v[72:73]
	v_pk_mul_f32 v[76:77], v[2:3], v[2:3]
	v_pk_fma_f32 v[68:69], v[68:69], s[38:39], 1.0 op_sel_hi:[1,0,0]
	v_pk_fma_f32 v[70:71], v[70:71], s[38:39], 1.0 op_sel_hi:[1,0,0]
	v_pk_fma_f32 v[74:75], v[74:75], s[38:39], 1.0 op_sel_hi:[1,0,0]
	v_pk_fma_f32 v[76:77], v[76:77], s[38:39], 1.0 op_sel_hi:[1,0,0]
	v_pk_mul_f32 v[68:69], v[68:69], v[66:67]
	v_pk_mul_f32 v[70:71], v[70:71], v[0:1]
	v_pk_mul_f32 v[74:75], v[74:75], v[72:73]
	v_pk_mul_f32 v[76:77], v[76:77], v[2:3]
	v_pk_mul_f32 v[68:69], v[68:69], s[36:37] op_sel_hi:[1,0]
	v_pk_mul_f32 v[70:71], v[70:71], s[36:37] op_sel_hi:[1,0]
	v_pk_mul_f32 v[74:75], v[74:75], s[36:37] op_sel_hi:[1,0]
	v_pk_mul_f32 v[76:77], v[76:77], s[36:37] op_sel_hi:[1,0]
	v_exp_f32_e32 v68, v68
	v_exp_f32_e32 v69, v69
	v_exp_f32_e32 v70, v70
	v_exp_f32_e32 v71, v71
	v_exp_f32_e32 v74, v74
	v_exp_f32_e32 v75, v75
	v_exp_f32_e32 v76, v76
	v_exp_f32_e32 v77, v77
	v_pk_add_f32 v[68:69], v[68:69], 1.0 op_sel_hi:[1,0]
	v_pk_add_f32 v[70:71], v[70:71], 1.0 op_sel_hi:[1,0]
	v_pk_add_f32 v[74:75], v[74:75], 1.0 op_sel_hi:[1,0]
	v_pk_add_f32 v[76:77], v[76:77], 1.0 op_sel_hi:[1,0]
	v_rcp_f32_e32 v68, v68
	v_rcp_f32_e32 v69, v69
	v_rcp_f32_e32 v78, v70
	v_rcp_f32_e32 v79, v71
	v_rcp_f32_e32 v74, v74
	v_rcp_f32_e32 v75, v75
	v_rcp_f32_e32 v76, v76
	v_rcp_f32_e32 v77, v77
	v_pk_mul_f32 v[70:71], v[68:69], v[66:67]
	v_pk_mul_f32 v[68:69], v[78:79], v[0:1]
	v_pk_mul_f32 v[66:67], v[74:75], v[72:73]
	v_pk_mul_f32 v[72:73], v[76:77], v[2:3]
	v_cvt_pk_bf16_f32 v142, v70, v71
	v_cvt_pk_bf16_f32 v140, v68, v69
	v_cvt_pk_bf16_f32 v139, v66, v67
	s_nop 0
	v_cvt_pk_bf16_f32 v138, v72, v73
	s_waitcnt vmcnt(7)
	v_mov_b32_e32 v0, v200
	v_mov_b32_e32 v1, v201
	v_mov_b32_e32 v2, v202
	v_mov_b32_e32 v3, v203
	v_lshlrev_b32_e32 v74, 16, v0
	v_and_b32_e32 v75, 0xffff0000, v0
	v_lshlrev_b32_e32 v0, 16, v1
	v_and_b32_e32 v1, 0xffff0000, v1
	v_lshlrev_b32_e32 v80, 16, v2
	v_and_b32_e32 v81, 0xffff0000, v2
	v_lshlrev_b32_e32 v2, 16, v3
	v_and_b32_e32 v3, 0xffff0000, v3
	v_pk_mul_f32 v[76:77], v[74:75], v[74:75]
	v_pk_mul_f32 v[78:79], v[0:1], v[0:1]
	v_pk_mul_f32 v[82:83], v[80:81], v[80:81]
	v_pk_mul_f32 v[84:85], v[2:3], v[2:3]
	v_pk_fma_f32 v[76:77], v[76:77], s[38:39], 1.0 op_sel_hi:[1,0,0]
	v_pk_fma_f32 v[78:79], v[78:79], s[38:39], 1.0 op_sel_hi:[1,0,0]
	v_pk_fma_f32 v[82:83], v[82:83], s[38:39], 1.0 op_sel_hi:[1,0,0]
	v_pk_fma_f32 v[84:85], v[84:85], s[38:39], 1.0 op_sel_hi:[1,0,0]
	v_pk_mul_f32 v[76:77], v[76:77], v[74:75]
	v_pk_mul_f32 v[78:79], v[78:79], v[0:1]
	v_pk_mul_f32 v[82:83], v[82:83], v[80:81]
	v_pk_mul_f32 v[84:85], v[84:85], v[2:3]
	v_pk_mul_f32 v[76:77], v[76:77], s[36:37] op_sel_hi:[1,0]
	v_pk_mul_f32 v[78:79], v[78:79], s[36:37] op_sel_hi:[1,0]
	v_pk_mul_f32 v[82:83], v[82:83], s[36:37] op_sel_hi:[1,0]
	v_pk_mul_f32 v[84:85], v[84:85], s[36:37] op_sel_hi:[1,0]
	v_exp_f32_e32 v76, v76
	v_exp_f32_e32 v77, v77
	v_exp_f32_e32 v78, v78
	v_exp_f32_e32 v79, v79
	v_exp_f32_e32 v82, v82
	v_exp_f32_e32 v83, v83
	v_exp_f32_e32 v84, v84
	v_exp_f32_e32 v85, v85
	v_pk_add_f32 v[76:77], v[76:77], 1.0 op_sel_hi:[1,0]
	v_pk_add_f32 v[78:79], v[78:79], 1.0 op_sel_hi:[1,0]
	v_pk_add_f32 v[82:83], v[82:83], 1.0 op_sel_hi:[1,0]
	v_pk_add_f32 v[84:85], v[84:85], 1.0 op_sel_hi:[1,0]
	v_rcp_f32_e32 v76, v76
	v_rcp_f32_e32 v77, v77
	v_rcp_f32_e32 v86, v78
	v_rcp_f32_e32 v87, v79
	v_rcp_f32_e32 v82, v82
	v_rcp_f32_e32 v83, v83
	v_rcp_f32_e32 v84, v84
	v_rcp_f32_e32 v85, v85
	v_pk_mul_f32 v[78:79], v[76:77], v[74:75]
	v_pk_mul_f32 v[76:77], v[86:87], v[0:1]
	v_pk_mul_f32 v[74:75], v[82:83], v[80:81]
	v_pk_mul_f32 v[80:81], v[84:85], v[2:3]
	v_cvt_pk_bf16_f32 v146, v78, v79
	v_cvt_pk_bf16_f32 v144, v76, v77
	v_cvt_pk_bf16_f32 v143, v74, v75
	s_nop 0
	v_cvt_pk_bf16_f32 v141, v80, v81
	s_waitcnt vmcnt(6)
	v_mov_b32_e32 v0, v204
	v_mov_b32_e32 v1, v205
	v_mov_b32_e32 v2, v206
	v_mov_b32_e32 v3, v207
	v_lshlrev_b32_e32 v82, 16, v0
	v_and_b32_e32 v83, 0xffff0000, v0
	v_lshlrev_b32_e32 v0, 16, v1
	v_and_b32_e32 v1, 0xffff0000, v1
	v_lshlrev_b32_e32 v84, 16, v2
	v_and_b32_e32 v85, 0xffff0000, v2
	v_lshlrev_b32_e32 v2, 16, v3
	v_and_b32_e32 v3, 0xffff0000, v3
	v_pk_mul_f32 v[86:87], v[82:83], v[82:83]
	v_pk_mul_f32 v[88:89], v[0:1], v[0:1]
	v_pk_mul_f32 v[90:91], v[84:85], v[84:85]
	v_pk_mul_f32 v[92:93], v[2:3], v[2:3]
	v_pk_fma_f32 v[86:87], v[86:87], s[38:39], 1.0 op_sel_hi:[1,0,0]
	v_pk_fma_f32 v[88:89], v[88:89], s[38:39], 1.0 op_sel_hi:[1,0,0]
	v_pk_fma_f32 v[90:91], v[90:91], s[38:39], 1.0 op_sel_hi:[1,0,0]
	v_pk_fma_f32 v[92:93], v[92:93], s[38:39], 1.0 op_sel_hi:[1,0,0]
	v_pk_mul_f32 v[86:87], v[86:87], v[82:83]
	v_pk_mul_f32 v[88:89], v[88:89], v[0:1]
	v_pk_mul_f32 v[90:91], v[90:91], v[84:85]
	v_pk_mul_f32 v[92:93], v[92:93], v[2:3]
	v_pk_mul_f32 v[86:87], v[86:87], s[36:37] op_sel_hi:[1,0]
	v_pk_mul_f32 v[88:89], v[88:89], s[36:37] op_sel_hi:[1,0]
	v_pk_mul_f32 v[90:91], v[90:91], s[36:37] op_sel_hi:[1,0]
	v_pk_mul_f32 v[92:93], v[92:93], s[36:37] op_sel_hi:[1,0]
	v_exp_f32_e32 v86, v86
	v_exp_f32_e32 v87, v87
	v_exp_f32_e32 v88, v88
	v_exp_f32_e32 v89, v89
	v_exp_f32_e32 v90, v90
	v_exp_f32_e32 v91, v91
	v_exp_f32_e32 v92, v92
	v_exp_f32_e32 v93, v93
	v_pk_add_f32 v[86:87], v[86:87], 1.0 op_sel_hi:[1,0]
	v_pk_add_f32 v[88:89], v[88:89], 1.0 op_sel_hi:[1,0]
	v_pk_add_f32 v[90:91], v[90:91], 1.0 op_sel_hi:[1,0]
	v_pk_add_f32 v[92:93], v[92:93], 1.0 op_sel_hi:[1,0]
	v_rcp_f32_e32 v86, v86
	v_rcp_f32_e32 v87, v87
	v_rcp_f32_e32 v88, v88
	v_rcp_f32_e32 v89, v89
	v_rcp_f32_e32 v94, v90
	v_rcp_f32_e32 v95, v91
	v_rcp_f32_e32 v92, v92
	v_rcp_f32_e32 v93, v93
	v_pk_mul_f32 v[90:91], v[86:87], v[82:83]
	v_pk_mul_f32 v[86:87], v[88:89], v[0:1]
	v_pk_mul_f32 v[84:85], v[94:95], v[84:85]
	v_pk_mul_f32 v[82:83], v[92:93], v[2:3]
	v_cvt_pk_bf16_f32 v149, v90, v91
	v_cvt_pk_bf16_f32 v148, v86, v87
	v_cvt_pk_bf16_f32 v147, v84, v85
	s_nop 0
	v_cvt_pk_bf16_f32 v145, v82, v83
	s_waitcnt vmcnt(5)
	v_mov_b32_e32 v0, v208
	v_mov_b32_e32 v1, v209
	v_mov_b32_e32 v2, v210
	v_mov_b32_e32 v3, v211
	v_lshlrev_b32_e32 v88, 16, v0
	v_and_b32_e32 v89, 0xffff0000, v0
	v_lshlrev_b32_e32 v0, 16, v1
	v_and_b32_e32 v1, 0xffff0000, v1
	v_lshlrev_b32_e32 v92, 16, v2
	v_and_b32_e32 v93, 0xffff0000, v2
	v_lshlrev_b32_e32 v2, 16, v3
	v_and_b32_e32 v3, 0xffff0000, v3
	v_pk_mul_f32 v[94:95], v[88:89], v[88:89]
	v_pk_mul_f32 v[96:97], v[0:1], v[0:1]
	v_pk_mul_f32 v[98:99], v[92:93], v[92:93]
	v_pk_mul_f32 v[100:101], v[2:3], v[2:3]
	v_pk_fma_f32 v[94:95], v[94:95], s[38:39], 1.0 op_sel_hi:[1,0,0]
	v_pk_fma_f32 v[96:97], v[96:97], s[38:39], 1.0 op_sel_hi:[1,0,0]
	v_pk_fma_f32 v[98:99], v[98:99], s[38:39], 1.0 op_sel_hi:[1,0,0]
	v_pk_fma_f32 v[100:101], v[100:101], s[38:39], 1.0 op_sel_hi:[1,0,0]
	v_pk_mul_f32 v[94:95], v[94:95], v[88:89]
	v_pk_mul_f32 v[96:97], v[96:97], v[0:1]
	v_pk_mul_f32 v[98:99], v[98:99], v[92:93]
	v_pk_mul_f32 v[100:101], v[100:101], v[2:3]
	v_pk_mul_f32 v[94:95], v[94:95], s[36:37] op_sel_hi:[1,0]
	v_pk_mul_f32 v[96:97], v[96:97], s[36:37] op_sel_hi:[1,0]
	v_pk_mul_f32 v[98:99], v[98:99], s[36:37] op_sel_hi:[1,0]
	v_pk_mul_f32 v[100:101], v[100:101], s[36:37] op_sel_hi:[1,0]
	v_exp_f32_e32 v94, v94
	v_exp_f32_e32 v95, v95
	v_exp_f32_e32 v96, v96
	v_exp_f32_e32 v97, v97
	v_exp_f32_e32 v98, v98
	v_exp_f32_e32 v99, v99
	v_exp_f32_e32 v100, v100
	v_exp_f32_e32 v101, v101
	v_pk_add_f32 v[94:95], v[94:95], 1.0 op_sel_hi:[1,0]
	v_pk_add_f32 v[96:97], v[96:97], 1.0 op_sel_hi:[1,0]
	v_pk_add_f32 v[98:99], v[98:99], 1.0 op_sel_hi:[1,0]
	v_pk_add_f32 v[100:101], v[100:101], 1.0 op_sel_hi:[1,0]
	v_rcp_f32_e32 v94, v94
	v_rcp_f32_e32 v95, v95
	v_rcp_f32_e32 v102, v96
	v_rcp_f32_e32 v103, v97
	v_rcp_f32_e32 v98, v98
	v_rcp_f32_e32 v99, v99
	v_rcp_f32_e32 v100, v100
	v_rcp_f32_e32 v101, v101
	v_pk_mul_f32 v[96:97], v[94:95], v[88:89]
	v_pk_mul_f32 v[94:95], v[102:103], v[0:1]
	v_pk_mul_f32 v[92:93], v[98:99], v[92:93]
	v_pk_mul_f32 v[98:99], v[100:101], v[2:3]
	v_cvt_pk_bf16_f32 v154, v96, v97
	v_cvt_pk_bf16_f32 v152, v94, v95
	v_cvt_pk_bf16_f32 v151, v92, v93
	v_mov_b32_e32 v89, 0
	v_cvt_pk_bf16_f32 v150, v98, v99
	v_mov_b32_e32 v88, v17
	v_pk_add_f32 v[6:7], v[6:7], v[88:89]
	v_mov_b32_e32 v17, v22
	v_pk_add_f32 v[6:7], v[10:11], v[6:7]
	v_pk_mul_f32 v[10:11], v[20:21], v[20:21]
	s_waitcnt vmcnt(4)
	v_mov_b32_e32 v0, v212
	v_mov_b32_e32 v1, v213
	v_mov_b32_e32 v2, v214
	v_mov_b32_e32 v3, v215
	v_lshlrev_b32_e32 v100, 16, v0
	v_and_b32_e32 v101, 0xffff0000, v0
	v_lshlrev_b32_e32 v0, 16, v1
	v_and_b32_e32 v1, 0xffff0000, v1
	v_lshlrev_b32_e32 v106, 16, v2
	v_and_b32_e32 v107, 0xffff0000, v2
	v_lshlrev_b32_e32 v2, 16, v3
	v_and_b32_e32 v3, 0xffff0000, v3
	v_pk_mul_f32 v[102:103], v[100:101], v[100:101]
	v_pk_mul_f32 v[104:105], v[0:1], v[0:1]
	v_pk_mul_f32 v[156:157], v[106:107], v[106:107]
	v_pk_mul_f32 v[158:159], v[2:3], v[2:3]
	v_pk_fma_f32 v[102:103], v[102:103], s[38:39], 1.0 op_sel_hi:[1,0,0]
	v_pk_fma_f32 v[104:105], v[104:105], s[38:39], 1.0 op_sel_hi:[1,0,0]
	v_pk_fma_f32 v[156:157], v[156:157], s[38:39], 1.0 op_sel_hi:[1,0,0]
	v_pk_fma_f32 v[158:159], v[158:159], s[38:39], 1.0 op_sel_hi:[1,0,0]
	v_pk_mul_f32 v[102:103], v[102:103], v[100:101]
	v_pk_mul_f32 v[104:105], v[104:105], v[0:1]
	v_pk_mul_f32 v[156:157], v[156:157], v[106:107]
	v_pk_mul_f32 v[158:159], v[158:159], v[2:3]
	v_pk_mul_f32 v[102:103], v[102:103], s[36:37] op_sel_hi:[1,0]
	v_pk_mul_f32 v[104:105], v[104:105], s[36:37] op_sel_hi:[1,0]
	v_pk_mul_f32 v[156:157], v[156:157], s[36:37] op_sel_hi:[1,0]
	v_pk_mul_f32 v[158:159], v[158:159], s[36:37] op_sel_hi:[1,0]
	v_exp_f32_e32 v102, v102
	v_exp_f32_e32 v103, v103
	v_exp_f32_e32 v104, v104
	v_exp_f32_e32 v105, v105
	v_exp_f32_e32 v156, v156
	v_exp_f32_e32 v157, v157
	v_exp_f32_e32 v158, v158
	v_exp_f32_e32 v159, v159
	v_pk_add_f32 v[102:103], v[102:103], 1.0 op_sel_hi:[1,0]
	v_pk_add_f32 v[104:105], v[104:105], 1.0 op_sel_hi:[1,0]
	v_pk_add_f32 v[156:157], v[156:157], 1.0 op_sel_hi:[1,0]
	v_pk_add_f32 v[158:159], v[158:159], 1.0 op_sel_hi:[1,0]
	v_rcp_f32_e32 v102, v102
	v_rcp_f32_e32 v103, v103
	v_rcp_f32_e32 v160, v104
	v_rcp_f32_e32 v161, v105
	v_rcp_f32_e32 v156, v156
	v_rcp_f32_e32 v157, v157
	v_rcp_f32_e32 v158, v158
	v_rcp_f32_e32 v159, v159
	v_pk_mul_f32 v[104:105], v[102:103], v[100:101]
	v_pk_mul_f32 v[102:103], v[160:161], v[0:1]
	v_pk_mul_f32 v[100:101], v[156:157], v[106:107]
	v_pk_mul_f32 v[106:107], v[158:159], v[2:3]
	v_cvt_pk_bf16_f32 v157, v104, v105
	v_cvt_pk_bf16_f32 v156, v102, v103
	v_cvt_pk_bf16_f32 v155, v100, v101
	v_pk_mul_f32 v[160:161], v[8:9], v[8:9]
	v_cvt_pk_bf16_f32 v153, v106, v107
	v_mov_b32_e32 v166, v160
	v_mov_b32_e32 v8, v161
	v_pk_add_f32 v[8:9], v[166:167], v[8:9]
	v_mov_b32_e32 v161, v20
	v_pk_add_f32 v[6:7], v[8:9], v[6:7]
	v_pk_mul_f32 v[8:9], v[22:23], v[22:23]
	v_pk_add_f32 v[6:7], v[12:13], v[6:7]
	v_mov_b32_e32 v16, v8
	v_mov_b32_e32 v22, v9
	v_pk_mul_f32 v[12:13], v[18:19], v[18:19]
	v_mov_b32_e32 v160, v10
	v_mov_b32_e32 v20, v11
	v_pk_add_f32 v[8:9], v[16:17], v[22:23]
	v_mov_b32_e32 v162, v12
	v_mov_b32_e32 v18, v13
	v_pk_add_f32 v[10:11], v[160:161], v[20:21]
	v_pk_add_f32 v[6:7], v[6:7], v[8:9]
	v_pk_add_f32 v[12:13], v[162:163], v[18:19]
	v_pk_add_f32 v[6:7], v[10:11], v[6:7]
	v_pk_mul_f32 v[8:9], v[30:31], v[30:31]
	v_pk_add_f32 v[6:7], v[12:13], v[6:7]
	v_mov_b32_e32 v11, v30
	v_pk_mul_f32 v[12:13], v[28:29], v[28:29]
	v_mov_b32_e32 v10, v8
	v_mov_b32_e32 v30, v9
	v_pk_add_f32 v[6:7], v[14:15], v[6:7]
	v_mov_b32_e32 v15, v28
	v_pk_mul_f32 v[16:17], v[26:27], v[26:27]
	v_mov_b32_e32 v14, v12
	v_mov_b32_e32 v28, v13
	v_pk_add_f32 v[8:9], v[10:11], v[30:31]
	v_pk_mul_f32 v[18:19], v[32:33], v[32:33]
	v_mov_b32_e32 v21, v26
	v_mov_b32_e32 v20, v16
	v_mov_b32_e32 v26, v17
	v_pk_add_f32 v[10:11], v[14:15], v[28:29]
	v_pk_add_f32 v[6:7], v[6:7], v[8:9]
	v_mov_b32_e32 v23, v32
	v_mov_b32_e32 v22, v18
	v_mov_b32_e32 v32, v19
	v_pk_add_f32 v[12:13], v[20:21], v[26:27]
	v_pk_add_f32 v[6:7], v[10:11], v[6:7]
	v_pk_add_f32 v[14:15], v[22:23], v[32:33]
	v_pk_add_f32 v[6:7], v[12:13], v[6:7]
	v_pk_mul_f32 v[16:17], v[38:39], v[38:39]
	v_pk_add_f32 v[14:15], v[14:15], v[6:7]
	v_mov_b32_e32 v31, v38
	v_mov_b32_e32 v30, v16
	v_mov_b32_e32 v38, v17
	v_pk_mul_f32 v[26:27], v[34:35], v[34:35]
	v_mov_b32_e32 v33, v36
	v_mov_b32_e32 v32, v24
	v_mov_b32_e32 v36, v25
	v_pk_add_f32 v[16:17], v[30:31], v[38:39]
	v_pk_mul_f32 v[28:29], v[40:41], v[40:41]
	v_mov_b32_e32 v161, v34
	v_mov_b32_e32 v160, v26
	v_mov_b32_e32 v34, v27
	v_pk_add_f32 v[24:25], v[32:33], v[36:37]
	v_pk_add_f32 v[14:15], v[14:15], v[16:17]
	v_mov_b32_e32 v163, v40
	v_mov_b32_e32 v162, v28
	v_mov_b32_e32 v40, v29
	v_pk_add_f32 v[26:27], v[160:161], v[34:35]
	v_pk_add_f32 v[14:15], v[24:25], v[14:15]
	v_pk_mul_f32 v[16:17], v[46:47], v[46:47]
	v_pk_add_f32 v[28:29], v[162:163], v[40:41]
	v_pk_add_f32 v[14:15], v[26:27], v[14:15]
	v_pk_mul_f32 v[24:25], v[44:45], v[44:45]
	v_mov_b32_e32 v31, v46
	v_mov_b32_e32 v30, v16
	v_mov_b32_e32 v46, v17
	v_pk_add_f32 v[14:15], v[28:29], v[14:15]
	v_pk_mul_f32 v[26:27], v[42:43], v[42:43]
	v_mov_b32_e32 v33, v44
	v_mov_b32_e32 v32, v24
	v_mov_b32_e32 v44, v25
	v_pk_add_f32 v[16:17], v[30:31], v[46:47]
	v_pk_mul_f32 v[28:29], v[48:49], v[48:49]
	s_waitcnt vmcnt(3)
	v_mov_b32_e32 v0, v216
	v_mov_b32_e32 v1, v217
	v_mov_b32_e32 v2, v218
	v_mov_b32_e32 v3, v219
	v_lshlrev_b32_e32 v6, 16, v0
	v_and_b32_e32 v7, 0xffff0000, v0
	v_lshlrev_b32_e32 v0, 16, v1
	v_and_b32_e32 v1, 0xffff0000, v1
	v_lshlrev_b32_e32 v10, 16, v2
	v_and_b32_e32 v11, 0xffff0000, v2
	v_lshlrev_b32_e32 v12, 16, v3
	v_and_b32_e32 v13, 0xffff0000, v3
	v_pk_mul_f32 v[2:3], v[6:7], v[6:7]
	v_pk_mul_f32 v[8:9], v[0:1], v[0:1]
	v_pk_mul_f32 v[18:19], v[10:11], v[10:11]
	v_pk_mul_f32 v[20:21], v[12:13], v[12:13]
	v_pk_fma_f32 v[2:3], v[2:3], s[38:39], 1.0 op_sel_hi:[1,0,0]
	v_pk_fma_f32 v[8:9], v[8:9], s[38:39], 1.0 op_sel_hi:[1,0,0]
	v_pk_fma_f32 v[18:19], v[18:19], s[38:39], 1.0 op_sel_hi:[1,0,0]
	v_pk_fma_f32 v[20:21], v[20:21], s[38:39], 1.0 op_sel_hi:[1,0,0]
	v_pk_mul_f32 v[2:3], v[2:3], v[6:7]
	v_pk_mul_f32 v[8:9], v[8:9], v[0:1]
	v_pk_mul_f32 v[18:19], v[18:19], v[10:11]
	v_pk_mul_f32 v[20:21], v[20:21], v[12:13]
	v_pk_mul_f32 v[2:3], v[2:3], s[36:37] op_sel_hi:[1,0]
	v_pk_mul_f32 v[8:9], v[8:9], s[36:37] op_sel_hi:[1,0]
	v_pk_mul_f32 v[18:19], v[18:19], s[36:37] op_sel_hi:[1,0]
	v_pk_mul_f32 v[20:21], v[20:21], s[36:37] op_sel_hi:[1,0]
	v_exp_f32_e32 v2, v2
	v_exp_f32_e32 v3, v3
	v_exp_f32_e32 v8, v8
	v_exp_f32_e32 v9, v9
	v_exp_f32_e32 v18, v18
	v_exp_f32_e32 v19, v19
	v_exp_f32_e32 v20, v20
	v_exp_f32_e32 v21, v21
	v_pk_add_f32 v[2:3], v[2:3], 1.0 op_sel_hi:[1,0]
	v_pk_add_f32 v[8:9], v[8:9], 1.0 op_sel_hi:[1,0]
	v_pk_add_f32 v[18:19], v[18:19], 1.0 op_sel_hi:[1,0]
	v_pk_add_f32 v[20:21], v[20:21], 1.0 op_sel_hi:[1,0]
	v_rcp_f32_e32 v2, v2
	v_rcp_f32_e32 v3, v3
	v_rcp_f32_e32 v22, v8
	v_rcp_f32_e32 v23, v9
	v_rcp_f32_e32 v18, v18
	v_rcp_f32_e32 v19, v19
	v_rcp_f32_e32 v20, v20
	v_rcp_f32_e32 v21, v21
	v_pk_mul_f32 v[8:9], v[2:3], v[6:7]
	v_pk_mul_f32 v[6:7], v[22:23], v[0:1]
	v_pk_mul_f32 v[2:3], v[18:19], v[10:11]
	v_pk_mul_f32 v[0:1], v[20:21], v[12:13]
	v_cvt_pk_bf16_f32 v22, v8, v9
	v_cvt_pk_bf16_f32 v20, v6, v7
	v_cvt_pk_bf16_f32 v19, v2, v3
	v_mov_b32_e32 v35, v42
	v_cvt_pk_bf16_f32 v18, v0, v1
	v_mov_b32_e32 v34, v26
	v_mov_b32_e32 v42, v27
	v_pk_add_f32 v[24:25], v[32:33], v[44:45]
	v_pk_add_f32 v[14:15], v[14:15], v[16:17]
	v_mov_b32_e32 v37, v48
	v_mov_b32_e32 v36, v28
	v_mov_b32_e32 v48, v29
	v_pk_add_f32 v[26:27], v[34:35], v[42:43]
	v_pk_add_f32 v[14:15], v[24:25], v[14:15]
	v_pk_mul_f32 v[16:17], v[54:55], v[54:55]
	v_pk_add_f32 v[28:29], v[36:37], v[48:49]
	v_pk_add_f32 v[14:15], v[26:27], v[14:15]
	v_mov_b32_e32 v25, v54
	v_pk_mul_f32 v[26:27], v[52:53], v[52:53]
	v_mov_b32_e32 v24, v16
	v_mov_b32_e32 v54, v17
	v_pk_add_f32 v[14:15], v[28:29], v[14:15]
	v_pk_mul_f32 v[28:29], v[50:51], v[50:51]
	v_mov_b32_e32 v33, v52
	v_mov_b32_e32 v32, v26
	v_mov_b32_e32 v52, v27
	v_pk_add_f32 v[16:17], v[24:25], v[54:55]
	v_pk_mul_f32 v[30:31], v[56:57], v[56:57]
	v_mov_b32_e32 v35, v50
	v_mov_b32_e32 v34, v28
	v_mov_b32_e32 v50, v29
	v_pk_add_f32 v[24:25], v[32:33], v[52:53]
	v_pk_add_f32 v[14:15], v[14:15], v[16:17]
	v_mov_b32_e32 v37, v56
	v_mov_b32_e32 v36, v30
	v_mov_b32_e32 v56, v31
	v_pk_add_f32 v[26:27], v[34:35], v[50:51]
	v_pk_add_f32 v[14:15], v[24:25], v[14:15]
	v_pk_add_f32 v[28:29], v[36:37], v[56:57]
	v_pk_add_f32 v[14:15], v[26:27], v[14:15]
	v_pk_mul_f32 v[16:17], v[60:61], v[60:61]
	v_pk_add_f32 v[32:33], v[28:29], v[14:15]
	v_pk_mul_f32 v[14:15], v[62:63], v[62:63]
	v_mov_b32_e32 v39, v62
	v_mov_b32_e32 v38, v14
	v_mov_b32_e32 v62, v15
	v_mov_b32_e32 v41, v60
	v_mov_b32_e32 v40, v16
	v_mov_b32_e32 v60, v17
	v_pk_mul_f32 v[34:35], v[58:59], v[58:59]
	v_pk_mul_f32 v[36:37], v[64:65], v[64:65]
	v_mov_b32_e32 v43, v58
	v_mov_b32_e32 v42, v34
	v_mov_b32_e32 v58, v35
	v_pk_add_f32 v[34:35], v[38:39], v[62:63]
	v_mov_b32_e32 v45, v64
	v_mov_b32_e32 v44, v36
	v_mov_b32_e32 v64, v37
	v_pk_add_f32 v[36:37], v[40:41], v[60:61]
	v_pk_add_f32 v[32:33], v[32:33], v[34:35]
	v_pk_add_f32 v[38:39], v[42:43], v[58:59]
	v_pk_add_f32 v[32:33], v[36:37], v[32:33]
	v_pk_add_f32 v[40:41], v[44:45], v[64:65]
	v_pk_add_f32 v[32:33], v[38:39], v[32:33]
	v_pk_mul_f32 v[34:35], v[70:71], v[70:71]
	v_pk_add_f32 v[32:33], v[40:41], v[32:33]
	v_pk_mul_f32 v[36:37], v[68:69], v[68:69]
	v_mov_b32_e32 v41, v70
	v_mov_b32_e32 v40, v34
	v_mov_b32_e32 v70, v35
	v_pk_mul_f32 v[38:39], v[66:67], v[66:67]
	v_mov_b32_e32 v43, v68
	v_mov_b32_e32 v42, v36
	v_mov_b32_e32 v68, v37
	v_pk_add_f32 v[34:35], v[40:41], v[70:71]
	v_mov_b32_e32 v45, v66
	v_mov_b32_e32 v44, v38
	v_mov_b32_e32 v66, v39
	v_pk_add_f32 v[36:37], v[42:43], v[68:69]
	v_pk_add_f32 v[32:33], v[32:33], v[34:35]
	v_mov_b32_e32 v49, v72
	v_pk_add_f32 v[38:39], v[44:45], v[66:67]
	v_pk_add_f32 v[32:33], v[36:37], v[32:33]
	v_pk_mul_f32 v[34:35], v[78:79], v[78:79]
	s_waitcnt vmcnt(2)
	v_mov_b32_e32 v10, v220
	v_mov_b32_e32 v11, v221
	v_mov_b32_e32 v12, v222
	v_mov_b32_e32 v13, v223
	v_lshlrev_b32_e32 v14, 16, v10
	v_and_b32_e32 v15, 0xffff0000, v10
	v_lshlrev_b32_e32 v10, 16, v11
	v_and_b32_e32 v11, 0xffff0000, v11
	v_lshlrev_b32_e32 v24, 16, v12
	v_and_b32_e32 v25, 0xffff0000, v12
	v_lshlrev_b32_e32 v26, 16, v13
	v_and_b32_e32 v27, 0xffff0000, v13
	v_pk_mul_f32 v[12:13], v[14:15], v[14:15]
	v_pk_mul_f32 v[16:17], v[10:11], v[10:11]
	v_pk_mul_f32 v[28:29], v[24:25], v[24:25]
	v_pk_mul_f32 v[30:31], v[26:27], v[26:27]
	v_pk_fma_f32 v[12:13], v[12:13], s[38:39], 1.0 op_sel_hi:[1,0,0]
	v_pk_fma_f32 v[16:17], v[16:17], s[38:39], 1.0 op_sel_hi:[1,0,0]
	v_pk_fma_f32 v[28:29], v[28:29], s[38:39], 1.0 op_sel_hi:[1,0,0]
	v_pk_fma_f32 v[30:31], v[30:31], s[38:39], 1.0 op_sel_hi:[1,0,0]
	v_pk_mul_f32 v[12:13], v[12:13], v[14:15]
	v_pk_mul_f32 v[16:17], v[16:17], v[10:11]
	v_pk_mul_f32 v[28:29], v[28:29], v[24:25]
	v_pk_mul_f32 v[30:31], v[30:31], v[26:27]
	v_pk_mul_f32 v[12:13], v[12:13], s[36:37] op_sel_hi:[1,0]
	v_pk_mul_f32 v[16:17], v[16:17], s[36:37] op_sel_hi:[1,0]
	v_pk_mul_f32 v[28:29], v[28:29], s[36:37] op_sel_hi:[1,0]
	v_pk_mul_f32 v[30:31], v[30:31], s[36:37] op_sel_hi:[1,0]
	v_exp_f32_e32 v12, v12
	v_exp_f32_e32 v13, v13
	v_exp_f32_e32 v16, v16
	v_exp_f32_e32 v17, v17
	v_exp_f32_e32 v28, v28
	v_exp_f32_e32 v29, v29
	v_exp_f32_e32 v30, v30
	v_exp_f32_e32 v31, v31
	v_pk_add_f32 v[12:13], v[12:13], 1.0 op_sel_hi:[1,0]
	v_pk_add_f32 v[16:17], v[16:17], 1.0 op_sel_hi:[1,0]
	v_pk_add_f32 v[28:29], v[28:29], 1.0 op_sel_hi:[1,0]
	v_pk_add_f32 v[30:31], v[30:31], 1.0 op_sel_hi:[1,0]
	v_rcp_f32_e32 v12, v12
	v_rcp_f32_e32 v13, v13
	v_rcp_f32_e32 v46, v16
	v_rcp_f32_e32 v47, v17
	v_rcp_f32_e32 v28, v28
	v_rcp_f32_e32 v29, v29
	v_rcp_f32_e32 v30, v30
	v_rcp_f32_e32 v31, v31
	v_pk_mul_f32 v[16:17], v[12:13], v[14:15]
	v_pk_mul_f32 v[14:15], v[46:47], v[10:11]
	v_pk_mul_f32 v[12:13], v[28:29], v[24:25]
	v_pk_mul_f32 v[10:11], v[30:31], v[26:27]
	v_cvt_pk_bf16_f32 v26, v16, v17
	v_cvt_pk_bf16_f32 v24, v14, v15
	v_cvt_pk_bf16_f32 v23, v12, v13
	v_pk_mul_f32 v[46:47], v[72:73], v[72:73]
	v_cvt_pk_bf16_f32 v21, v10, v11
	v_mov_b32_e32 v48, v46
	v_mov_b32_e32 v72, v47
	v_pk_add_f32 v[40:41], v[48:49], v[72:73]
	v_pk_add_f32 v[32:33], v[38:39], v[32:33]
	v_pk_mul_f32 v[36:37], v[76:77], v[76:77]
	v_mov_b32_e32 v43, v78
	v_mov_b32_e32 v42, v34
	v_mov_b32_e32 v78, v35
	v_pk_add_f32 v[32:33], v[40:41], v[32:33]
	v_pk_mul_f32 v[38:39], v[74:75], v[74:75]
	v_mov_b32_e32 v45, v76
	v_mov_b32_e32 v44, v36
	v_mov_b32_e32 v76, v37
	v_pk_add_f32 v[34:35], v[42:43], v[78:79]
	v_pk_mul_f32 v[40:41], v[80:81], v[80:81]
	v_mov_b32_e32 v47, v74
	v_mov_b32_e32 v46, v38
	v_mov_b32_e32 v74, v39
	v_pk_add_f32 v[36:37], v[44:45], v[76:77]
	v_pk_add_f32 v[32:33], v[32:33], v[34:35]
	v_mov_b32_e32 v49, v80
	v_mov_b32_e32 v48, v40
	v_mov_b32_e32 v80, v41
	v_pk_add_f32 v[38:39], v[46:47], v[74:75]
	v_pk_add_f32 v[32:33], v[36:37], v[32:33]
	v_pk_add_f32 v[40:41], v[48:49], v[80:81]
	v_pk_add_f32 v[32:33], v[38:39], v[32:33]
	v_pk_mul_f32 v[36:37], v[86:87], v[86:87]
	v_pk_add_f32 v[34:35], v[40:41], v[32:33]
	v_pk_mul_f32 v[32:33], v[90:91], v[90:91]
	v_pk_mul_f32 v[38:39], v[84:85], v[84:85]
	v_mov_b32_e32 v43, v90
	v_mov_b32_e32 v42, v32
	v_mov_b32_e32 v90, v33
	v_pk_mul_f32 v[40:41], v[82:83], v[82:83]
	v_mov_b32_e32 v45, v86
	v_mov_b32_e32 v47, v84
	v_mov_b32_e32 v44, v36
	v_mov_b32_e32 v86, v37
	v_mov_b32_e32 v46, v38
	v_mov_b32_e32 v84, v39
	v_pk_add_f32 v[36:37], v[42:43], v[90:91]
	v_mov_b32_e32 v49, v82
	v_mov_b32_e32 v48, v40
	v_mov_b32_e32 v82, v41
	v_pk_add_f32 v[38:39], v[44:45], v[86:87]
	v_pk_add_f32 v[40:41], v[46:47], v[84:85]
	v_pk_add_f32 v[34:35], v[34:35], v[36:37]
	v_pk_mul_f32 v[36:37], v[94:95], v[94:95]
	v_pk_add_f32 v[34:35], v[38:39], v[34:35]
	v_mov_b32_e32 v39, v96
	v_pk_add_f32 v[34:35], v[40:41], v[34:35]
	v_mov_b32_e32 v41, v94
	v_mov_b32_e32 v40, v36
	v_mov_b32_e32 v94, v37
	v_pk_mul_f32 v[54:55], v[98:99], v[98:99]
	v_pk_add_f32 v[36:37], v[40:41], v[94:95]
	v_mov_b32_e32 v57, v98
	v_mov_b32_e32 v56, v54
	v_mov_b32_e32 v98, v55
	v_pk_add_f32 v[40:41], v[56:57], v[98:99]
	v_mov_b32_e32 v55, v100
	v_mov_b32_e32 v57, v106
	v_mov_b32_e32 v158, s17
	v_pk_mul_f32 v[58:59], v[10:11], v[10:11]
	v_mov_b32_e32 v61, v12
	v_mov_b32_e32 v63, v10
	v_mov_b32_e32 v62, v58
	v_mov_b32_e32 v10, v59
	v_pk_add_f32 v[10:11], v[62:63], v[10:11]
	v_mov_b32_e32 v76, 0
	v_mov_b32_e32 v77, 0
	v_mov_b32_e32 v78, 0
	v_mov_b32_e32 v79, 0
	v_mov_b32_e32 v72, 0
	v_mov_b32_e32 v73, 0
	v_mov_b32_e32 v74, 0
	v_mov_b32_e32 v75, 0
	s_waitcnt vmcnt(1)
	v_mov_b32_e32 v28, v228
	v_mov_b32_e32 v29, v229
	v_mov_b32_e32 v30, v230
	v_mov_b32_e32 v31, v231
	v_lshlrev_b32_e32 v32, 16, v28
	v_and_b32_e32 v33, 0xffff0000, v28
	v_lshlrev_b32_e32 v28, 16, v29
	v_and_b32_e32 v29, 0xffff0000, v29
	v_lshlrev_b32_e32 v42, 16, v30
	v_and_b32_e32 v43, 0xffff0000, v30
	v_lshlrev_b32_e32 v30, 16, v31
	v_and_b32_e32 v31, 0xffff0000, v31
	v_pk_mul_f32 v[44:45], v[32:33], v[32:33]
	v_pk_mul_f32 v[46:47], v[28:29], v[28:29]
	v_pk_mul_f32 v[50:51], v[42:43], v[42:43]
	v_pk_mul_f32 v[52:53], v[30:31], v[30:31]
	v_pk_fma_f32 v[44:45], v[44:45], s[38:39], 1.0 op_sel_hi:[1,0,0]
	v_pk_fma_f32 v[46:47], v[46:47], s[38:39], 1.0 op_sel_hi:[1,0,0]
	v_pk_fma_f32 v[50:51], v[50:51], s[38:39], 1.0 op_sel_hi:[1,0,0]
	v_pk_fma_f32 v[52:53], v[52:53], s[38:39], 1.0 op_sel_hi:[1,0,0]
	v_pk_mul_f32 v[44:45], v[44:45], v[32:33]
	v_pk_mul_f32 v[46:47], v[46:47], v[28:29]
	v_pk_mul_f32 v[50:51], v[50:51], v[42:43]
	v_pk_mul_f32 v[52:53], v[52:53], v[30:31]
	v_pk_mul_f32 v[44:45], v[44:45], s[36:37] op_sel_hi:[1,0]
	v_pk_mul_f32 v[46:47], v[46:47], s[36:37] op_sel_hi:[1,0]
	v_pk_mul_f32 v[50:51], v[50:51], s[36:37] op_sel_hi:[1,0]
	v_pk_mul_f32 v[52:53], v[52:53], s[36:37] op_sel_hi:[1,0]
	v_exp_f32_e32 v44, v44
	v_exp_f32_e32 v45, v45
	v_exp_f32_e32 v46, v46
	v_exp_f32_e32 v47, v47
	v_exp_f32_e32 v50, v50
	v_exp_f32_e32 v51, v51
	v_exp_f32_e32 v52, v52
	v_exp_f32_e32 v53, v53
	v_pk_add_f32 v[44:45], v[44:45], 1.0 op_sel_hi:[1,0]
	v_pk_add_f32 v[46:47], v[46:47], 1.0 op_sel_hi:[1,0]
	v_pk_add_f32 v[50:51], v[50:51], 1.0 op_sel_hi:[1,0]
	v_pk_add_f32 v[52:53], v[52:53], 1.0 op_sel_hi:[1,0]
	v_rcp_f32_e32 v44, v44
	v_rcp_f32_e32 v45, v45
	v_rcp_f32_e32 v46, v46
	v_rcp_f32_e32 v47, v47
	v_rcp_f32_e32 v50, v50
	v_rcp_f32_e32 v51, v51
	v_rcp_f32_e32 v52, v52
	v_rcp_f32_e32 v53, v53
	v_pk_mul_f32 v[44:45], v[44:45], v[32:33]
	v_pk_mul_f32 v[46:47], v[46:47], v[28:29]
	v_pk_mul_f32 v[42:43], v[50:51], v[42:43]
	v_pk_mul_f32 v[50:51], v[52:53], v[30:31]
	v_cvt_pk_bf16_f32 v29, v44, v45
	v_cvt_pk_bf16_f32 v28, v46, v47
	v_cvt_pk_bf16_f32 v27, v42, v43
	v_mov_b32_e32 v53, v92
	v_cvt_pk_bf16_f32 v25, v50, v51
	v_pk_add_f32 v[4:5], v[48:49], v[82:83]
	v_pk_mul_f32 v[48:49], v[92:93], v[92:93]
	v_pk_add_f32 v[4:5], v[4:5], v[34:35]
	v_pk_mul_f32 v[34:35], v[96:97], v[96:97]
	v_mov_b32_e32 v52, v48
	v_mov_b32_e32 v38, v34
	v_mov_b32_e32 v96, v35
	v_pk_add_f32 v[34:35], v[38:39], v[96:97]
	v_mov_b32_e32 v92, v49
	v_pk_add_f32 v[4:5], v[4:5], v[34:35]
	v_pk_add_f32 v[38:39], v[52:53], v[92:93]
	v_pk_add_f32 v[4:5], v[36:37], v[4:5]
	v_pk_mul_f32 v[34:35], v[104:105], v[104:105]
	v_pk_add_f32 v[4:5], v[38:39], v[4:5]
	v_pk_mul_f32 v[36:37], v[102:103], v[102:103]
	v_mov_b32_e32 v49, v104
	v_mov_b32_e32 v48, v34
	v_mov_b32_e32 v104, v35
	v_pk_add_f32 v[4:5], v[40:41], v[4:5]
	v_pk_mul_f32 v[38:39], v[100:101], v[100:101]
	v_mov_b32_e32 v53, v102
	v_mov_b32_e32 v52, v36
	v_mov_b32_e32 v102, v37
	v_pk_add_f32 v[34:35], v[48:49], v[104:105]
	v_pk_mul_f32 v[40:41], v[106:107], v[106:107]
	v_mov_b32_e32 v54, v38
	v_mov_b32_e32 v100, v39
	v_pk_add_f32 v[36:37], v[52:53], v[102:103]
	v_pk_add_f32 v[4:5], v[4:5], v[34:35]
	v_mov_b32_e32 v56, v40
	v_mov_b32_e32 v106, v41
	v_pk_add_f32 v[38:39], v[54:55], v[100:101]
	v_pk_add_f32 v[4:5], v[36:37], v[4:5]
	v_pk_mul_f32 v[34:35], v[8:9], v[8:9]
	v_pk_add_f32 v[40:41], v[56:57], v[106:107]
	v_pk_add_f32 v[4:5], v[38:39], v[4:5]
	v_pk_mul_f32 v[36:37], v[6:7], v[6:7]
	v_mov_b32_e32 v49, v8
	v_mov_b32_e32 v48, v34
	v_mov_b32_e32 v8, v35
	v_pk_add_f32 v[4:5], v[40:41], v[4:5]
	v_pk_mul_f32 v[38:39], v[2:3], v[2:3]
	v_mov_b32_e32 v53, v6
	v_mov_b32_e32 v52, v36
	v_mov_b32_e32 v6, v37
	v_pk_add_f32 v[8:9], v[48:49], v[8:9]
	v_pk_mul_f32 v[40:41], v[0:1], v[0:1]
	v_mov_b32_e32 v55, v2
	v_mov_b32_e32 v54, v38
	v_mov_b32_e32 v2, v39
	v_pk_add_f32 v[6:7], v[52:53], v[6:7]
	v_pk_add_f32 v[4:5], v[4:5], v[8:9]
	v_mov_b32_e32 v57, v0
	v_mov_b32_e32 v56, v40
	v_mov_b32_e32 v0, v41
	v_pk_add_f32 v[2:3], v[54:55], v[2:3]
	v_pk_add_f32 v[4:5], v[6:7], v[4:5]
	v_pk_add_f32 v[0:1], v[56:57], v[0:1]
	v_pk_add_f32 v[2:3], v[2:3], v[4:5]
	v_pk_mul_f32 v[8:9], v[16:17], v[16:17]
	v_pk_add_f32 v[0:1], v[0:1], v[2:3]
	v_mov_b32_e32 v35, v16
	v_pk_mul_f32 v[52:53], v[14:15], v[14:15]
	v_mov_b32_e32 v34, v8
	v_mov_b32_e32 v16, v9
	v_mov_b32_e32 v55, v14
	v_pk_mul_f32 v[56:57], v[12:13], v[12:13]
	v_mov_b32_e32 v54, v52
	v_mov_b32_e32 v14, v53
	v_pk_add_f32 v[8:9], v[34:35], v[16:17]
	v_mov_b32_e32 v60, v56
	v_mov_b32_e32 v12, v57
	v_pk_add_f32 v[14:15], v[54:55], v[14:15]
	v_pk_add_f32 v[0:1], v[0:1], v[8:9]
	v_pk_add_f32 v[12:13], v[60:61], v[12:13]
	v_pk_add_f32 v[0:1], v[14:15], v[0:1]
	v_pk_mul_f32 v[8:9], v[44:45], v[44:45]
	v_pk_add_f32 v[0:1], v[12:13], v[0:1]
	v_mov_b32_e32 v17, v44
	s_waitcnt vmcnt(0)
	v_mov_b32_e32 v30, v232
	v_mov_b32_e32 v31, v233
	v_mov_b32_e32 v32, v234
	v_mov_b32_e32 v33, v235
	v_lshlrev_b32_e32 v2, 16, v30
	v_and_b32_e32 v3, 0xffff0000, v30
	v_lshlrev_b32_e32 v4, 16, v31
	v_and_b32_e32 v5, 0xffff0000, v31
	v_lshlrev_b32_e32 v6, 16, v32
	v_and_b32_e32 v7, 0xffff0000, v32
	v_lshlrev_b32_e32 v30, 16, v33
	v_and_b32_e32 v31, 0xffff0000, v33
	v_pk_mul_f32 v[32:33], v[2:3], v[2:3]
	v_pk_mul_f32 v[36:37], v[4:5], v[4:5]
	v_pk_mul_f32 v[38:39], v[6:7], v[6:7]
	v_pk_mul_f32 v[40:41], v[30:31], v[30:31]
	v_pk_fma_f32 v[32:33], v[32:33], s[38:39], 1.0 op_sel_hi:[1,0,0]
	v_pk_fma_f32 v[36:37], v[36:37], s[38:39], 1.0 op_sel_hi:[1,0,0]
	v_pk_fma_f32 v[38:39], v[38:39], s[38:39], 1.0 op_sel_hi:[1,0,0]
	v_pk_fma_f32 v[40:41], v[40:41], s[38:39], 1.0 op_sel_hi:[1,0,0]
	v_pk_mul_f32 v[32:33], v[32:33], v[2:3]
	v_pk_mul_f32 v[36:37], v[36:37], v[4:5]
	v_pk_mul_f32 v[38:39], v[38:39], v[6:7]
	v_pk_mul_f32 v[40:41], v[40:41], v[30:31]
	v_pk_mul_f32 v[32:33], v[32:33], s[36:37] op_sel_hi:[1,0]
	v_pk_mul_f32 v[36:37], v[36:37], s[36:37] op_sel_hi:[1,0]
	v_pk_mul_f32 v[38:39], v[38:39], s[36:37] op_sel_hi:[1,0]
	v_pk_mul_f32 v[40:41], v[40:41], s[36:37] op_sel_hi:[1,0]
	v_exp_f32_e32 v32, v32
	v_exp_f32_e32 v33, v33
	v_exp_f32_e32 v36, v36
	v_exp_f32_e32 v37, v37
	v_exp_f32_e32 v38, v38
	v_exp_f32_e32 v39, v39
	v_exp_f32_e32 v40, v40
	v_exp_f32_e32 v41, v41
	v_pk_add_f32 v[32:33], v[32:33], 1.0 op_sel_hi:[1,0]
	v_pk_add_f32 v[36:37], v[36:37], 1.0 op_sel_hi:[1,0]
	v_pk_add_f32 v[38:39], v[38:39], 1.0 op_sel_hi:[1,0]
	v_pk_add_f32 v[40:41], v[40:41], 1.0 op_sel_hi:[1,0]
	v_rcp_f32_e32 v32, v32
	v_rcp_f32_e32 v33, v33
	v_rcp_f32_e32 v36, v36
	v_rcp_f32_e32 v37, v37
	v_rcp_f32_e32 v38, v38
	v_rcp_f32_e32 v39, v39
	v_rcp_f32_e32 v40, v40
	v_rcp_f32_e32 v41, v41
	v_pk_mul_f32 v[32:33], v[32:33], v[2:3]
	v_pk_mul_f32 v[36:37], v[36:37], v[4:5]
	v_pk_mul_f32 v[38:39], v[38:39], v[6:7]
	v_pk_mul_f32 v[30:31], v[40:41], v[30:31]
	v_cvt_pk_bf16_f32 v6, v32, v33
	v_cvt_pk_bf16_f32 v5, v36, v37
	v_cvt_pk_bf16_f32 v4, v38, v39
	v_pk_add_f32 v[0:1], v[10:11], v[0:1]
	v_cvt_pk_bf16_f32 v3, v30, v31
	s_waitcnt lgkmcnt(0)
	ds_read_b128 v[172:175], v255 offset:0
	ds_read_b128 v[176:179], v255 offset:16
	ds_read_b128 v[180:183], v255 offset:32
	ds_read_b128 v[184:187], v255 offset:48
	ds_read_b128 v[188:191], v255 offset:64
	ds_read_b128 v[192:195], v255 offset:80
	ds_read_b128 v[196:199], v255 offset:96
	ds_read_b128 v[200:203], v255 offset:112
	ds_read_b128 v[204:207], v255 offset:128
	ds_read_b128 v[208:211], v255 offset:144
	ds_read_b128 v[212:215], v255 offset:160
	ds_read_b128 v[216:219], v255 offset:176
	ds_read_b128 v[220:223], v255 offset:192
	ds_read_b128 v[228:231], v255 offset:208
	ds_read_b128 v[232:235], v255 offset:224
	ds_read_b128 v[236:239], v255 offset:240
	v_pk_mul_f32 v[10:11], v[46:47], v[46:47]
	v_mov_b32_e32 v16, v8
	v_mov_b32_e32 v44, v9
	v_pk_mul_f32 v[12:13], v[42:43], v[42:43]
	v_mov_b32_e32 v35, v46
	v_mov_b32_e32 v34, v10
	v_mov_b32_e32 v46, v11
	v_pk_add_f32 v[8:9], v[16:17], v[44:45]
	v_pk_mul_f32 v[14:15], v[50:51], v[50:51]
	v_mov_b32_e32 v53, v42
	v_mov_b32_e32 v52, v12
	v_mov_b32_e32 v42, v13
	v_pk_add_f32 v[10:11], v[34:35], v[46:47]
	v_pk_add_f32 v[0:1], v[0:1], v[8:9]
	v_mov_b32_e32 v55, v50
	v_mov_b32_e32 v54, v14
	v_mov_b32_e32 v50, v15
	v_pk_add_f32 v[12:13], v[52:53], v[42:43]
	v_pk_add_f32 v[0:1], v[10:11], v[0:1]
	v_pk_mul_f32 v[8:9], v[32:33], v[32:33]
	v_pk_add_f32 v[14:15], v[54:55], v[50:51]
	v_pk_add_f32 v[0:1], v[12:13], v[0:1]
	v_pk_mul_f32 v[10:11], v[36:37], v[36:37]
	v_mov_b32_e32 v17, v32
	v_mov_b32_e32 v16, v8
	v_mov_b32_e32 v32, v9
	v_pk_add_f32 v[0:1], v[14:15], v[0:1]
	v_pk_mul_f32 v[12:13], v[38:39], v[38:39]
	v_mov_b32_e32 v35, v36
	v_mov_b32_e32 v34, v10
	v_mov_b32_e32 v36, v11
	v_pk_add_f32 v[8:9], v[16:17], v[32:33]
	v_pk_mul_f32 v[14:15], v[30:31], v[30:31]
	v_mov_b32_e32 v43, v38
	v_mov_b32_e32 v42, v12
	v_mov_b32_e32 v38, v13
	v_pk_add_f32 v[10:11], v[34:35], v[36:37]
	v_pk_add_f32 v[0:1], v[0:1], v[8:9]
	v_mov_b32_e32 v45, v30
	v_mov_b32_e32 v44, v14
	v_mov_b32_e32 v30, v15
	v_pk_add_f32 v[12:13], v[42:43], v[38:39]
	v_pk_add_f32 v[0:1], v[10:11], v[0:1]
	v_pk_add_f32 v[14:15], v[44:45], v[30:31]
	v_pk_add_f32 v[0:1], v[12:13], v[0:1]
	v_lshlrev_b32_e32 v8, 16, v114
	v_pk_add_f32 v[0:1], v[14:15], v[0:1]
	v_and_b32_e32 v9, 0xffff0000, v114
	v_pk_mul_f32 v[0:1], v[0:1], s[40:41] op_sel_hi:[1,0]
	v_lshlrev_b32_e32 v12, 16, v112
	v_fma_f32 v2, -v1, v1, v0
	v_max_f32_e32 v2, 0, v2
	v_add_f32_e32 v2, 0x3727c5ac, v2
	v_rsq_f32_e32 v2, v2
	v_pk_add_f32 v[8:9], v[8:9], v[0:1] op_sel:[0,1] neg_lo:[0,1] neg_hi:[0,1]
	v_and_b32_e32 v13, 0xffff0000, v112
	s_mul_i32 s41, s41, 0x8a00
	v_pk_mul_f32 v[8:9], v[8:9], v[2:3] op_sel_hi:[1,0]
	v_pk_add_f32 v[12:13], v[12:13], v[0:1] op_sel:[0,1] neg_lo:[0,1] neg_hi:[0,1]
	s_add_i32 s17, s41, 0
	v_pk_mul_f32 v[12:13], v[12:13], v[2:3] op_sel_hi:[1,0]
	v_lshl_add_u32 v7, v109, 1, s17
	v_and_b32_e32 v15, 0xffff0000, v3
	s_waitcnt lgkmcnt(15)
	v_pk_fma_f32 v[8:9], v[172:173], v[8:9], v[174:175]
	s_nop 0
	v_cvt_pk_bf16_f32 v14, v8, v9
	ds_write_b16 v7, v14
	ds_write_b16_d16_hi v7, v14 offset:272
	s_waitcnt lgkmcnt(15)
	v_pk_fma_f32 v[8:9], v[176:177], v[12:13], v[178:179]
	s_nop 0
	v_cvt_pk_bf16_f32 v14, v8, v9
	v_lshlrev_b32_e32 v12, 16, v111
	v_and_b32_e32 v13, 0xffff0000, v111
	v_pk_add_f32 v[12:13], v[12:13], v[0:1] op_sel:[0,1] neg_lo:[0,1] neg_hi:[0,1]
	ds_write_b16 v7, v14 offset:544
	ds_write_b16_d16_hi v7, v14 offset:816
	v_pk_mul_f32 v[12:13], v[12:13], v[2:3] op_sel_hi:[1,0]
	s_waitcnt lgkmcnt(15)
	v_pk_fma_f32 v[8:9], v[180:181], v[12:13], v[182:183]
	s_nop 0
	v_cvt_pk_bf16_f32 v14, v8, v9
	v_lshlrev_b32_e32 v12, 16, v110
	v_and_b32_e32 v13, 0xffff0000, v110
	v_pk_add_f32 v[12:13], v[12:13], v[0:1] op_sel:[0,1] neg_lo:[0,1] neg_hi:[0,1]
	ds_write_b16 v7, v14 offset:1088
	ds_write_b16_d16_hi v7, v14 offset:1360
	v_pk_mul_f32 v[12:13], v[12:13], v[2:3] op_sel_hi:[1,0]
	s_waitcnt lgkmcnt(15)
	v_pk_fma_f32 v[8:9], v[184:185], v[12:13], v[186:187]
	s_nop 0
	v_cvt_pk_bf16_f32 v14, v8, v9
	v_lshlrev_b32_e32 v12, 16, v117
	v_and_b32_e32 v13, 0xffff0000, v117
	v_pk_add_f32 v[12:13], v[12:13], v[0:1] op_sel:[0,1] neg_lo:[0,1] neg_hi:[0,1]
	ds_write_b16 v7, v14 offset:1632
	ds_write_b16_d16_hi v7, v14 offset:1904
	v_pk_mul_f32 v[12:13], v[12:13], v[2:3] op_sel_hi:[1,0]
	s_waitcnt lgkmcnt(15)
	v_pk_fma_f32 v[8:9], v[188:189], v[12:13], v[190:191]
	s_nop 0
	v_cvt_pk_bf16_f32 v14, v8, v9
	v_lshlrev_b32_e32 v12, 16, v116
	v_and_b32_e32 v13, 0xffff0000, v116
	v_pk_add_f32 v[12:13], v[12:13], v[0:1] op_sel:[0,1] neg_lo:[0,1] neg_hi:[0,1]
	ds_write_b16 v7, v14 offset:2176
	ds_write_b16_d16_hi v7, v14 offset:2448
	v_pk_mul_f32 v[12:13], v[12:13], v[2:3] op_sel_hi:[1,0]
	s_waitcnt lgkmcnt(15)
	v_pk_fma_f32 v[8:9], v[12:13], v[192:193], v[194:195]
	s_nop 0
	v_cvt_pk_bf16_f32 v14, v8, v9
	v_lshlrev_b32_e32 v12, 16, v115
	v_and_b32_e32 v13, 0xffff0000, v115
	v_pk_add_f32 v[12:13], v[12:13], v[0:1] op_sel:[0,1] neg_lo:[0,1] neg_hi:[0,1]
	ds_write_b16 v7, v14 offset:2720
	ds_write_b16_d16_hi v7, v14 offset:2992
	v_pk_mul_f32 v[12:13], v[12:13], v[2:3] op_sel_hi:[1,0]
	v_bfe_u32 v115, v108, 5, 1
	v_lshlrev_b32_e32 v88, 5, v115
	v_lshl_add_u64 v[90:91], s[12:13], 0, v[88:89]
	s_waitcnt lgkmcnt(15)
	v_pk_fma_f32 v[8:9], v[12:13], v[196:197], v[198:199]
	s_nop 0
	v_cvt_pk_bf16_f32 v14, v8, v9
	v_lshlrev_b32_e32 v12, 16, v113
	v_and_b32_e32 v13, 0xffff0000, v113
	v_pk_add_f32 v[12:13], v[12:13], v[0:1] op_sel:[0,1] neg_lo:[0,1] neg_hi:[0,1]
	ds_write_b16 v7, v14 offset:3264
	ds_write_b16_d16_hi v7, v14 offset:3536
	v_pk_mul_f32 v[12:13], v[12:13], v[2:3] op_sel_hi:[1,0]
	s_waitcnt lgkmcnt(15)
	v_pk_fma_f32 v[8:9], v[12:13], v[200:201], v[202:203]
	s_nop 0
	v_cvt_pk_bf16_f32 v14, v8, v9
	ds_read_b128 v[172:175], v255 offset:256
	ds_read_b128 v[176:179], v255 offset:272
	ds_read_b128 v[180:183], v255 offset:288
	ds_read_b128 v[184:187], v255 offset:304
	ds_read_b128 v[188:191], v255 offset:320
	ds_read_b128 v[192:195], v255 offset:336
	ds_read_b128 v[196:199], v255 offset:352
	ds_read_b128 v[200:203], v255 offset:368
	v_lshlrev_b32_e32 v12, 16, v122
	v_and_b32_e32 v13, 0xffff0000, v122
	v_pk_add_f32 v[12:13], v[12:13], v[0:1] op_sel:[0,1] neg_lo:[0,1] neg_hi:[0,1]
	ds_write_b16 v7, v14 offset:3808
	ds_write_b16_d16_hi v7, v14 offset:4080
	v_pk_mul_f32 v[12:13], v[12:13], v[2:3] op_sel_hi:[1,0]
	s_waitcnt lgkmcnt(15)
	v_pk_fma_f32 v[8:9], v[12:13], v[204:205], v[206:207]
	s_nop 0
	v_cvt_pk_bf16_f32 v14, v8, v9
	v_lshlrev_b32_e32 v12, 16, v120
	v_and_b32_e32 v13, 0xffff0000, v120
	v_pk_add_f32 v[12:13], v[12:13], v[0:1] op_sel:[0,1] neg_lo:[0,1] neg_hi:[0,1]
	ds_write_b16 v7, v14 offset:4352
	ds_write_b16_d16_hi v7, v14 offset:4624
	v_pk_mul_f32 v[12:13], v[12:13], v[2:3] op_sel_hi:[1,0]
	s_waitcnt lgkmcnt(15)
	v_pk_fma_f32 v[8:9], v[12:13], v[208:209], v[210:211]
	s_nop 0
	v_cvt_pk_bf16_f32 v14, v8, v9
	v_lshlrev_b32_e32 v12, 16, v119
	v_and_b32_e32 v13, 0xffff0000, v119
	v_pk_add_f32 v[12:13], v[12:13], v[0:1] op_sel:[0,1] neg_lo:[0,1] neg_hi:[0,1]
	ds_write_b16 v7, v14 offset:4896
	ds_write_b16_d16_hi v7, v14 offset:5168
	v_pk_mul_f32 v[12:13], v[12:13], v[2:3] op_sel_hi:[1,0]
	s_waitcnt lgkmcnt(15)
	v_pk_fma_f32 v[8:9], v[12:13], v[212:213], v[214:215]
	s_nop 0
	v_cvt_pk_bf16_f32 v14, v8, v9
	v_lshlrev_b32_e32 v12, 16, v118
	v_and_b32_e32 v13, 0xffff0000, v118
	v_pk_add_f32 v[12:13], v[12:13], v[0:1] op_sel:[0,1] neg_lo:[0,1] neg_hi:[0,1]
	ds_write_b16 v7, v14 offset:5440
	ds_write_b16_d16_hi v7, v14 offset:5712
	v_pk_mul_f32 v[12:13], v[12:13], v[2:3] op_sel_hi:[1,0]
	v_and_b32_e32 v118, 31, v108
	s_waitcnt lgkmcnt(15)
	v_pk_fma_f32 v[8:9], v[12:13], v[216:217], v[218:219]
	s_nop 0
	v_cvt_pk_bf16_f32 v14, v8, v9
	v_lshlrev_b32_e32 v12, 16, v126
	v_and_b32_e32 v13, 0xffff0000, v126
	v_pk_add_f32 v[12:13], v[12:13], v[0:1] op_sel:[0,1] neg_lo:[0,1] neg_hi:[0,1]
	ds_write_b16 v7, v14 offset:5984
	ds_write_b16_d16_hi v7, v14 offset:6256
	v_pk_mul_f32 v[12:13], v[12:13], v[2:3] op_sel_hi:[1,0]
	s_waitcnt lgkmcnt(15)
	v_pk_fma_f32 v[8:9], v[12:13], v[220:221], v[222:223]
	s_nop 0
	v_cvt_pk_bf16_f32 v14, v8, v9
	v_lshlrev_b32_e32 v12, 16, v124
	v_and_b32_e32 v13, 0xffff0000, v124
	v_pk_add_f32 v[12:13], v[12:13], v[0:1] op_sel:[0,1] neg_lo:[0,1] neg_hi:[0,1]
	ds_write_b16 v7, v14 offset:6528
	ds_write_b16_d16_hi v7, v14 offset:6800
	v_pk_mul_f32 v[12:13], v[12:13], v[2:3] op_sel_hi:[1,0]
	s_waitcnt lgkmcnt(15)
	v_pk_fma_f32 v[8:9], v[12:13], v[228:229], v[230:231]
	s_nop 0
	v_cvt_pk_bf16_f32 v14, v8, v9
	v_lshlrev_b32_e32 v12, 16, v123
	v_and_b32_e32 v13, 0xffff0000, v123
	v_pk_add_f32 v[12:13], v[12:13], v[0:1] op_sel:[0,1] neg_lo:[0,1] neg_hi:[0,1]
	ds_write_b16 v7, v14 offset:7072
	ds_write_b16_d16_hi v7, v14 offset:7344
	v_pk_mul_f32 v[12:13], v[12:13], v[2:3] op_sel_hi:[1,0]
	s_waitcnt lgkmcnt(15)
	v_pk_fma_f32 v[8:9], v[12:13], v[232:233], v[234:235]
	s_nop 0
	v_cvt_pk_bf16_f32 v14, v8, v9
	v_lshlrev_b32_e32 v12, 16, v121
	v_and_b32_e32 v13, 0xffff0000, v121
	v_pk_add_f32 v[12:13], v[12:13], v[0:1] op_sel:[0,1] neg_lo:[0,1] neg_hi:[0,1]
	ds_write_b16 v7, v14 offset:7616
	ds_write_b16_d16_hi v7, v14 offset:7888
	v_pk_mul_f32 v[12:13], v[12:13], v[2:3] op_sel_hi:[1,0]
	s_waitcnt lgkmcnt(15)
	v_pk_fma_f32 v[8:9], v[12:13], v[236:237], v[238:239]
	s_nop 0
	v_cvt_pk_bf16_f32 v14, v8, v9
	ds_read_b128 v[204:207], v255 offset:384
	ds_read_b128 v[208:211], v255 offset:400
	ds_read_b128 v[212:215], v255 offset:416
	ds_read_b128 v[216:219], v255 offset:432
	ds_read_b128 v[220:223], v255 offset:448
	ds_read_b128 v[228:231], v255 offset:464
	ds_read_b128 v[232:235], v255 offset:480
	ds_read_b128 v[236:239], v255 offset:496
	v_lshlrev_b32_e32 v12, 16, v129
	v_and_b32_e32 v13, 0xffff0000, v129
	v_pk_add_f32 v[12:13], v[12:13], v[0:1] op_sel:[0,1] neg_lo:[0,1] neg_hi:[0,1]
	ds_write_b16 v7, v14 offset:8160
	ds_write_b16_d16_hi v7, v14 offset:8432
	v_pk_mul_f32 v[12:13], v[12:13], v[2:3] op_sel_hi:[1,0]
	s_waitcnt lgkmcnt(15)
	v_pk_fma_f32 v[8:9], v[12:13], v[172:173], v[174:175]
	s_nop 0
	v_cvt_pk_bf16_f32 v14, v8, v9
	v_lshlrev_b32_e32 v12, 16, v128
	v_and_b32_e32 v13, 0xffff0000, v128
	v_pk_add_f32 v[12:13], v[12:13], v[0:1] op_sel:[0,1] neg_lo:[0,1] neg_hi:[0,1]
	ds_write_b16 v7, v14 offset:8704
	ds_write_b16_d16_hi v7, v14 offset:8976
	v_pk_mul_f32 v[12:13], v[12:13], v[2:3] op_sel_hi:[1,0]
	s_waitcnt lgkmcnt(15)
	v_pk_fma_f32 v[8:9], v[12:13], v[176:177], v[178:179]
	s_nop 0
	v_cvt_pk_bf16_f32 v14, v8, v9
	v_lshlrev_b32_e32 v12, 16, v127
	v_and_b32_e32 v13, 0xffff0000, v127
	v_pk_add_f32 v[12:13], v[12:13], v[0:1] op_sel:[0,1] neg_lo:[0,1] neg_hi:[0,1]
	ds_write_b16 v7, v14 offset:9248
	ds_write_b16_d16_hi v7, v14 offset:9520
	v_pk_mul_f32 v[12:13], v[12:13], v[2:3] op_sel_hi:[1,0]
	s_waitcnt lgkmcnt(15)
	v_pk_fma_f32 v[8:9], v[12:13], v[180:181], v[182:183]
	s_nop 0
	v_cvt_pk_bf16_f32 v14, v8, v9
	v_lshlrev_b32_e32 v12, 16, v125
	v_and_b32_e32 v13, 0xffff0000, v125
	v_pk_add_f32 v[12:13], v[12:13], v[0:1] op_sel:[0,1] neg_lo:[0,1] neg_hi:[0,1]
	ds_write_b16 v7, v14 offset:9792
	ds_write_b16_d16_hi v7, v14 offset:10064
	v_pk_mul_f32 v[12:13], v[12:13], v[2:3] op_sel_hi:[1,0]
	s_waitcnt lgkmcnt(15)
	v_pk_fma_f32 v[8:9], v[12:13], v[184:185], v[186:187]
	s_nop 0
	v_cvt_pk_bf16_f32 v14, v8, v9
	v_lshlrev_b32_e32 v12, 16, v134
	v_and_b32_e32 v13, 0xffff0000, v134
	v_pk_add_f32 v[12:13], v[12:13], v[0:1] op_sel:[0,1] neg_lo:[0,1] neg_hi:[0,1]
	ds_write_b16 v7, v14 offset:10336
	ds_write_b16_d16_hi v7, v14 offset:10608
	v_pk_mul_f32 v[12:13], v[12:13], v[2:3] op_sel_hi:[1,0]
	s_waitcnt lgkmcnt(15)
	v_pk_fma_f32 v[8:9], v[12:13], v[188:189], v[190:191]
	s_nop 0
	v_cvt_pk_bf16_f32 v14, v8, v9
	v_lshlrev_b32_e32 v12, 16, v132
	v_and_b32_e32 v13, 0xffff0000, v132
	v_pk_add_f32 v[12:13], v[12:13], v[0:1] op_sel:[0,1] neg_lo:[0,1] neg_hi:[0,1]
	ds_write_b16 v7, v14 offset:10880
	ds_write_b16_d16_hi v7, v14 offset:11152
	v_pk_mul_f32 v[12:13], v[12:13], v[2:3] op_sel_hi:[1,0]
	s_waitcnt lgkmcnt(15)
	v_pk_fma_f32 v[8:9], v[12:13], v[192:193], v[194:195]
	s_nop 0
	v_cvt_pk_bf16_f32 v14, v8, v9
	v_lshlrev_b32_e32 v12, 16, v131
	v_and_b32_e32 v13, 0xffff0000, v131
	v_pk_add_f32 v[12:13], v[12:13], v[0:1] op_sel:[0,1] neg_lo:[0,1] neg_hi:[0,1]
	ds_write_b16 v7, v14 offset:11424
	ds_write_b16_d16_hi v7, v14 offset:11696
	v_pk_mul_f32 v[12:13], v[12:13], v[2:3] op_sel_hi:[1,0]
	s_waitcnt lgkmcnt(15)
	v_pk_fma_f32 v[8:9], v[12:13], v[196:197], v[198:199]
	s_nop 0
	v_cvt_pk_bf16_f32 v14, v8, v9
	v_lshlrev_b32_e32 v12, 16, v130
	v_and_b32_e32 v13, 0xffff0000, v130
	v_pk_add_f32 v[12:13], v[12:13], v[0:1] op_sel:[0,1] neg_lo:[0,1] neg_hi:[0,1]
	ds_write_b16 v7, v14 offset:11968
	ds_write_b16_d16_hi v7, v14 offset:12240
	v_pk_mul_f32 v[12:13], v[12:13], v[2:3] op_sel_hi:[1,0]
	s_waitcnt lgkmcnt(15)
	v_pk_fma_f32 v[8:9], v[12:13], v[200:201], v[202:203]
	s_nop 0
	v_cvt_pk_bf16_f32 v14, v8, v9
	ds_read_b128 v[172:175], v255 offset:512
	ds_read_b128 v[176:179], v255 offset:528
	ds_read_b128 v[180:183], v255 offset:544
	ds_read_b128 v[184:187], v255 offset:560
	ds_read_b128 v[188:191], v255 offset:576
	ds_read_b128 v[192:195], v255 offset:592
	ds_read_b128 v[196:199], v255 offset:608
	ds_read_b128 v[200:203], v255 offset:624
	v_lshlrev_b32_e32 v12, 16, v137
	v_and_b32_e32 v13, 0xffff0000, v137
	v_pk_add_f32 v[12:13], v[12:13], v[0:1] op_sel:[0,1] neg_lo:[0,1] neg_hi:[0,1]
	ds_write_b16 v7, v14 offset:12512
	ds_write_b16_d16_hi v7, v14 offset:12784
	v_pk_mul_f32 v[12:13], v[12:13], v[2:3] op_sel_hi:[1,0]
	s_waitcnt lgkmcnt(15)
	v_pk_fma_f32 v[8:9], v[12:13], v[204:205], v[206:207]
	s_nop 0
	v_cvt_pk_bf16_f32 v14, v8, v9
	v_lshlrev_b32_e32 v12, 16, v136
	v_and_b32_e32 v13, 0xffff0000, v136
	v_pk_add_f32 v[12:13], v[12:13], v[0:1] op_sel:[0,1] neg_lo:[0,1] neg_hi:[0,1]
	ds_write_b16 v7, v14 offset:13056
	ds_write_b16_d16_hi v7, v14 offset:13328
	v_pk_mul_f32 v[12:13], v[12:13], v[2:3] op_sel_hi:[1,0]
	s_waitcnt lgkmcnt(15)
	v_pk_fma_f32 v[8:9], v[12:13], v[208:209], v[210:211]
	s_nop 0
	v_cvt_pk_bf16_f32 v14, v8, v9
	v_lshlrev_b32_e32 v12, 16, v135
	v_and_b32_e32 v13, 0xffff0000, v135
	v_pk_add_f32 v[12:13], v[12:13], v[0:1] op_sel:[0,1] neg_lo:[0,1] neg_hi:[0,1]
	ds_write_b16 v7, v14 offset:13600
	ds_write_b16_d16_hi v7, v14 offset:13872
	v_pk_mul_f32 v[12:13], v[12:13], v[2:3] op_sel_hi:[1,0]
	s_waitcnt lgkmcnt(15)
	v_pk_fma_f32 v[8:9], v[12:13], v[212:213], v[214:215]
	s_nop 0
	v_cvt_pk_bf16_f32 v14, v8, v9
	v_lshlrev_b32_e32 v12, 16, v133
	v_and_b32_e32 v13, 0xffff0000, v133
	v_pk_add_f32 v[12:13], v[12:13], v[0:1] op_sel:[0,1] neg_lo:[0,1] neg_hi:[0,1]
	ds_write_b16 v7, v14 offset:14144
	ds_write_b16_d16_hi v7, v14 offset:14416
	v_pk_mul_f32 v[12:13], v[12:13], v[2:3] op_sel_hi:[1,0]
	s_waitcnt lgkmcnt(15)
	v_pk_fma_f32 v[8:9], v[12:13], v[216:217], v[218:219]
	s_nop 0
	v_cvt_pk_bf16_f32 v14, v8, v9
	v_lshlrev_b32_e32 v12, 16, v142
	v_and_b32_e32 v13, 0xffff0000, v142
	v_pk_add_f32 v[12:13], v[12:13], v[0:1] op_sel:[0,1] neg_lo:[0,1] neg_hi:[0,1]
	ds_write_b16 v7, v14 offset:14688
	ds_write_b16_d16_hi v7, v14 offset:14960
	v_pk_mul_f32 v[12:13], v[12:13], v[2:3] op_sel_hi:[1,0]
	s_waitcnt lgkmcnt(15)
	v_pk_fma_f32 v[8:9], v[12:13], v[220:221], v[222:223]
	s_nop 0
	v_cvt_pk_bf16_f32 v14, v8, v9
	v_lshlrev_b32_e32 v12, 16, v140
	v_and_b32_e32 v13, 0xffff0000, v140
	v_pk_add_f32 v[12:13], v[12:13], v[0:1] op_sel:[0,1] neg_lo:[0,1] neg_hi:[0,1]
	ds_write_b16 v7, v14 offset:15232
	ds_write_b16_d16_hi v7, v14 offset:15504
	v_pk_mul_f32 v[12:13], v[12:13], v[2:3] op_sel_hi:[1,0]
	s_waitcnt lgkmcnt(15)
	v_pk_fma_f32 v[8:9], v[12:13], v[228:229], v[230:231]
	s_nop 0
	v_cvt_pk_bf16_f32 v14, v8, v9
	v_lshlrev_b32_e32 v12, 16, v139
	v_and_b32_e32 v13, 0xffff0000, v139
	v_pk_add_f32 v[12:13], v[12:13], v[0:1] op_sel:[0,1] neg_lo:[0,1] neg_hi:[0,1]
	ds_write_b16 v7, v14 offset:15776
	ds_write_b16_d16_hi v7, v14 offset:16048
	v_pk_mul_f32 v[12:13], v[12:13], v[2:3] op_sel_hi:[1,0]
	s_waitcnt lgkmcnt(15)
	v_pk_fma_f32 v[8:9], v[12:13], v[232:233], v[234:235]
	s_nop 0
	v_cvt_pk_bf16_f32 v14, v8, v9
	v_lshlrev_b32_e32 v12, 16, v138
	v_and_b32_e32 v13, 0xffff0000, v138
	v_pk_add_f32 v[12:13], v[12:13], v[0:1] op_sel:[0,1] neg_lo:[0,1] neg_hi:[0,1]
	ds_write_b16 v7, v14 offset:16320
	ds_write_b16_d16_hi v7, v14 offset:16592
	v_pk_mul_f32 v[12:13], v[12:13], v[2:3] op_sel_hi:[1,0]
	s_waitcnt lgkmcnt(15)
	v_pk_fma_f32 v[8:9], v[12:13], v[236:237], v[238:239]
	s_nop 0
	v_cvt_pk_bf16_f32 v14, v8, v9
	ds_read_b128 v[204:207], v255 offset:640
	ds_read_b128 v[208:211], v255 offset:656
	ds_read_b128 v[212:215], v255 offset:672
	ds_read_b128 v[216:219], v255 offset:688
	ds_read_b128 v[220:223], v255 offset:704
	ds_read_b128 v[228:231], v255 offset:720
	ds_read_b128 v[232:235], v255 offset:736
	ds_read_b128 v[236:239], v255 offset:752
	v_lshlrev_b32_e32 v12, 16, v146
	v_and_b32_e32 v13, 0xffff0000, v146
	v_pk_add_f32 v[12:13], v[12:13], v[0:1] op_sel:[0,1] neg_lo:[0,1] neg_hi:[0,1]
	ds_write_b16 v7, v14 offset:16864
	ds_write_b16_d16_hi v7, v14 offset:17136
	v_pk_mul_f32 v[12:13], v[12:13], v[2:3] op_sel_hi:[1,0]
	s_waitcnt lgkmcnt(15)
	v_pk_fma_f32 v[8:9], v[12:13], v[172:173], v[174:175]
	s_nop 0
	v_cvt_pk_bf16_f32 v14, v8, v9
	v_lshlrev_b32_e32 v12, 16, v144
	v_and_b32_e32 v13, 0xffff0000, v144
	v_pk_add_f32 v[12:13], v[12:13], v[0:1] op_sel:[0,1] neg_lo:[0,1] neg_hi:[0,1]
	ds_write_b16 v7, v14 offset:17408
	ds_write_b16_d16_hi v7, v14 offset:17680
	v_pk_mul_f32 v[12:13], v[12:13], v[2:3] op_sel_hi:[1,0]
	s_waitcnt lgkmcnt(15)
	v_pk_fma_f32 v[8:9], v[12:13], v[176:177], v[178:179]
	s_nop 0
	v_cvt_pk_bf16_f32 v14, v8, v9
	v_lshlrev_b32_e32 v12, 16, v143
	v_and_b32_e32 v13, 0xffff0000, v143
	v_pk_add_f32 v[12:13], v[12:13], v[0:1] op_sel:[0,1] neg_lo:[0,1] neg_hi:[0,1]
	ds_write_b16 v7, v14 offset:17952
	ds_write_b16_d16_hi v7, v14 offset:18224
	v_pk_mul_f32 v[12:13], v[12:13], v[2:3] op_sel_hi:[1,0]
	s_waitcnt lgkmcnt(15)
	v_pk_fma_f32 v[8:9], v[12:13], v[180:181], v[182:183]
	s_nop 0
	v_cvt_pk_bf16_f32 v14, v8, v9
	v_lshlrev_b32_e32 v12, 16, v141
	v_and_b32_e32 v13, 0xffff0000, v141
	v_pk_add_f32 v[12:13], v[12:13], v[0:1] op_sel:[0,1] neg_lo:[0,1] neg_hi:[0,1]
	ds_write_b16 v7, v14 offset:18496
	ds_write_b16_d16_hi v7, v14 offset:18768
	v_pk_mul_f32 v[12:13], v[12:13], v[2:3] op_sel_hi:[1,0]
	s_waitcnt lgkmcnt(15)
	v_pk_fma_f32 v[8:9], v[12:13], v[184:185], v[186:187]
	s_nop 0
	v_cvt_pk_bf16_f32 v14, v8, v9
	v_lshlrev_b32_e32 v12, 16, v149
	v_and_b32_e32 v13, 0xffff0000, v149
	v_pk_add_f32 v[12:13], v[12:13], v[0:1] op_sel:[0,1] neg_lo:[0,1] neg_hi:[0,1]
	ds_write_b16 v7, v14 offset:19040
	ds_write_b16_d16_hi v7, v14 offset:19312
	v_pk_mul_f32 v[12:13], v[12:13], v[2:3] op_sel_hi:[1,0]
	s_waitcnt lgkmcnt(15)
	v_pk_fma_f32 v[8:9], v[12:13], v[188:189], v[190:191]
	s_nop 0
	v_cvt_pk_bf16_f32 v14, v8, v9
	v_lshlrev_b32_e32 v12, 16, v148
	v_and_b32_e32 v13, 0xffff0000, v148
	v_pk_add_f32 v[12:13], v[12:13], v[0:1] op_sel:[0,1] neg_lo:[0,1] neg_hi:[0,1]
	ds_write_b16 v7, v14 offset:19584
	ds_write_b16_d16_hi v7, v14 offset:19856
	v_pk_mul_f32 v[12:13], v[12:13], v[2:3] op_sel_hi:[1,0]
	s_waitcnt lgkmcnt(15)
	v_pk_fma_f32 v[8:9], v[12:13], v[192:193], v[194:195]
	s_nop 0
	v_cvt_pk_bf16_f32 v14, v8, v9
	v_lshlrev_b32_e32 v12, 16, v147
	v_and_b32_e32 v13, 0xffff0000, v147
	v_pk_add_f32 v[12:13], v[12:13], v[0:1] op_sel:[0,1] neg_lo:[0,1] neg_hi:[0,1]
	ds_write_b16 v7, v14 offset:20128
	ds_write_b16_d16_hi v7, v14 offset:20400
	v_pk_mul_f32 v[12:13], v[12:13], v[2:3] op_sel_hi:[1,0]
	s_waitcnt lgkmcnt(15)
	v_pk_fma_f32 v[8:9], v[12:13], v[196:197], v[198:199]
	s_nop 0
	v_cvt_pk_bf16_f32 v14, v8, v9
	v_lshlrev_b32_e32 v12, 16, v145
	v_and_b32_e32 v13, 0xffff0000, v145
	v_pk_add_f32 v[12:13], v[12:13], v[0:1] op_sel:[0,1] neg_lo:[0,1] neg_hi:[0,1]
	ds_write_b16 v7, v14 offset:20672
	ds_write_b16_d16_hi v7, v14 offset:20944
	v_pk_mul_f32 v[12:13], v[12:13], v[2:3] op_sel_hi:[1,0]
	s_waitcnt lgkmcnt(15)
	v_pk_fma_f32 v[8:9], v[12:13], v[200:201], v[202:203]
	s_nop 0
	v_cvt_pk_bf16_f32 v14, v8, v9
	ds_read_b128 v[172:175], v255 offset:768
	ds_read_b128 v[176:179], v255 offset:784
	ds_read_b128 v[180:183], v255 offset:800
	ds_read_b128 v[184:187], v255 offset:816
	ds_read_b128 v[188:191], v255 offset:832
	ds_read_b128 v[192:195], v255 offset:848
	ds_read_b128 v[196:199], v255 offset:864
	ds_read_b128 v[200:203], v255 offset:880
	v_lshlrev_b32_e32 v12, 16, v154
	v_and_b32_e32 v13, 0xffff0000, v154
	v_pk_add_f32 v[12:13], v[12:13], v[0:1] op_sel:[0,1] neg_lo:[0,1] neg_hi:[0,1]
	ds_write_b16 v7, v14 offset:21216
	ds_write_b16_d16_hi v7, v14 offset:21488
	v_pk_mul_f32 v[12:13], v[12:13], v[2:3] op_sel_hi:[1,0]
	s_waitcnt lgkmcnt(15)
	v_pk_fma_f32 v[8:9], v[12:13], v[204:205], v[206:207]
	s_nop 0
	v_cvt_pk_bf16_f32 v14, v8, v9
	v_lshlrev_b32_e32 v12, 16, v152
	v_and_b32_e32 v13, 0xffff0000, v152
	v_pk_add_f32 v[12:13], v[12:13], v[0:1] op_sel:[0,1] neg_lo:[0,1] neg_hi:[0,1]
	ds_write_b16 v7, v14 offset:21760
	ds_write_b16_d16_hi v7, v14 offset:22032
	v_pk_mul_f32 v[12:13], v[12:13], v[2:3] op_sel_hi:[1,0]
	s_waitcnt lgkmcnt(15)
	v_pk_fma_f32 v[8:9], v[12:13], v[208:209], v[210:211]
	s_nop 0
	v_cvt_pk_bf16_f32 v14, v8, v9
	v_lshlrev_b32_e32 v12, 16, v151
	v_and_b32_e32 v13, 0xffff0000, v151
	v_pk_add_f32 v[12:13], v[12:13], v[0:1] op_sel:[0,1] neg_lo:[0,1] neg_hi:[0,1]
	ds_write_b16 v7, v14 offset:22304
	ds_write_b16_d16_hi v7, v14 offset:22576
	v_pk_mul_f32 v[12:13], v[12:13], v[2:3] op_sel_hi:[1,0]
	s_waitcnt lgkmcnt(15)
	v_pk_fma_f32 v[8:9], v[12:13], v[212:213], v[214:215]
	s_nop 0
	v_cvt_pk_bf16_f32 v14, v8, v9
	v_lshlrev_b32_e32 v12, 16, v150
	v_and_b32_e32 v13, 0xffff0000, v150
	v_pk_add_f32 v[12:13], v[12:13], v[0:1] op_sel:[0,1] neg_lo:[0,1] neg_hi:[0,1]
	ds_write_b16 v7, v14 offset:22848
	ds_write_b16_d16_hi v7, v14 offset:23120
	v_pk_mul_f32 v[12:13], v[12:13], v[2:3] op_sel_hi:[1,0]
	s_waitcnt lgkmcnt(15)
	v_pk_fma_f32 v[8:9], v[12:13], v[216:217], v[218:219]
	s_nop 0
	v_cvt_pk_bf16_f32 v14, v8, v9
	v_lshlrev_b32_e32 v12, 16, v157
	v_and_b32_e32 v13, 0xffff0000, v157
	v_pk_add_f32 v[12:13], v[12:13], v[0:1] op_sel:[0,1] neg_lo:[0,1] neg_hi:[0,1]
	ds_write_b16 v7, v14 offset:23392
	ds_write_b16_d16_hi v7, v14 offset:23664
	v_pk_mul_f32 v[12:13], v[12:13], v[2:3] op_sel_hi:[1,0]
	s_waitcnt lgkmcnt(15)
	v_pk_fma_f32 v[8:9], v[12:13], v[220:221], v[222:223]
	s_nop 0
	v_cvt_pk_bf16_f32 v14, v8, v9
	v_lshlrev_b32_e32 v12, 16, v156
	v_and_b32_e32 v13, 0xffff0000, v156
	v_pk_add_f32 v[12:13], v[12:13], v[0:1] op_sel:[0,1] neg_lo:[0,1] neg_hi:[0,1]
	ds_write_b16 v7, v14 offset:23936
	ds_write_b16_d16_hi v7, v14 offset:24208
	v_pk_mul_f32 v[12:13], v[12:13], v[2:3] op_sel_hi:[1,0]
	s_waitcnt lgkmcnt(15)
	v_pk_fma_f32 v[8:9], v[12:13], v[228:229], v[230:231]
	s_nop 0
	v_cvt_pk_bf16_f32 v14, v8, v9
	v_lshlrev_b32_e32 v12, 16, v155
	v_and_b32_e32 v13, 0xffff0000, v155
	v_pk_add_f32 v[12:13], v[12:13], v[0:1] op_sel:[0,1] neg_lo:[0,1] neg_hi:[0,1]
	ds_write_b16 v7, v14 offset:24480
	ds_write_b16_d16_hi v7, v14 offset:24752
	v_pk_mul_f32 v[12:13], v[12:13], v[2:3] op_sel_hi:[1,0]
	s_waitcnt lgkmcnt(15)
	v_pk_fma_f32 v[8:9], v[12:13], v[232:233], v[234:235]
	s_nop 0
	v_cvt_pk_bf16_f32 v14, v8, v9
	v_lshlrev_b32_e32 v12, 16, v153
	v_and_b32_e32 v13, 0xffff0000, v153
	v_pk_add_f32 v[12:13], v[12:13], v[0:1] op_sel:[0,1] neg_lo:[0,1] neg_hi:[0,1]
	ds_write_b16 v7, v14 offset:25024
	ds_write_b16_d16_hi v7, v14 offset:25296
	v_pk_mul_f32 v[12:13], v[12:13], v[2:3] op_sel_hi:[1,0]
	s_waitcnt lgkmcnt(15)
	v_pk_fma_f32 v[8:9], v[12:13], v[236:237], v[238:239]
	s_nop 0
	v_cvt_pk_bf16_f32 v14, v8, v9
	ds_read_b128 v[204:207], v255 offset:896
	ds_read_b128 v[208:211], v255 offset:912
	ds_read_b128 v[212:215], v255 offset:928
	ds_read_b128 v[216:219], v255 offset:944
	ds_read_b128 v[220:223], v255 offset:960
	ds_read_b128 v[228:231], v255 offset:976
	ds_read_b128 v[232:235], v255 offset:992
	ds_read_b128 v[236:239], v255 offset:1008
	v_lshlrev_b32_e32 v12, 16, v22
	v_and_b32_e32 v13, 0xffff0000, v22
	v_pk_add_f32 v[12:13], v[12:13], v[0:1] op_sel:[0,1] neg_lo:[0,1] neg_hi:[0,1]
	ds_write_b16 v7, v14 offset:25568
	ds_write_b16_d16_hi v7, v14 offset:25840
	v_pk_mul_f32 v[12:13], v[12:13], v[2:3] op_sel_hi:[1,0]
	s_waitcnt lgkmcnt(15)
	v_pk_fma_f32 v[8:9], v[12:13], v[172:173], v[174:175]
	s_nop 0
	v_cvt_pk_bf16_f32 v14, v8, v9
	v_lshlrev_b32_e32 v12, 16, v20
	v_and_b32_e32 v13, 0xffff0000, v20
	v_pk_add_f32 v[12:13], v[12:13], v[0:1] op_sel:[0,1] neg_lo:[0,1] neg_hi:[0,1]
	ds_write_b16 v7, v14 offset:26112
	ds_write_b16_d16_hi v7, v14 offset:26384
	v_pk_mul_f32 v[12:13], v[12:13], v[2:3] op_sel_hi:[1,0]
	s_waitcnt lgkmcnt(15)
	v_pk_fma_f32 v[8:9], v[12:13], v[176:177], v[178:179]
	s_nop 0
	v_cvt_pk_bf16_f32 v14, v8, v9
	v_lshlrev_b32_e32 v12, 16, v19
	v_and_b32_e32 v13, 0xffff0000, v19
	v_pk_add_f32 v[12:13], v[12:13], v[0:1] op_sel:[0,1] neg_lo:[0,1] neg_hi:[0,1]
	ds_write_b16 v7, v14 offset:26656
	ds_write_b16_d16_hi v7, v14 offset:26928
	v_pk_mul_f32 v[12:13], v[12:13], v[2:3] op_sel_hi:[1,0]
	s_waitcnt lgkmcnt(15)
	v_pk_fma_f32 v[8:9], v[12:13], v[180:181], v[182:183]
	s_nop 0
	v_cvt_pk_bf16_f32 v14, v8, v9
	v_lshlrev_b32_e32 v12, 16, v18
	v_and_b32_e32 v13, 0xffff0000, v18
	v_pk_add_f32 v[12:13], v[12:13], v[0:1] op_sel:[0,1] neg_lo:[0,1] neg_hi:[0,1]
	ds_write_b16 v7, v14 offset:27200
	ds_write_b16_d16_hi v7, v14 offset:27472
	v_pk_mul_f32 v[12:13], v[12:13], v[2:3] op_sel_hi:[1,0]
	s_waitcnt lgkmcnt(15)
	v_pk_fma_f32 v[8:9], v[12:13], v[184:185], v[186:187]
	s_nop 0
	v_cvt_pk_bf16_f32 v14, v8, v9
	v_lshlrev_b32_e32 v12, 16, v26
	v_and_b32_e32 v13, 0xffff0000, v26
	v_pk_add_f32 v[12:13], v[12:13], v[0:1] op_sel:[0,1] neg_lo:[0,1] neg_hi:[0,1]
	ds_write_b16 v7, v14 offset:27744
	ds_write_b16_d16_hi v7, v14 offset:28016
	v_pk_mul_f32 v[12:13], v[12:13], v[2:3] op_sel_hi:[1,0]
	s_waitcnt lgkmcnt(15)
	v_pk_fma_f32 v[8:9], v[12:13], v[188:189], v[190:191]
	s_nop 0
	v_cvt_pk_bf16_f32 v14, v8, v9
	v_lshlrev_b32_e32 v12, 16, v24
	v_and_b32_e32 v13, 0xffff0000, v24
	v_pk_add_f32 v[12:13], v[12:13], v[0:1] op_sel:[0,1] neg_lo:[0,1] neg_hi:[0,1]
	ds_write_b16 v7, v14 offset:28288
	ds_write_b16_d16_hi v7, v14 offset:28560
	v_pk_mul_f32 v[12:13], v[12:13], v[2:3] op_sel_hi:[1,0]
	s_waitcnt lgkmcnt(15)
	v_pk_fma_f32 v[8:9], v[12:13], v[192:193], v[194:195]
	s_nop 0
	v_cvt_pk_bf16_f32 v14, v8, v9
	v_lshlrev_b32_e32 v12, 16, v23
	v_and_b32_e32 v13, 0xffff0000, v23
	v_pk_add_f32 v[12:13], v[12:13], v[0:1] op_sel:[0,1] neg_lo:[0,1] neg_hi:[0,1]
	ds_write_b16 v7, v14 offset:28832
	ds_write_b16_d16_hi v7, v14 offset:29104
	v_pk_mul_f32 v[12:13], v[12:13], v[2:3] op_sel_hi:[1,0]
	s_waitcnt lgkmcnt(15)
	v_pk_fma_f32 v[8:9], v[12:13], v[196:197], v[198:199]
	s_nop 0
	v_cvt_pk_bf16_f32 v14, v8, v9
	v_lshlrev_b32_e32 v12, 16, v21
	v_and_b32_e32 v13, 0xffff0000, v21
	v_pk_add_f32 v[12:13], v[12:13], v[0:1] op_sel:[0,1] neg_lo:[0,1] neg_hi:[0,1]
	ds_write_b16 v7, v14 offset:29376
	ds_write_b16_d16_hi v7, v14 offset:29648
	v_pk_mul_f32 v[12:13], v[12:13], v[2:3] op_sel_hi:[1,0]
	s_waitcnt lgkmcnt(15)
	v_pk_fma_f32 v[8:9], v[12:13], v[200:201], v[202:203]
	s_nop 0
	v_cvt_pk_bf16_f32 v14, v8, v9
	v_lshlrev_b32_e32 v12, 16, v29
	v_and_b32_e32 v13, 0xffff0000, v29
	v_pk_add_f32 v[12:13], v[12:13], v[0:1] op_sel:[0,1] neg_lo:[0,1] neg_hi:[0,1]
	ds_write_b16 v7, v14 offset:29920
	ds_write_b16_d16_hi v7, v14 offset:30192
	v_pk_mul_f32 v[12:13], v[12:13], v[2:3] op_sel_hi:[1,0]
	s_waitcnt lgkmcnt(15)
	v_pk_fma_f32 v[8:9], v[12:13], v[204:205], v[206:207]
	s_nop 0
	v_cvt_pk_bf16_f32 v14, v8, v9
	v_lshlrev_b32_e32 v12, 16, v28
	v_and_b32_e32 v13, 0xffff0000, v28
	v_pk_add_f32 v[12:13], v[12:13], v[0:1] op_sel:[0,1] neg_lo:[0,1] neg_hi:[0,1]
	ds_write_b16 v7, v14 offset:30464
	ds_write_b16_d16_hi v7, v14 offset:30736
	v_pk_mul_f32 v[12:13], v[12:13], v[2:3] op_sel_hi:[1,0]
	s_waitcnt lgkmcnt(15)
	v_pk_fma_f32 v[8:9], v[12:13], v[208:209], v[210:211]
	s_nop 0
	v_cvt_pk_bf16_f32 v14, v8, v9
	v_lshlrev_b32_e32 v12, 16, v27
	v_and_b32_e32 v13, 0xffff0000, v27
	v_pk_add_f32 v[12:13], v[12:13], v[0:1] op_sel:[0,1] neg_lo:[0,1] neg_hi:[0,1]
	ds_write_b16 v7, v14 offset:31008
	ds_write_b16_d16_hi v7, v14 offset:31280
	v_pk_mul_f32 v[12:13], v[12:13], v[2:3] op_sel_hi:[1,0]
	s_waitcnt lgkmcnt(15)
	v_pk_fma_f32 v[8:9], v[12:13], v[212:213], v[214:215]
	s_nop 0
	v_cvt_pk_bf16_f32 v14, v8, v9
	v_lshlrev_b32_e32 v12, 16, v25
	v_and_b32_e32 v13, 0xffff0000, v25
	v_pk_add_f32 v[12:13], v[12:13], v[0:1] op_sel:[0,1] neg_lo:[0,1] neg_hi:[0,1]
	ds_write_b16 v7, v14 offset:31552
	ds_write_b16_d16_hi v7, v14 offset:31824
	v_pk_mul_f32 v[12:13], v[12:13], v[2:3] op_sel_hi:[1,0]
	s_waitcnt lgkmcnt(15)
	v_pk_fma_f32 v[8:9], v[12:13], v[216:217], v[218:219]
	s_nop 0
	v_cvt_pk_bf16_f32 v14, v8, v9
	v_lshlrev_b32_e32 v12, 16, v6
	v_and_b32_e32 v13, 0xffff0000, v6
	v_pk_add_f32 v[12:13], v[12:13], v[0:1] op_sel:[0,1] neg_lo:[0,1] neg_hi:[0,1]
	ds_write_b16 v7, v14 offset:32096
	ds_write_b16_d16_hi v7, v14 offset:32368
	v_pk_mul_f32 v[12:13], v[12:13], v[2:3] op_sel_hi:[1,0]
	v_lshlrev_b32_e32 v14, 16, v3
	s_waitcnt lgkmcnt(15)
	v_pk_fma_f32 v[8:9], v[12:13], v[220:221], v[222:223]
	s_nop 0
	v_cvt_pk_bf16_f32 v6, v8, v9
	v_lshlrev_b32_e32 v12, 16, v5
	v_and_b32_e32 v13, 0xffff0000, v5
	v_pk_add_f32 v[12:13], v[12:13], v[0:1] op_sel:[0,1] neg_lo:[0,1] neg_hi:[0,1]
	ds_write_b16 v7, v6 offset:32640
	ds_write_b16_d16_hi v7, v6 offset:32912
	v_pk_mul_f32 v[12:13], v[12:13], v[2:3] op_sel_hi:[1,0]
	s_waitcnt lgkmcnt(15)
	v_pk_fma_f32 v[8:9], v[12:13], v[228:229], v[230:231]
	s_nop 0
	v_cvt_pk_bf16_f32 v6, v8, v9
	v_lshlrev_b32_e32 v12, 16, v4
	v_and_b32_e32 v13, 0xffff0000, v4
	v_pk_add_f32 v[4:5], v[12:13], v[0:1] op_sel:[0,1] neg_lo:[0,1] neg_hi:[0,1]
	ds_write_b16 v7, v6 offset:33184
	ds_write_b16_d16_hi v7, v6 offset:33456
	v_pk_mul_f32 v[4:5], v[4:5], v[2:3] op_sel_hi:[1,0]
	v_pk_add_f32 v[0:1], v[14:15], v[0:1] op_sel:[0,1] neg_lo:[0,1] neg_hi:[0,1]
	s_waitcnt lgkmcnt(15)
	v_pk_fma_f32 v[4:5], v[4:5], v[232:233], v[234:235]
	s_nop 0
	v_cvt_pk_bf16_f32 v6, v4, v5
	s_bfe_u32 s8, s39, 0x10006
	v_lshl_or_b32 v124, s8, 5, v118
	v_or_b32_e32 v10, s37, v124
	v_pk_mul_f32 v[0:1], v[0:1], v[2:3] op_sel_hi:[1,0]
	v_lshlrev_b32_e32 v88, 9, v10
	v_lshl_add_u64 v[8:9], v[90:91], 0, v[88:89]
	ds_write_b16 v7, v6 offset:33728
	ds_write_b16_d16_hi v7, v6 offset:34000
	s_and_b32 s9, 64, s39
	s_cmp_eq_u32 s8, 0
	s_cselect_b64 s[12:13], -1, 0
	s_cmp_lg_u32 s9, 0
	s_cselect_b64 s[10:11], -1, 0
	s_and_b64 vcc, exec, s[12:13]
	s_waitcnt lgkmcnt(15)
	v_pk_fma_f32 v[0:1], v[0:1], v[236:237], v[238:239]
	s_nop 0
	v_cvt_pk_bf16_f32 v0, v0, v1
	ds_write_b16 v7, v0 offset:34272
	ds_write_b16_d16_hi v7, v0 offset:34544
	s_waitcnt lgkmcnt(0)
	s_barrier
	global_load_dwordx4 v[0:3], v[8:9], off offset:16
	global_load_dwordx4 v[4:7], v[8:9], off
	global_load_dwordx4 v[80:83], v[8:9], off offset:80
	global_load_dwordx4 v[84:87], v[8:9], off offset:64
	s_cbranch_vccnz .LBB0_404
	global_load_dwordx4 v[76:79], v[8:9], off offset:128
	global_load_dwordx4 v[72:75], v[8:9], off offset:144

.LBB0_1261:
	s_cmpk_gt_i32 s64, 0x7f
	s_cselect_b64 s[10:11], -1, 0
	s_and_b64 s[10:11], s[40:41], s[10:11]
	s_andn2_b64 vcc, exec, s[10:11]
	s_cbranch_vccnz .LBB0_1289
	v_add_u32_e32 v2, 0xffffffc0, v224
	v_cmp_gt_u32_e32 vcc, 64, v2
	s_and_saveexec_b64 s[90:91], vcc
	s_cbranch_execz .Lsgu_stage_1
	s_load_dwordx4 s[84:87], s[38:39], 0x40
	s_and_b32 s88, s64, 3
	s_lshl_b32 s88, s88, 9
	v_lshlrev_b32_e32 v0, 3, v2
	v_add_u32_e32 v0, s88, v0
	v_lshlrev_b32_e32 v1, 4, v2
	v_add_u32_e32 v1, 0x22800, v1
	s_waitcnt lgkmcnt(0)
	global_load_dwordx2 v[4:5], v0, s[84:85] offset:2048
	global_load_dwordx2 v[6:7], v0, s[86:87] offset:2048
	s_waitcnt vmcnt(0)
	ds_write_b128 v1, v[4:7]
	s_waitcnt lgkmcnt(0)
.Lsgu_stage_1:
	s_or_b64 exec, exec, s[90:91]
	s_and_saveexec_b64 s[10:11], s[4:5]
	s_cbranch_execz .LBB0_1272
	s_mov_b32 s16, 0x400001
	v_mov_b32_e32 v0, 0
	s_movk_i32 s17, 0xff
	s_movk_i32 s18, 0x100
	s_branch .LBB0_1265

.LBB0_1272:
	s_or_b64 exec, exec, s[10:11]
	v_mov_b32_e32 v108, v224
	s_waitcnt vmcnt(0)
	s_barrier
	s_load_dwordx8 s[12:19], s[38:39], 0x40
	v_mov_b32_e32 v255, 0x22800
	s_movk_i32 s10, 0x80
	v_readfirstlane_b32 s11, v108
	s_ashr_i32 s45, s11, 7
	s_cmp_eq_u32 s45, 2
	s_cselect_b32 s10, s10, 0x100
	s_cmp_lg_u32 s45, 1
	s_cselect_b32 s10, s10, 0
	s_cmpk_gt_u32 s11, 0x7f
	s_cselect_b32 s10, s10, 0xffffff80
	s_add_i32 s10, s10, s64
	s_mov_b32 s39, 0
	s_lshr_b32 s38, s10, 2
	v_and_b32_e32 v109, 0x7f, v108
	s_lshl_b64 s[40:41], s[38:39], 7
	v_or_b32_e32 v2, s40, v109
	s_movk_i32 s10, 0x1400
	v_mov_b64_e32 v[0:1], s[20:21]
	v_mad_u64_u32 v[0:1], s[22:23], v2, s10, v[0:1]
	s_lshl_b32 s10, s64, 7
	v_mov_b32_e32 v2, 0x1400
	s_and_b32 s43, s10, 0x180
	v_mad_u32_u24 v1, s41, v2, v1
	s_lshl_b32 s38, s43, 1
	v_lshl_add_u64 v[4:5], v[0:1], 0, s[38:39]
	s_movk_i32 s10, 0x1000
	v_add_co_u32_e32 v0, vcc, s10, v4
	s_mov_b32 s42, 0x3d372713
	s_nop 0
	v_addc_co_u32_e32 v1, vcc, 0, v5, vcc
	global_load_dwordx4 v[0:3], v[0:1], off
	s_mov_b32 s10, 0xc0135761
	s_mov_b64 s[22:23], 0x1000
	v_lshl_add_u64 v[4:5], v[4:5], 0, s[22:23]
	global_load_dwordx4 v[172:175], v[4:5], off offset:16
	global_load_dwordx4 v[176:179], v[4:5], off offset:32
	global_load_dwordx4 v[180:183], v[4:5], off offset:48
	global_load_dwordx4 v[184:187], v[4:5], off offset:64
	global_load_dwordx4 v[188:191], v[4:5], off offset:80
	global_load_dwordx4 v[192:195], v[4:5], off offset:96
	global_load_dwordx4 v[196:199], v[4:5], off offset:112
	global_load_dwordx4 v[200:203], v[4:5], off offset:128
	global_load_dwordx4 v[204:207], v[4:5], off offset:144
	global_load_dwordx4 v[208:211], v[4:5], off offset:160
	global_load_dwordx4 v[212:215], v[4:5], off offset:176
	global_load_dwordx4 v[216:219], v[4:5], off offset:192
	global_load_dwordx4 v[220:223], v[4:5], off offset:208
	global_load_dwordx4 v[228:231], v[4:5], off offset:224
	global_load_dwordx4 v[232:235], v[4:5], off offset:240
	s_lshl_b32 s22, s43, 2
	s_brev_b32 s44, 60
	s_waitcnt vmcnt(15)
	v_lshlrev_b32_e32 v6, 16, v0
	v_and_b32_e32 v7, 0xffff0000, v0
	v_lshlrev_b32_e32 v0, 16, v1
	v_and_b32_e32 v1, 0xffff0000, v1
	v_lshlrev_b32_e32 v8, 16, v2
	v_and_b32_e32 v9, 0xffff0000, v2
	v_lshlrev_b32_e32 v2, 16, v3
	v_and_b32_e32 v3, 0xffff0000, v3
	v_pk_mul_f32 v[10:11], v[6:7], v[6:7]
	v_pk_mul_f32 v[12:13], v[0:1], v[0:1]
	v_pk_mul_f32 v[14:15], v[8:9], v[8:9]
	v_pk_mul_f32 v[16:17], v[2:3], v[2:3]
	v_pk_fma_f32 v[10:11], v[10:11], s[42:43], 1.0 op_sel_hi:[1,0,0]
	v_pk_fma_f32 v[12:13], v[12:13], s[42:43], 1.0 op_sel_hi:[1,0,0]
	v_pk_fma_f32 v[14:15], v[14:15], s[42:43], 1.0 op_sel_hi:[1,0,0]
	v_pk_fma_f32 v[16:17], v[16:17], s[42:43], 1.0 op_sel_hi:[1,0,0]
	v_pk_mul_f32 v[10:11], v[10:11], v[6:7]
	v_pk_mul_f32 v[12:13], v[12:13], v[0:1]
	v_pk_mul_f32 v[14:15], v[14:15], v[8:9]
	v_pk_mul_f32 v[16:17], v[16:17], v[2:3]
	v_pk_mul_f32 v[10:11], v[10:11], s[10:11] op_sel_hi:[1,0]
	v_pk_mul_f32 v[12:13], v[12:13], s[10:11] op_sel_hi:[1,0]
	v_pk_mul_f32 v[14:15], v[14:15], s[10:11] op_sel_hi:[1,0]
	v_pk_mul_f32 v[16:17], v[16:17], s[10:11] op_sel_hi:[1,0]
	v_exp_f32_e32 v10, v10
	v_exp_f32_e32 v11, v11
	v_exp_f32_e32 v12, v12
	v_exp_f32_e32 v13, v13
	v_exp_f32_e32 v14, v14
	v_exp_f32_e32 v15, v15
	v_exp_f32_e32 v16, v16
	v_exp_f32_e32 v17, v17
	v_pk_add_f32 v[10:11], v[10:11], 1.0 op_sel_hi:[1,0]
	v_pk_add_f32 v[12:13], v[12:13], 1.0 op_sel_hi:[1,0]
	v_pk_add_f32 v[18:19], v[14:15], 1.0 op_sel_hi:[1,0]
	v_pk_add_f32 v[16:17], v[16:17], 1.0 op_sel_hi:[1,0]
	v_rcp_f32_e32 v14, v10
	v_rcp_f32_e32 v15, v11
	v_rcp_f32_e32 v10, v12
	v_rcp_f32_e32 v11, v13
	v_rcp_f32_e32 v12, v18
	v_rcp_f32_e32 v13, v19
	v_rcp_f32_e32 v18, v16
	v_rcp_f32_e32 v19, v17
	v_pk_mul_f32 v[16:17], v[14:15], v[6:7]
	v_pk_mul_f32 v[10:11], v[10:11], v[0:1]
	v_pk_mul_f32 v[8:9], v[12:13], v[8:9]
	v_pk_mul_f32 v[12:13], v[18:19], v[2:3]
	v_cvt_pk_bf16_f32 v114, v16, v17
	v_cvt_pk_bf16_f32 v112, v10, v11
	v_cvt_pk_bf16_f32 v111, v8, v9
	v_pk_fma_f32 v[6:7], v[14:15], v[6:7], v[16:17] op_sel_hi:[1,1,0]
	v_cvt_pk_bf16_f32 v110, v12, v13
	v_pk_mul_f32 v[14:15], v[16:17], v[16:17]
	v_pk_mul_f32 v[16:17], v[10:11], v[10:11]
	v_mov_b32_e32 v165, v10
	v_mov_b32_e32 v164, v14
	v_mov_b32_e32 v10, v15
	v_mov_b32_e32 v6, v16
	v_mov_b32_e32 v167, v8
	v_pk_add_f32 v[10:11], v[164:165], v[10:11]
	v_pk_mul_f32 v[162:163], v[12:13], v[12:13]
	v_mov_b32_e32 v169, v12
	v_mov_b32_e32 v168, v162
	v_mov_b32_e32 v12, v163
	v_pk_add_f32 v[12:13], v[168:169], v[12:13]
	s_waitcnt vmcnt(14)
	v_mov_b32_e32 v0, v172
	v_mov_b32_e32 v1, v173
	v_mov_b32_e32 v2, v174
	v_mov_b32_e32 v3, v175
	v_lshlrev_b32_e32 v18, 16, v0
	v_and_b32_e32 v19, 0xffff0000, v0
	v_lshlrev_b32_e32 v0, 16, v1
	v_and_b32_e32 v1, 0xffff0000, v1
	v_lshlrev_b32_e32 v24, 16, v2
	v_and_b32_e32 v25, 0xffff0000, v2
	v_lshlrev_b32_e32 v2, 16, v3
	v_and_b32_e32 v3, 0xffff0000, v3
	v_pk_mul_f32 v[20:21], v[18:19], v[18:19]
	v_pk_mul_f32 v[22:23], v[0:1], v[0:1]
	v_pk_mul_f32 v[26:27], v[24:25], v[24:25]
	v_pk_mul_f32 v[28:29], v[2:3], v[2:3]
	v_pk_fma_f32 v[20:21], v[20:21], s[42:43], 1.0 op_sel_hi:[1,0,0]
	v_pk_fma_f32 v[22:23], v[22:23], s[42:43], 1.0 op_sel_hi:[1,0,0]
	v_pk_fma_f32 v[26:27], v[26:27], s[42:43], 1.0 op_sel_hi:[1,0,0]
	v_pk_fma_f32 v[28:29], v[28:29], s[42:43], 1.0 op_sel_hi:[1,0,0]
	v_pk_mul_f32 v[20:21], v[20:21], v[18:19]
	v_pk_mul_f32 v[22:23], v[22:23], v[0:1]
	v_pk_mul_f32 v[26:27], v[26:27], v[24:25]
	v_pk_mul_f32 v[28:29], v[28:29], v[2:3]
	v_pk_mul_f32 v[20:21], v[20:21], s[10:11] op_sel_hi:[1,0]
	v_pk_mul_f32 v[22:23], v[22:23], s[10:11] op_sel_hi:[1,0]
	v_pk_mul_f32 v[26:27], v[26:27], s[10:11] op_sel_hi:[1,0]
	v_pk_mul_f32 v[28:29], v[28:29], s[10:11] op_sel_hi:[1,0]
	v_exp_f32_e32 v20, v20
	v_exp_f32_e32 v21, v21
	v_exp_f32_e32 v22, v22
	v_exp_f32_e32 v23, v23
	v_exp_f32_e32 v26, v26
	v_exp_f32_e32 v27, v27
	v_exp_f32_e32 v28, v28
	v_exp_f32_e32 v29, v29
	v_pk_add_f32 v[20:21], v[20:21], 1.0 op_sel_hi:[1,0]
	v_pk_add_f32 v[22:23], v[22:23], 1.0 op_sel_hi:[1,0]
	v_pk_add_f32 v[26:27], v[26:27], 1.0 op_sel_hi:[1,0]
	v_pk_add_f32 v[28:29], v[28:29], 1.0 op_sel_hi:[1,0]
	v_rcp_f32_e32 v20, v20
	v_rcp_f32_e32 v21, v21
	v_rcp_f32_e32 v30, v22
	v_rcp_f32_e32 v31, v23
	v_rcp_f32_e32 v26, v26
	v_rcp_f32_e32 v27, v27
	v_rcp_f32_e32 v28, v28
	v_rcp_f32_e32 v29, v29
	v_pk_mul_f32 v[22:23], v[20:21], v[18:19]
	v_pk_mul_f32 v[20:21], v[30:31], v[0:1]
	v_pk_mul_f32 v[18:19], v[26:27], v[24:25]
	v_pk_mul_f32 v[24:25], v[28:29], v[2:3]
	v_cvt_pk_bf16_f32 v117, v22, v23
	v_cvt_pk_bf16_f32 v116, v20, v21
	v_cvt_pk_bf16_f32 v115, v18, v19
	v_mov_b32_e32 v163, v18
	v_cvt_pk_bf16_f32 v113, v24, v25
	v_pk_mul_f32 v[14:15], v[24:25], v[24:25]
	v_mov_b32_e32 v165, v24
	v_mov_b32_e32 v164, v14
	v_mov_b32_e32 v24, v15
	v_pk_add_f32 v[14:15], v[164:165], v[24:25]
	s_waitcnt vmcnt(13)
	v_mov_b32_e32 v0, v176
	v_mov_b32_e32 v1, v177
	v_mov_b32_e32 v2, v178
	v_mov_b32_e32 v3, v179
	v_lshlrev_b32_e32 v26, 16, v0
	v_and_b32_e32 v27, 0xffff0000, v0
	v_lshlrev_b32_e32 v0, 16, v1
	v_and_b32_e32 v1, 0xffff0000, v1
	v_lshlrev_b32_e32 v32, 16, v2
	v_and_b32_e32 v33, 0xffff0000, v2
	v_lshlrev_b32_e32 v2, 16, v3
	v_and_b32_e32 v3, 0xffff0000, v3
	v_pk_mul_f32 v[28:29], v[26:27], v[26:27]
	v_pk_mul_f32 v[30:31], v[0:1], v[0:1]
	v_pk_mul_f32 v[34:35], v[32:33], v[32:33]
	v_pk_mul_f32 v[36:37], v[2:3], v[2:3]
	v_pk_fma_f32 v[28:29], v[28:29], s[42:43], 1.0 op_sel_hi:[1,0,0]
	v_pk_fma_f32 v[30:31], v[30:31], s[42:43], 1.0 op_sel_hi:[1,0,0]
	v_pk_fma_f32 v[34:35], v[34:35], s[42:43], 1.0 op_sel_hi:[1,0,0]
	v_pk_fma_f32 v[36:37], v[36:37], s[42:43], 1.0 op_sel_hi:[1,0,0]
	v_pk_mul_f32 v[28:29], v[28:29], v[26:27]
	v_pk_mul_f32 v[30:31], v[30:31], v[0:1]
	v_pk_mul_f32 v[34:35], v[34:35], v[32:33]
	v_pk_mul_f32 v[36:37], v[36:37], v[2:3]
	v_pk_mul_f32 v[28:29], v[28:29], s[10:11] op_sel_hi:[1,0]
	v_pk_mul_f32 v[30:31], v[30:31], s[10:11] op_sel_hi:[1,0]
	v_pk_mul_f32 v[34:35], v[34:35], s[10:11] op_sel_hi:[1,0]
	v_pk_mul_f32 v[36:37], v[36:37], s[10:11] op_sel_hi:[1,0]
	v_exp_f32_e32 v28, v28
	v_exp_f32_e32 v29, v29
	v_exp_f32_e32 v30, v30
	v_exp_f32_e32 v31, v31
	v_exp_f32_e32 v34, v34
	v_exp_f32_e32 v35, v35
	v_exp_f32_e32 v36, v36
	v_exp_f32_e32 v37, v37
	v_pk_add_f32 v[28:29], v[28:29], 1.0 op_sel_hi:[1,0]
	v_pk_add_f32 v[30:31], v[30:31], 1.0 op_sel_hi:[1,0]
	v_pk_add_f32 v[34:35], v[34:35], 1.0 op_sel_hi:[1,0]
	v_pk_add_f32 v[36:37], v[36:37], 1.0 op_sel_hi:[1,0]
	v_rcp_f32_e32 v28, v28
	v_rcp_f32_e32 v29, v29
	v_rcp_f32_e32 v38, v30
	v_rcp_f32_e32 v39, v31
	v_rcp_f32_e32 v34, v34
	v_rcp_f32_e32 v35, v35
	v_rcp_f32_e32 v36, v36
	v_rcp_f32_e32 v37, v37
	v_pk_mul_f32 v[30:31], v[28:29], v[26:27]
	v_pk_mul_f32 v[28:29], v[38:39], v[0:1]
	v_pk_mul_f32 v[26:27], v[34:35], v[32:33]
	v_pk_mul_f32 v[32:33], v[36:37], v[2:3]
	v_cvt_pk_bf16_f32 v122, v30, v31
	v_cvt_pk_bf16_f32 v120, v28, v29
	v_cvt_pk_bf16_f32 v119, v26, v27
	s_nop 0
	v_cvt_pk_bf16_f32 v118, v32, v33
	s_waitcnt vmcnt(12)
	v_mov_b32_e32 v0, v180
	v_mov_b32_e32 v1, v181
	v_mov_b32_e32 v2, v182
	v_mov_b32_e32 v3, v183
	v_lshlrev_b32_e32 v34, 16, v0
	v_and_b32_e32 v35, 0xffff0000, v0
	v_lshlrev_b32_e32 v0, 16, v1
	v_and_b32_e32 v1, 0xffff0000, v1
	v_lshlrev_b32_e32 v40, 16, v2
	v_and_b32_e32 v41, 0xffff0000, v2
	v_lshlrev_b32_e32 v2, 16, v3
	v_and_b32_e32 v3, 0xffff0000, v3
	v_pk_mul_f32 v[36:37], v[34:35], v[34:35]
	v_pk_mul_f32 v[38:39], v[0:1], v[0:1]
	v_pk_mul_f32 v[42:43], v[40:41], v[40:41]
	v_pk_mul_f32 v[44:45], v[2:3], v[2:3]
	v_pk_fma_f32 v[36:37], v[36:37], s[42:43], 1.0 op_sel_hi:[1,0,0]
	v_pk_fma_f32 v[38:39], v[38:39], s[42:43], 1.0 op_sel_hi:[1,0,0]
	v_pk_fma_f32 v[42:43], v[42:43], s[42:43], 1.0 op_sel_hi:[1,0,0]
	v_pk_fma_f32 v[44:45], v[44:45], s[42:43], 1.0 op_sel_hi:[1,0,0]
	v_pk_mul_f32 v[36:37], v[36:37], v[34:35]
	v_pk_mul_f32 v[38:39], v[38:39], v[0:1]
	v_pk_mul_f32 v[42:43], v[42:43], v[40:41]
	v_pk_mul_f32 v[44:45], v[44:45], v[2:3]
	v_pk_mul_f32 v[36:37], v[36:37], s[10:11] op_sel_hi:[1,0]
	v_pk_mul_f32 v[38:39], v[38:39], s[10:11] op_sel_hi:[1,0]
	v_pk_mul_f32 v[42:43], v[42:43], s[10:11] op_sel_hi:[1,0]
	v_pk_mul_f32 v[44:45], v[44:45], s[10:11] op_sel_hi:[1,0]
	v_exp_f32_e32 v36, v36
	v_exp_f32_e32 v37, v37
	v_exp_f32_e32 v38, v38
	v_exp_f32_e32 v39, v39
	v_exp_f32_e32 v42, v42
	v_exp_f32_e32 v43, v43
	v_exp_f32_e32 v44, v44
	v_exp_f32_e32 v45, v45
	v_pk_add_f32 v[36:37], v[36:37], 1.0 op_sel_hi:[1,0]
	v_pk_add_f32 v[38:39], v[38:39], 1.0 op_sel_hi:[1,0]
	v_pk_add_f32 v[42:43], v[42:43], 1.0 op_sel_hi:[1,0]
	v_pk_add_f32 v[44:45], v[44:45], 1.0 op_sel_hi:[1,0]
	v_rcp_f32_e32 v36, v36
	v_rcp_f32_e32 v37, v37
	v_rcp_f32_e32 v46, v38
	v_rcp_f32_e32 v47, v39
	v_rcp_f32_e32 v42, v42
	v_rcp_f32_e32 v43, v43
	v_rcp_f32_e32 v44, v44
	v_rcp_f32_e32 v45, v45
	v_pk_mul_f32 v[38:39], v[36:37], v[34:35]
	v_pk_mul_f32 v[36:37], v[46:47], v[0:1]
	v_pk_mul_f32 v[34:35], v[42:43], v[40:41]
	v_pk_mul_f32 v[40:41], v[44:45], v[2:3]
	v_cvt_pk_bf16_f32 v126, v38, v39
	v_cvt_pk_bf16_f32 v124, v36, v37
	v_cvt_pk_bf16_f32 v123, v34, v35
	v_pk_mul_f32 v[24:25], v[36:37], v[36:37]
	v_cvt_pk_bf16_f32 v121, v40, v41
	s_waitcnt vmcnt(11)
	v_mov_b32_e32 v0, v184
	v_mov_b32_e32 v1, v185
	v_mov_b32_e32 v2, v186
	v_mov_b32_e32 v3, v187
	v_lshlrev_b32_e32 v42, 16, v0
	v_and_b32_e32 v43, 0xffff0000, v0
	v_lshlrev_b32_e32 v0, 16, v1
	v_and_b32_e32 v1, 0xffff0000, v1
	v_lshlrev_b32_e32 v48, 16, v2
	v_and_b32_e32 v49, 0xffff0000, v2
	v_lshlrev_b32_e32 v2, 16, v3
	v_and_b32_e32 v3, 0xffff0000, v3
	v_pk_mul_f32 v[44:45], v[42:43], v[42:43]
	v_pk_mul_f32 v[46:47], v[0:1], v[0:1]
	v_pk_mul_f32 v[50:51], v[48:49], v[48:49]
	v_pk_mul_f32 v[52:53], v[2:3], v[2:3]
	v_pk_fma_f32 v[44:45], v[44:45], s[42:43], 1.0 op_sel_hi:[1,0,0]
	v_pk_fma_f32 v[46:47], v[46:47], s[42:43], 1.0 op_sel_hi:[1,0,0]
	v_pk_fma_f32 v[50:51], v[50:51], s[42:43], 1.0 op_sel_hi:[1,0,0]
	v_pk_fma_f32 v[52:53], v[52:53], s[42:43], 1.0 op_sel_hi:[1,0,0]
	v_pk_mul_f32 v[44:45], v[44:45], v[42:43]
	v_pk_mul_f32 v[46:47], v[46:47], v[0:1]
	v_pk_mul_f32 v[50:51], v[50:51], v[48:49]
	v_pk_mul_f32 v[52:53], v[52:53], v[2:3]
	v_pk_mul_f32 v[44:45], v[44:45], s[10:11] op_sel_hi:[1,0]
	v_pk_mul_f32 v[46:47], v[46:47], s[10:11] op_sel_hi:[1,0]
	v_pk_mul_f32 v[50:51], v[50:51], s[10:11] op_sel_hi:[1,0]
	v_pk_mul_f32 v[52:53], v[52:53], s[10:11] op_sel_hi:[1,0]
	v_exp_f32_e32 v44, v44
	v_exp_f32_e32 v45, v45
	v_exp_f32_e32 v46, v46
	v_exp_f32_e32 v47, v47
	v_exp_f32_e32 v50, v50
	v_exp_f32_e32 v51, v51
	v_exp_f32_e32 v52, v52
	v_exp_f32_e32 v53, v53
	v_pk_add_f32 v[44:45], v[44:45], 1.0 op_sel_hi:[1,0]
	v_pk_add_f32 v[46:47], v[46:47], 1.0 op_sel_hi:[1,0]
	v_pk_add_f32 v[50:51], v[50:51], 1.0 op_sel_hi:[1,0]
	v_pk_add_f32 v[52:53], v[52:53], 1.0 op_sel_hi:[1,0]
	v_rcp_f32_e32 v44, v44
	v_rcp_f32_e32 v45, v45
	v_rcp_f32_e32 v54, v46
	v_rcp_f32_e32 v55, v47
	v_rcp_f32_e32 v50, v50
	v_rcp_f32_e32 v51, v51
	v_rcp_f32_e32 v52, v52
	v_rcp_f32_e32 v53, v53
	v_pk_mul_f32 v[46:47], v[44:45], v[42:43]
	v_pk_mul_f32 v[44:45], v[54:55], v[0:1]
	v_pk_mul_f32 v[42:43], v[50:51], v[48:49]
	v_pk_mul_f32 v[48:49], v[52:53], v[2:3]
	v_cvt_pk_bf16_f32 v129, v46, v47
	v_cvt_pk_bf16_f32 v128, v44, v45
	v_cvt_pk_bf16_f32 v127, v42, v43
	s_nop 0
	v_cvt_pk_bf16_f32 v125, v48, v49
	s_waitcnt vmcnt(10)
	v_mov_b32_e32 v0, v188
	v_mov_b32_e32 v1, v189
	v_mov_b32_e32 v2, v190
	v_mov_b32_e32 v3, v191
	v_lshlrev_b32_e32 v50, 16, v0
	v_and_b32_e32 v51, 0xffff0000, v0
	v_lshlrev_b32_e32 v0, 16, v1
	v_and_b32_e32 v1, 0xffff0000, v1
	v_lshlrev_b32_e32 v56, 16, v2
	v_and_b32_e32 v57, 0xffff0000, v2
	v_lshlrev_b32_e32 v2, 16, v3
	v_and_b32_e32 v3, 0xffff0000, v3
	v_pk_mul_f32 v[52:53], v[50:51], v[50:51]
	v_pk_mul_f32 v[54:55], v[0:1], v[0:1]
	v_pk_mul_f32 v[58:59], v[56:57], v[56:57]
	v_pk_mul_f32 v[60:61], v[2:3], v[2:3]
	v_pk_fma_f32 v[52:53], v[52:53], s[42:43], 1.0 op_sel_hi:[1,0,0]
	v_pk_fma_f32 v[54:55], v[54:55], s[42:43], 1.0 op_sel_hi:[1,0,0]
	v_pk_fma_f32 v[58:59], v[58:59], s[42:43], 1.0 op_sel_hi:[1,0,0]
	v_pk_fma_f32 v[60:61], v[60:61], s[42:43], 1.0 op_sel_hi:[1,0,0]
	v_pk_mul_f32 v[52:53], v[52:53], v[50:51]
	v_pk_mul_f32 v[54:55], v[54:55], v[0:1]
	v_pk_mul_f32 v[58:59], v[58:59], v[56:57]
	v_pk_mul_f32 v[60:61], v[60:61], v[2:3]
	v_pk_mul_f32 v[52:53], v[52:53], s[10:11] op_sel_hi:[1,0]
	v_pk_mul_f32 v[54:55], v[54:55], s[10:11] op_sel_hi:[1,0]
	v_pk_mul_f32 v[58:59], v[58:59], s[10:11] op_sel_hi:[1,0]
	v_pk_mul_f32 v[60:61], v[60:61], s[10:11] op_sel_hi:[1,0]
	v_exp_f32_e32 v52, v52
	v_exp_f32_e32 v53, v53
	v_exp_f32_e32 v54, v54
	v_exp_f32_e32 v55, v55
	v_exp_f32_e32 v58, v58
	v_exp_f32_e32 v59, v59
	v_exp_f32_e32 v60, v60
	v_exp_f32_e32 v61, v61
	v_pk_add_f32 v[52:53], v[52:53], 1.0 op_sel_hi:[1,0]
	v_pk_add_f32 v[54:55], v[54:55], 1.0 op_sel_hi:[1,0]
	v_pk_add_f32 v[58:59], v[58:59], 1.0 op_sel_hi:[1,0]
	v_pk_add_f32 v[60:61], v[60:61], 1.0 op_sel_hi:[1,0]
	v_rcp_f32_e32 v52, v52
	v_rcp_f32_e32 v53, v53
	v_rcp_f32_e32 v62, v54
	v_rcp_f32_e32 v63, v55
	v_rcp_f32_e32 v58, v58
	v_rcp_f32_e32 v59, v59
	v_rcp_f32_e32 v60, v60
	v_rcp_f32_e32 v61, v61
	v_pk_mul_f32 v[54:55], v[52:53], v[50:51]
	v_pk_mul_f32 v[52:53], v[62:63], v[0:1]
	v_pk_mul_f32 v[50:51], v[58:59], v[56:57]
	v_pk_mul_f32 v[56:57], v[60:61], v[2:3]
	v_cvt_pk_bf16_f32 v134, v54, v55
	v_cvt_pk_bf16_f32 v132, v52, v53
	v_cvt_pk_bf16_f32 v131, v50, v51
	s_nop 0
	v_cvt_pk_bf16_f32 v130, v56, v57
	s_waitcnt vmcnt(9)
	v_mov_b32_e32 v0, v192
	v_mov_b32_e32 v1, v193
	v_mov_b32_e32 v2, v194
	v_mov_b32_e32 v3, v195
	v_lshlrev_b32_e32 v58, 16, v0
	v_and_b32_e32 v59, 0xffff0000, v0
	v_lshlrev_b32_e32 v0, 16, v1
	v_and_b32_e32 v1, 0xffff0000, v1
	v_lshlrev_b32_e32 v64, 16, v2
	v_and_b32_e32 v65, 0xffff0000, v2
	v_lshlrev_b32_e32 v2, 16, v3
	v_and_b32_e32 v3, 0xffff0000, v3
	v_pk_mul_f32 v[60:61], v[58:59], v[58:59]
	v_pk_mul_f32 v[62:63], v[0:1], v[0:1]
	v_pk_mul_f32 v[66:67], v[64:65], v[64:65]
	v_pk_mul_f32 v[68:69], v[2:3], v[2:3]
	v_pk_fma_f32 v[60:61], v[60:61], s[42:43], 1.0 op_sel_hi:[1,0,0]
	v_pk_fma_f32 v[62:63], v[62:63], s[42:43], 1.0 op_sel_hi:[1,0,0]
	v_pk_fma_f32 v[66:67], v[66:67], s[42:43], 1.0 op_sel_hi:[1,0,0]
	v_pk_fma_f32 v[68:69], v[68:69], s[42:43], 1.0 op_sel_hi:[1,0,0]
	v_pk_mul_f32 v[60:61], v[60:61], v[58:59]
	v_pk_mul_f32 v[62:63], v[62:63], v[0:1]
	v_pk_mul_f32 v[66:67], v[66:67], v[64:65]
	v_pk_mul_f32 v[68:69], v[68:69], v[2:3]
	v_pk_mul_f32 v[60:61], v[60:61], s[10:11] op_sel_hi:[1,0]
	v_pk_mul_f32 v[62:63], v[62:63], s[10:11] op_sel_hi:[1,0]
	v_pk_mul_f32 v[66:67], v[66:67], s[10:11] op_sel_hi:[1,0]
	v_pk_mul_f32 v[68:69], v[68:69], s[10:11] op_sel_hi:[1,0]
	v_exp_f32_e32 v60, v60
	v_exp_f32_e32 v61, v61
	v_exp_f32_e32 v62, v62
	v_exp_f32_e32 v63, v63
	v_exp_f32_e32 v66, v66
	v_exp_f32_e32 v67, v67
	v_exp_f32_e32 v68, v68
	v_exp_f32_e32 v69, v69
	v_pk_add_f32 v[60:61], v[60:61], 1.0 op_sel_hi:[1,0]
	v_pk_add_f32 v[62:63], v[62:63], 1.0 op_sel_hi:[1,0]
	v_pk_add_f32 v[66:67], v[66:67], 1.0 op_sel_hi:[1,0]
	v_pk_add_f32 v[68:69], v[68:69], 1.0 op_sel_hi:[1,0]
	v_rcp_f32_e32 v60, v60
	v_rcp_f32_e32 v61, v61
	v_rcp_f32_e32 v70, v62
	v_rcp_f32_e32 v71, v63
	v_rcp_f32_e32 v66, v66
	v_rcp_f32_e32 v67, v67
	v_rcp_f32_e32 v68, v68
	v_rcp_f32_e32 v69, v69
	v_pk_mul_f32 v[62:63], v[60:61], v[58:59]
	v_pk_mul_f32 v[60:61], v[70:71], v[0:1]
	v_pk_mul_f32 v[58:59], v[66:67], v[64:65]
	v_pk_mul_f32 v[64:65], v[68:69], v[2:3]
	v_cvt_pk_bf16_f32 v137, v62, v63
	v_cvt_pk_bf16_f32 v136, v60, v61
	v_cvt_pk_bf16_f32 v135, v58, v59
	s_nop 0
	v_cvt_pk_bf16_f32 v133, v64, v65
	s_waitcnt vmcnt(8)
	v_mov_b32_e32 v0, v196
	v_mov_b32_e32 v1, v197
	v_mov_b32_e32 v2, v198
	v_mov_b32_e32 v3, v199
	v_lshlrev_b32_e32 v66, 16, v0
	v_and_b32_e32 v67, 0xffff0000, v0
	v_lshlrev_b32_e32 v0, 16, v1
	v_and_b32_e32 v1, 0xffff0000, v1
	v_lshlrev_b32_e32 v72, 16, v2
	v_and_b32_e32 v73, 0xffff0000, v2
	v_lshlrev_b32_e32 v2, 16, v3
	v_and_b32_e32 v3, 0xffff0000, v3
	v_pk_mul_f32 v[68:69], v[66:67], v[66:67]
	v_pk_mul_f32 v[70:71], v[0:1], v[0:1]
	v_pk_mul_f32 v[74:75], v[72:73], v[72:73]
	v_pk_mul_f32 v[76:77], v[2:3], v[2:3]
	v_pk_fma_f32 v[68:69], v[68:69], s[42:43], 1.0 op_sel_hi:[1,0,0]
	v_pk_fma_f32 v[70:71], v[70:71], s[42:43], 1.0 op_sel_hi:[1,0,0]
	v_pk_fma_f32 v[74:75], v[74:75], s[42:43], 1.0 op_sel_hi:[1,0,0]
	v_pk_fma_f32 v[76:77], v[76:77], s[42:43], 1.0 op_sel_hi:[1,0,0]
	v_pk_mul_f32 v[68:69], v[68:69], v[66:67]
	v_pk_mul_f32 v[70:71], v[70:71], v[0:1]
	v_pk_mul_f32 v[74:75], v[74:75], v[72:73]
	v_pk_mul_f32 v[76:77], v[76:77], v[2:3]
	v_pk_mul_f32 v[68:69], v[68:69], s[10:11] op_sel_hi:[1,0]
	v_pk_mul_f32 v[70:71], v[70:71], s[10:11] op_sel_hi:[1,0]
	v_pk_mul_f32 v[74:75], v[74:75], s[10:11] op_sel_hi:[1,0]
	v_pk_mul_f32 v[76:77], v[76:77], s[10:11] op_sel_hi:[1,0]
	v_exp_f32_e32 v68, v68
	v_exp_f32_e32 v69, v69
	v_exp_f32_e32 v70, v70
	v_exp_f32_e32 v71, v71
	v_exp_f32_e32 v74, v74
	v_exp_f32_e32 v75, v75
	v_exp_f32_e32 v76, v76
	v_exp_f32_e32 v77, v77
	v_pk_add_f32 v[68:69], v[68:69], 1.0 op_sel_hi:[1,0]
	v_pk_add_f32 v[70:71], v[70:71], 1.0 op_sel_hi:[1,0]
	v_pk_add_f32 v[74:75], v[74:75], 1.0 op_sel_hi:[1,0]
	v_pk_add_f32 v[76:77], v[76:77], 1.0 op_sel_hi:[1,0]
	v_rcp_f32_e32 v68, v68
	v_rcp_f32_e32 v69, v69
	v_rcp_f32_e32 v78, v70
	v_rcp_f32_e32 v79, v71
	v_rcp_f32_e32 v74, v74
	v_rcp_f32_e32 v75, v75
	v_rcp_f32_e32 v76, v76
	v_rcp_f32_e32 v77, v77
	v_pk_mul_f32 v[70:71], v[68:69], v[66:67]
	v_pk_mul_f32 v[68:69], v[78:79], v[0:1]
	v_pk_mul_f32 v[66:67], v[74:75], v[72:73]
	v_pk_mul_f32 v[72:73], v[76:77], v[2:3]
	v_cvt_pk_bf16_f32 v142, v70, v71
	v_cvt_pk_bf16_f32 v140, v68, v69
	v_cvt_pk_bf16_f32 v139, v66, v67
	s_nop 0
	v_cvt_pk_bf16_f32 v138, v72, v73
	s_waitcnt vmcnt(7)
	v_mov_b32_e32 v0, v200
	v_mov_b32_e32 v1, v201
	v_mov_b32_e32 v2, v202
	v_mov_b32_e32 v3, v203
	v_lshlrev_b32_e32 v74, 16, v0
	v_and_b32_e32 v75, 0xffff0000, v0
	v_lshlrev_b32_e32 v0, 16, v1
	v_and_b32_e32 v1, 0xffff0000, v1
	v_lshlrev_b32_e32 v80, 16, v2
	v_and_b32_e32 v81, 0xffff0000, v2
	v_lshlrev_b32_e32 v2, 16, v3
	v_and_b32_e32 v3, 0xffff0000, v3
	v_pk_mul_f32 v[76:77], v[74:75], v[74:75]
	v_pk_mul_f32 v[78:79], v[0:1], v[0:1]
	v_pk_mul_f32 v[82:83], v[80:81], v[80:81]
	v_pk_mul_f32 v[84:85], v[2:3], v[2:3]
	v_pk_fma_f32 v[76:77], v[76:77], s[42:43], 1.0 op_sel_hi:[1,0,0]
	v_pk_fma_f32 v[78:79], v[78:79], s[42:43], 1.0 op_sel_hi:[1,0,0]
	v_pk_fma_f32 v[82:83], v[82:83], s[42:43], 1.0 op_sel_hi:[1,0,0]
	v_pk_fma_f32 v[84:85], v[84:85], s[42:43], 1.0 op_sel_hi:[1,0,0]
	v_pk_mul_f32 v[76:77], v[76:77], v[74:75]
	v_pk_mul_f32 v[78:79], v[78:79], v[0:1]
	v_pk_mul_f32 v[82:83], v[82:83], v[80:81]
	v_pk_mul_f32 v[84:85], v[84:85], v[2:3]
	v_pk_mul_f32 v[76:77], v[76:77], s[10:11] op_sel_hi:[1,0]
	v_pk_mul_f32 v[78:79], v[78:79], s[10:11] op_sel_hi:[1,0]
	v_pk_mul_f32 v[82:83], v[82:83], s[10:11] op_sel_hi:[1,0]
	v_pk_mul_f32 v[84:85], v[84:85], s[10:11] op_sel_hi:[1,0]
	v_exp_f32_e32 v76, v76
	v_exp_f32_e32 v77, v77
	v_exp_f32_e32 v78, v78
	v_exp_f32_e32 v79, v79
	v_exp_f32_e32 v82, v82
	v_exp_f32_e32 v83, v83
	v_exp_f32_e32 v84, v84
	v_exp_f32_e32 v85, v85
	v_pk_add_f32 v[76:77], v[76:77], 1.0 op_sel_hi:[1,0]
	v_pk_add_f32 v[78:79], v[78:79], 1.0 op_sel_hi:[1,0]
	v_pk_add_f32 v[82:83], v[82:83], 1.0 op_sel_hi:[1,0]
	v_pk_add_f32 v[84:85], v[84:85], 1.0 op_sel_hi:[1,0]
	v_rcp_f32_e32 v76, v76
	v_rcp_f32_e32 v77, v77
	v_rcp_f32_e32 v86, v78
	v_rcp_f32_e32 v87, v79
	v_rcp_f32_e32 v82, v82
	v_rcp_f32_e32 v83, v83
	v_rcp_f32_e32 v84, v84
	v_rcp_f32_e32 v85, v85
	v_pk_mul_f32 v[78:79], v[76:77], v[74:75]
	v_pk_mul_f32 v[76:77], v[86:87], v[0:1]
	v_pk_mul_f32 v[74:75], v[82:83], v[80:81]
	v_pk_mul_f32 v[80:81], v[84:85], v[2:3]
	v_cvt_pk_bf16_f32 v146, v78, v79
	v_cvt_pk_bf16_f32 v144, v76, v77
	v_cvt_pk_bf16_f32 v143, v74, v75
	s_nop 0
	v_cvt_pk_bf16_f32 v141, v80, v81
	s_waitcnt vmcnt(6)
	v_mov_b32_e32 v0, v204
	v_mov_b32_e32 v1, v205
	v_mov_b32_e32 v2, v206
	v_mov_b32_e32 v3, v207
	v_lshlrev_b32_e32 v82, 16, v0
	v_and_b32_e32 v83, 0xffff0000, v0
	v_lshlrev_b32_e32 v0, 16, v1
	v_and_b32_e32 v1, 0xffff0000, v1
	v_lshlrev_b32_e32 v84, 16, v2
	v_and_b32_e32 v85, 0xffff0000, v2
	v_lshlrev_b32_e32 v2, 16, v3
	v_and_b32_e32 v3, 0xffff0000, v3
	v_pk_mul_f32 v[86:87], v[82:83], v[82:83]
	v_pk_mul_f32 v[88:89], v[0:1], v[0:1]
	v_pk_mul_f32 v[90:91], v[84:85], v[84:85]
	v_pk_mul_f32 v[92:93], v[2:3], v[2:3]
	v_pk_fma_f32 v[86:87], v[86:87], s[42:43], 1.0 op_sel_hi:[1,0,0]
	v_pk_fma_f32 v[88:89], v[88:89], s[42:43], 1.0 op_sel_hi:[1,0,0]
	v_pk_fma_f32 v[90:91], v[90:91], s[42:43], 1.0 op_sel_hi:[1,0,0]
	v_pk_fma_f32 v[92:93], v[92:93], s[42:43], 1.0 op_sel_hi:[1,0,0]
	v_pk_mul_f32 v[86:87], v[86:87], v[82:83]
	v_pk_mul_f32 v[88:89], v[88:89], v[0:1]
	v_pk_mul_f32 v[90:91], v[90:91], v[84:85]
	v_pk_mul_f32 v[92:93], v[92:93], v[2:3]
	v_pk_mul_f32 v[86:87], v[86:87], s[10:11] op_sel_hi:[1,0]
	v_pk_mul_f32 v[88:89], v[88:89], s[10:11] op_sel_hi:[1,0]
	v_pk_mul_f32 v[90:91], v[90:91], s[10:11] op_sel_hi:[1,0]
	v_pk_mul_f32 v[92:93], v[92:93], s[10:11] op_sel_hi:[1,0]
	v_exp_f32_e32 v86, v86
	v_exp_f32_e32 v87, v87
	v_exp_f32_e32 v88, v88
	v_exp_f32_e32 v89, v89
	v_exp_f32_e32 v90, v90
	v_exp_f32_e32 v91, v91
	v_exp_f32_e32 v92, v92
	v_exp_f32_e32 v93, v93
	v_pk_add_f32 v[86:87], v[86:87], 1.0 op_sel_hi:[1,0]
	v_pk_add_f32 v[88:89], v[88:89], 1.0 op_sel_hi:[1,0]
	v_pk_add_f32 v[90:91], v[90:91], 1.0 op_sel_hi:[1,0]
	v_pk_add_f32 v[92:93], v[92:93], 1.0 op_sel_hi:[1,0]
	v_rcp_f32_e32 v86, v86
	v_rcp_f32_e32 v87, v87
	v_rcp_f32_e32 v88, v88
	v_rcp_f32_e32 v89, v89
	v_rcp_f32_e32 v94, v90
	v_rcp_f32_e32 v95, v91
	v_rcp_f32_e32 v92, v92
	v_rcp_f32_e32 v93, v93
	v_pk_mul_f32 v[90:91], v[86:87], v[82:83]
	v_pk_mul_f32 v[86:87], v[88:89], v[0:1]
	v_pk_mul_f32 v[84:85], v[94:95], v[84:85]
	v_pk_mul_f32 v[82:83], v[92:93], v[2:3]
	v_cvt_pk_bf16_f32 v149, v90, v91
	v_cvt_pk_bf16_f32 v148, v86, v87
	v_cvt_pk_bf16_f32 v147, v84, v85
	s_nop 0
	v_cvt_pk_bf16_f32 v145, v82, v83
	s_waitcnt vmcnt(5)
	v_mov_b32_e32 v0, v208
	v_mov_b32_e32 v1, v209
	v_mov_b32_e32 v2, v210
	v_mov_b32_e32 v3, v211
	v_lshlrev_b32_e32 v88, 16, v0
	v_and_b32_e32 v89, 0xffff0000, v0
	v_lshlrev_b32_e32 v0, 16, v1
	v_and_b32_e32 v1, 0xffff0000, v1
	v_lshlrev_b32_e32 v92, 16, v2
	v_and_b32_e32 v93, 0xffff0000, v2
	v_lshlrev_b32_e32 v2, 16, v3
	v_and_b32_e32 v3, 0xffff0000, v3
	v_pk_mul_f32 v[94:95], v[88:89], v[88:89]
	v_pk_mul_f32 v[96:97], v[0:1], v[0:1]
	v_pk_mul_f32 v[98:99], v[92:93], v[92:93]
	v_pk_mul_f32 v[100:101], v[2:3], v[2:3]
	v_pk_fma_f32 v[94:95], v[94:95], s[42:43], 1.0 op_sel_hi:[1,0,0]
	v_pk_fma_f32 v[96:97], v[96:97], s[42:43], 1.0 op_sel_hi:[1,0,0]
	v_pk_fma_f32 v[98:99], v[98:99], s[42:43], 1.0 op_sel_hi:[1,0,0]
	v_pk_fma_f32 v[100:101], v[100:101], s[42:43], 1.0 op_sel_hi:[1,0,0]
	v_pk_mul_f32 v[94:95], v[94:95], v[88:89]
	v_pk_mul_f32 v[96:97], v[96:97], v[0:1]
	v_pk_mul_f32 v[98:99], v[98:99], v[92:93]
	v_pk_mul_f32 v[100:101], v[100:101], v[2:3]
	v_pk_mul_f32 v[94:95], v[94:95], s[10:11] op_sel_hi:[1,0]
	v_pk_mul_f32 v[96:97], v[96:97], s[10:11] op_sel_hi:[1,0]
	v_pk_mul_f32 v[98:99], v[98:99], s[10:11] op_sel_hi:[1,0]
	v_pk_mul_f32 v[100:101], v[100:101], s[10:11] op_sel_hi:[1,0]
	v_exp_f32_e32 v94, v94
	v_exp_f32_e32 v95, v95
	v_exp_f32_e32 v96, v96
	v_exp_f32_e32 v97, v97
	v_exp_f32_e32 v98, v98
	v_exp_f32_e32 v99, v99
	v_exp_f32_e32 v100, v100
	v_exp_f32_e32 v101, v101
	v_pk_add_f32 v[94:95], v[94:95], 1.0 op_sel_hi:[1,0]
	v_pk_add_f32 v[96:97], v[96:97], 1.0 op_sel_hi:[1,0]
	v_pk_add_f32 v[98:99], v[98:99], 1.0 op_sel_hi:[1,0]
	v_pk_add_f32 v[100:101], v[100:101], 1.0 op_sel_hi:[1,0]
	v_rcp_f32_e32 v94, v94
	v_rcp_f32_e32 v95, v95
	v_rcp_f32_e32 v102, v96
	v_rcp_f32_e32 v103, v97
	v_rcp_f32_e32 v98, v98
	v_rcp_f32_e32 v99, v99
	v_rcp_f32_e32 v100, v100
	v_rcp_f32_e32 v101, v101
	v_pk_mul_f32 v[96:97], v[94:95], v[88:89]
	v_pk_mul_f32 v[94:95], v[102:103], v[0:1]
	v_pk_mul_f32 v[92:93], v[98:99], v[92:93]
	v_pk_mul_f32 v[98:99], v[100:101], v[2:3]
	v_cvt_pk_bf16_f32 v154, v96, v97
	v_cvt_pk_bf16_f32 v152, v94, v95
	v_cvt_pk_bf16_f32 v151, v92, v93
	v_mov_b32_e32 v89, 0
	v_cvt_pk_bf16_f32 v150, v98, v99
	v_mov_b32_e32 v88, v17
	v_pk_add_f32 v[6:7], v[6:7], v[88:89]
	v_mov_b32_e32 v17, v22
	v_pk_add_f32 v[6:7], v[10:11], v[6:7]
	v_pk_mul_f32 v[10:11], v[20:21], v[20:21]
	s_waitcnt vmcnt(4)
	v_mov_b32_e32 v0, v212
	v_mov_b32_e32 v1, v213
	v_mov_b32_e32 v2, v214
	v_mov_b32_e32 v3, v215
	v_lshlrev_b32_e32 v100, 16, v0
	v_and_b32_e32 v101, 0xffff0000, v0
	v_lshlrev_b32_e32 v0, 16, v1
	v_and_b32_e32 v1, 0xffff0000, v1
	v_lshlrev_b32_e32 v106, 16, v2
	v_and_b32_e32 v107, 0xffff0000, v2
	v_lshlrev_b32_e32 v2, 16, v3
	v_and_b32_e32 v3, 0xffff0000, v3
	v_pk_mul_f32 v[102:103], v[100:101], v[100:101]
	v_pk_mul_f32 v[104:105], v[0:1], v[0:1]
	v_pk_mul_f32 v[156:157], v[106:107], v[106:107]
	v_pk_mul_f32 v[158:159], v[2:3], v[2:3]
	v_pk_fma_f32 v[102:103], v[102:103], s[42:43], 1.0 op_sel_hi:[1,0,0]
	v_pk_fma_f32 v[104:105], v[104:105], s[42:43], 1.0 op_sel_hi:[1,0,0]
	v_pk_fma_f32 v[156:157], v[156:157], s[42:43], 1.0 op_sel_hi:[1,0,0]
	v_pk_fma_f32 v[158:159], v[158:159], s[42:43], 1.0 op_sel_hi:[1,0,0]
	v_pk_mul_f32 v[102:103], v[102:103], v[100:101]
	v_pk_mul_f32 v[104:105], v[104:105], v[0:1]
	v_pk_mul_f32 v[156:157], v[156:157], v[106:107]
	v_pk_mul_f32 v[158:159], v[158:159], v[2:3]
	v_pk_mul_f32 v[102:103], v[102:103], s[10:11] op_sel_hi:[1,0]
	v_pk_mul_f32 v[104:105], v[104:105], s[10:11] op_sel_hi:[1,0]
	v_pk_mul_f32 v[156:157], v[156:157], s[10:11] op_sel_hi:[1,0]
	v_pk_mul_f32 v[158:159], v[158:159], s[10:11] op_sel_hi:[1,0]
	v_exp_f32_e32 v102, v102
	v_exp_f32_e32 v103, v103
	v_exp_f32_e32 v104, v104
	v_exp_f32_e32 v105, v105
	v_exp_f32_e32 v156, v156
	v_exp_f32_e32 v157, v157
	v_exp_f32_e32 v158, v158
	v_exp_f32_e32 v159, v159
	v_pk_add_f32 v[102:103], v[102:103], 1.0 op_sel_hi:[1,0]
	v_pk_add_f32 v[104:105], v[104:105], 1.0 op_sel_hi:[1,0]
	v_pk_add_f32 v[156:157], v[156:157], 1.0 op_sel_hi:[1,0]
	v_pk_add_f32 v[158:159], v[158:159], 1.0 op_sel_hi:[1,0]
	v_rcp_f32_e32 v102, v102
	v_rcp_f32_e32 v103, v103
	v_rcp_f32_e32 v160, v104
	v_rcp_f32_e32 v161, v105
	v_rcp_f32_e32 v156, v156
	v_rcp_f32_e32 v157, v157
	v_rcp_f32_e32 v158, v158
	v_rcp_f32_e32 v159, v159
	v_pk_mul_f32 v[104:105], v[102:103], v[100:101]
	v_pk_mul_f32 v[102:103], v[160:161], v[0:1]
	v_pk_mul_f32 v[100:101], v[156:157], v[106:107]
	v_pk_mul_f32 v[106:107], v[158:159], v[2:3]
	v_cvt_pk_bf16_f32 v157, v104, v105
	v_cvt_pk_bf16_f32 v156, v102, v103
	v_cvt_pk_bf16_f32 v155, v100, v101
	v_pk_mul_f32 v[160:161], v[8:9], v[8:9]
	v_cvt_pk_bf16_f32 v153, v106, v107
	v_mov_b32_e32 v166, v160
	v_mov_b32_e32 v8, v161
	v_pk_add_f32 v[8:9], v[166:167], v[8:9]
	v_mov_b32_e32 v161, v20
	v_pk_add_f32 v[6:7], v[8:9], v[6:7]
	v_pk_mul_f32 v[8:9], v[22:23], v[22:23]
	v_pk_add_f32 v[6:7], v[12:13], v[6:7]
	v_mov_b32_e32 v16, v8
	v_mov_b32_e32 v22, v9
	v_pk_mul_f32 v[12:13], v[18:19], v[18:19]
	v_mov_b32_e32 v160, v10
	v_mov_b32_e32 v20, v11
	v_pk_add_f32 v[8:9], v[16:17], v[22:23]
	v_mov_b32_e32 v162, v12
	v_mov_b32_e32 v18, v13
	v_pk_add_f32 v[10:11], v[160:161], v[20:21]
	v_pk_add_f32 v[6:7], v[6:7], v[8:9]
	v_pk_add_f32 v[12:13], v[162:163], v[18:19]
	v_pk_add_f32 v[6:7], v[10:11], v[6:7]
	v_pk_mul_f32 v[8:9], v[30:31], v[30:31]
	v_pk_add_f32 v[6:7], v[12:13], v[6:7]
	v_mov_b32_e32 v11, v30
	v_pk_mul_f32 v[12:13], v[28:29], v[28:29]
	v_mov_b32_e32 v10, v8
	v_mov_b32_e32 v30, v9
	v_pk_add_f32 v[6:7], v[14:15], v[6:7]
	v_mov_b32_e32 v15, v28
	v_pk_mul_f32 v[16:17], v[26:27], v[26:27]
	v_mov_b32_e32 v14, v12
	v_mov_b32_e32 v28, v13
	v_pk_add_f32 v[8:9], v[10:11], v[30:31]
	v_pk_mul_f32 v[18:19], v[32:33], v[32:33]
	v_mov_b32_e32 v21, v26
	v_mov_b32_e32 v20, v16
	v_mov_b32_e32 v26, v17
	v_pk_add_f32 v[10:11], v[14:15], v[28:29]
	v_pk_add_f32 v[6:7], v[6:7], v[8:9]
	v_mov_b32_e32 v23, v32
	v_mov_b32_e32 v22, v18
	v_mov_b32_e32 v32, v19
	v_pk_add_f32 v[12:13], v[20:21], v[26:27]
	v_pk_add_f32 v[6:7], v[10:11], v[6:7]
	v_pk_add_f32 v[14:15], v[22:23], v[32:33]
	v_pk_add_f32 v[6:7], v[12:13], v[6:7]
	v_pk_mul_f32 v[16:17], v[38:39], v[38:39]
	v_pk_add_f32 v[14:15], v[14:15], v[6:7]
	v_mov_b32_e32 v31, v38
	v_mov_b32_e32 v30, v16
	v_mov_b32_e32 v38, v17
	v_pk_mul_f32 v[26:27], v[34:35], v[34:35]
	v_mov_b32_e32 v33, v36
	v_mov_b32_e32 v32, v24
	v_mov_b32_e32 v36, v25
	v_pk_add_f32 v[16:17], v[30:31], v[38:39]
	v_pk_mul_f32 v[28:29], v[40:41], v[40:41]
	v_mov_b32_e32 v161, v34
	v_mov_b32_e32 v160, v26
	v_mov_b32_e32 v34, v27
	v_pk_add_f32 v[24:25], v[32:33], v[36:37]
	v_pk_add_f32 v[14:15], v[14:15], v[16:17]
	v_mov_b32_e32 v163, v40
	v_mov_b32_e32 v162, v28
	v_mov_b32_e32 v40, v29
	v_pk_add_f32 v[26:27], v[160:161], v[34:35]
	v_pk_add_f32 v[14:15], v[24:25], v[14:15]
	v_pk_mul_f32 v[16:17], v[46:47], v[46:47]
	v_pk_add_f32 v[28:29], v[162:163], v[40:41]
	v_pk_add_f32 v[14:15], v[26:27], v[14:15]
	v_pk_mul_f32 v[24:25], v[44:45], v[44:45]
	v_mov_b32_e32 v31, v46
	v_mov_b32_e32 v30, v16
	v_mov_b32_e32 v46, v17
	v_pk_add_f32 v[14:15], v[28:29], v[14:15]
	v_pk_mul_f32 v[26:27], v[42:43], v[42:43]
	v_mov_b32_e32 v33, v44
	v_mov_b32_e32 v32, v24
	v_mov_b32_e32 v44, v25
	v_pk_add_f32 v[16:17], v[30:31], v[46:47]
	v_pk_mul_f32 v[28:29], v[48:49], v[48:49]
	s_waitcnt vmcnt(3)
	v_mov_b32_e32 v0, v216
	v_mov_b32_e32 v1, v217
	v_mov_b32_e32 v2, v218
	v_mov_b32_e32 v3, v219
	v_lshlrev_b32_e32 v6, 16, v0
	v_and_b32_e32 v7, 0xffff0000, v0
	v_lshlrev_b32_e32 v0, 16, v1
	v_and_b32_e32 v1, 0xffff0000, v1
	v_lshlrev_b32_e32 v10, 16, v2
	v_and_b32_e32 v11, 0xffff0000, v2
	v_lshlrev_b32_e32 v12, 16, v3
	v_and_b32_e32 v13, 0xffff0000, v3
	v_pk_mul_f32 v[2:3], v[6:7], v[6:7]
	v_pk_mul_f32 v[8:9], v[0:1], v[0:1]
	v_pk_mul_f32 v[18:19], v[10:11], v[10:11]
	v_pk_mul_f32 v[20:21], v[12:13], v[12:13]
	v_pk_fma_f32 v[2:3], v[2:3], s[42:43], 1.0 op_sel_hi:[1,0,0]
	v_pk_fma_f32 v[8:9], v[8:9], s[42:43], 1.0 op_sel_hi:[1,0,0]
	v_pk_fma_f32 v[18:19], v[18:19], s[42:43], 1.0 op_sel_hi:[1,0,0]
	v_pk_fma_f32 v[20:21], v[20:21], s[42:43], 1.0 op_sel_hi:[1,0,0]
	v_pk_mul_f32 v[2:3], v[2:3], v[6:7]
	v_pk_mul_f32 v[8:9], v[8:9], v[0:1]
	v_pk_mul_f32 v[18:19], v[18:19], v[10:11]
	v_pk_mul_f32 v[20:21], v[20:21], v[12:13]
	v_pk_mul_f32 v[2:3], v[2:3], s[10:11] op_sel_hi:[1,0]
	v_pk_mul_f32 v[8:9], v[8:9], s[10:11] op_sel_hi:[1,0]
	v_pk_mul_f32 v[18:19], v[18:19], s[10:11] op_sel_hi:[1,0]
	v_pk_mul_f32 v[20:21], v[20:21], s[10:11] op_sel_hi:[1,0]
	v_exp_f32_e32 v2, v2
	v_exp_f32_e32 v3, v3
	v_exp_f32_e32 v8, v8
	v_exp_f32_e32 v9, v9
	v_exp_f32_e32 v18, v18
	v_exp_f32_e32 v19, v19
	v_exp_f32_e32 v20, v20
	v_exp_f32_e32 v21, v21
	v_pk_add_f32 v[2:3], v[2:3], 1.0 op_sel_hi:[1,0]
	v_pk_add_f32 v[8:9], v[8:9], 1.0 op_sel_hi:[1,0]
	v_pk_add_f32 v[18:19], v[18:19], 1.0 op_sel_hi:[1,0]
	v_pk_add_f32 v[20:21], v[20:21], 1.0 op_sel_hi:[1,0]
	v_rcp_f32_e32 v2, v2
	v_rcp_f32_e32 v3, v3
	v_rcp_f32_e32 v22, v8
	v_rcp_f32_e32 v23, v9
	v_rcp_f32_e32 v18, v18
	v_rcp_f32_e32 v19, v19
	v_rcp_f32_e32 v20, v20
	v_rcp_f32_e32 v21, v21
	v_pk_mul_f32 v[8:9], v[2:3], v[6:7]
	v_pk_mul_f32 v[6:7], v[22:23], v[0:1]
	v_pk_mul_f32 v[2:3], v[18:19], v[10:11]
	v_pk_mul_f32 v[0:1], v[20:21], v[12:13]
	v_cvt_pk_bf16_f32 v22, v8, v9
	v_cvt_pk_bf16_f32 v20, v6, v7
	v_cvt_pk_bf16_f32 v19, v2, v3
	v_mov_b32_e32 v35, v42
	v_cvt_pk_bf16_f32 v18, v0, v1
	v_mov_b32_e32 v34, v26
	v_mov_b32_e32 v42, v27
	v_pk_add_f32 v[24:25], v[32:33], v[44:45]
	v_pk_add_f32 v[14:15], v[14:15], v[16:17]
	v_mov_b32_e32 v37, v48
	v_mov_b32_e32 v36, v28
	v_mov_b32_e32 v48, v29
	v_pk_add_f32 v[26:27], v[34:35], v[42:43]
	v_pk_add_f32 v[14:15], v[24:25], v[14:15]
	v_pk_mul_f32 v[16:17], v[54:55], v[54:55]
	v_pk_add_f32 v[28:29], v[36:37], v[48:49]
	v_pk_add_f32 v[14:15], v[26:27], v[14:15]
	v_mov_b32_e32 v25, v54
	v_pk_mul_f32 v[26:27], v[52:53], v[52:53]
	v_mov_b32_e32 v24, v16
	v_mov_b32_e32 v54, v17
	v_pk_add_f32 v[14:15], v[28:29], v[14:15]
	v_pk_mul_f32 v[28:29], v[50:51], v[50:51]
	v_mov_b32_e32 v33, v52
	v_mov_b32_e32 v32, v26
	v_mov_b32_e32 v52, v27
	v_pk_add_f32 v[16:17], v[24:25], v[54:55]
	v_pk_mul_f32 v[30:31], v[56:57], v[56:57]
	v_mov_b32_e32 v35, v50
	v_mov_b32_e32 v34, v28
	v_mov_b32_e32 v50, v29
	v_pk_add_f32 v[24:25], v[32:33], v[52:53]
	v_pk_add_f32 v[14:15], v[14:15], v[16:17]
	v_mov_b32_e32 v37, v56
	v_mov_b32_e32 v36, v30
	v_mov_b32_e32 v56, v31
	v_pk_add_f32 v[26:27], v[34:35], v[50:51]
	v_pk_add_f32 v[14:15], v[24:25], v[14:15]
	v_pk_add_f32 v[28:29], v[36:37], v[56:57]
	v_pk_add_f32 v[14:15], v[26:27], v[14:15]
	v_pk_mul_f32 v[16:17], v[60:61], v[60:61]
	v_pk_add_f32 v[32:33], v[28:29], v[14:15]
	v_pk_mul_f32 v[14:15], v[62:63], v[62:63]
	v_mov_b32_e32 v39, v62
	v_mov_b32_e32 v38, v14
	v_mov_b32_e32 v62, v15
	v_mov_b32_e32 v41, v60
	v_mov_b32_e32 v40, v16
	v_mov_b32_e32 v60, v17
	v_pk_mul_f32 v[34:35], v[58:59], v[58:59]
	v_pk_mul_f32 v[36:37], v[64:65], v[64:65]
	v_mov_b32_e32 v43, v58
	v_mov_b32_e32 v42, v34
	v_mov_b32_e32 v58, v35
	v_pk_add_f32 v[34:35], v[38:39], v[62:63]
	v_mov_b32_e32 v45, v64
	v_mov_b32_e32 v44, v36
	v_mov_b32_e32 v64, v37
	v_pk_add_f32 v[36:37], v[40:41], v[60:61]
	v_pk_add_f32 v[32:33], v[32:33], v[34:35]
	v_pk_add_f32 v[38:39], v[42:43], v[58:59]
	v_pk_add_f32 v[32:33], v[36:37], v[32:33]
	v_pk_add_f32 v[40:41], v[44:45], v[64:65]
	v_pk_add_f32 v[32:33], v[38:39], v[32:33]
	v_pk_mul_f32 v[34:35], v[70:71], v[70:71]
	v_pk_add_f32 v[32:33], v[40:41], v[32:33]
	v_pk_mul_f32 v[36:37], v[68:69], v[68:69]
	v_mov_b32_e32 v41, v70
	v_mov_b32_e32 v40, v34
	v_mov_b32_e32 v70, v35
	v_pk_mul_f32 v[38:39], v[66:67], v[66:67]
	v_mov_b32_e32 v43, v68
	v_mov_b32_e32 v42, v36
	v_mov_b32_e32 v68, v37
	v_pk_add_f32 v[34:35], v[40:41], v[70:71]
	v_mov_b32_e32 v45, v66
	v_mov_b32_e32 v44, v38
	v_mov_b32_e32 v66, v39
	v_pk_add_f32 v[36:37], v[42:43], v[68:69]
	v_pk_add_f32 v[32:33], v[32:33], v[34:35]
	v_mov_b32_e32 v49, v72
	v_pk_add_f32 v[38:39], v[44:45], v[66:67]
	v_pk_add_f32 v[32:33], v[36:37], v[32:33]
	v_pk_mul_f32 v[34:35], v[78:79], v[78:79]
	s_waitcnt vmcnt(2)
	v_mov_b32_e32 v10, v220
	v_mov_b32_e32 v11, v221
	v_mov_b32_e32 v12, v222
	v_mov_b32_e32 v13, v223
	v_lshlrev_b32_e32 v14, 16, v10
	v_and_b32_e32 v15, 0xffff0000, v10
	v_lshlrev_b32_e32 v10, 16, v11
	v_and_b32_e32 v11, 0xffff0000, v11
	v_lshlrev_b32_e32 v24, 16, v12
	v_and_b32_e32 v25, 0xffff0000, v12
	v_lshlrev_b32_e32 v26, 16, v13
	v_and_b32_e32 v27, 0xffff0000, v13
	v_pk_mul_f32 v[12:13], v[14:15], v[14:15]
	v_pk_mul_f32 v[16:17], v[10:11], v[10:11]
	v_pk_mul_f32 v[28:29], v[24:25], v[24:25]
	v_pk_mul_f32 v[30:31], v[26:27], v[26:27]
	v_pk_fma_f32 v[12:13], v[12:13], s[42:43], 1.0 op_sel_hi:[1,0,0]
	v_pk_fma_f32 v[16:17], v[16:17], s[42:43], 1.0 op_sel_hi:[1,0,0]
	v_pk_fma_f32 v[28:29], v[28:29], s[42:43], 1.0 op_sel_hi:[1,0,0]
	v_pk_fma_f32 v[30:31], v[30:31], s[42:43], 1.0 op_sel_hi:[1,0,0]
	v_pk_mul_f32 v[12:13], v[12:13], v[14:15]
	v_pk_mul_f32 v[16:17], v[16:17], v[10:11]
	v_pk_mul_f32 v[28:29], v[28:29], v[24:25]
	v_pk_mul_f32 v[30:31], v[30:31], v[26:27]
	v_pk_mul_f32 v[12:13], v[12:13], s[10:11] op_sel_hi:[1,0]
	v_pk_mul_f32 v[16:17], v[16:17], s[10:11] op_sel_hi:[1,0]
	v_pk_mul_f32 v[28:29], v[28:29], s[10:11] op_sel_hi:[1,0]
	v_pk_mul_f32 v[30:31], v[30:31], s[10:11] op_sel_hi:[1,0]
	v_exp_f32_e32 v12, v12
	v_exp_f32_e32 v13, v13
	v_exp_f32_e32 v16, v16
	v_exp_f32_e32 v17, v17
	v_exp_f32_e32 v28, v28
	v_exp_f32_e32 v29, v29
	v_exp_f32_e32 v30, v30
	v_exp_f32_e32 v31, v31
	v_pk_add_f32 v[12:13], v[12:13], 1.0 op_sel_hi:[1,0]
	v_pk_add_f32 v[16:17], v[16:17], 1.0 op_sel_hi:[1,0]
	v_pk_add_f32 v[28:29], v[28:29], 1.0 op_sel_hi:[1,0]
	v_pk_add_f32 v[30:31], v[30:31], 1.0 op_sel_hi:[1,0]
	v_rcp_f32_e32 v12, v12
	v_rcp_f32_e32 v13, v13
	v_rcp_f32_e32 v46, v16
	v_rcp_f32_e32 v47, v17
	v_rcp_f32_e32 v28, v28
	v_rcp_f32_e32 v29, v29
	v_rcp_f32_e32 v30, v30
	v_rcp_f32_e32 v31, v31
	v_pk_mul_f32 v[16:17], v[12:13], v[14:15]
	v_pk_mul_f32 v[14:15], v[46:47], v[10:11]
	v_pk_mul_f32 v[12:13], v[28:29], v[24:25]
	v_pk_mul_f32 v[10:11], v[30:31], v[26:27]
	v_cvt_pk_bf16_f32 v26, v16, v17
	v_cvt_pk_bf16_f32 v24, v14, v15
	v_cvt_pk_bf16_f32 v23, v12, v13
	v_pk_mul_f32 v[46:47], v[72:73], v[72:73]
	v_cvt_pk_bf16_f32 v21, v10, v11
	v_mov_b32_e32 v48, v46
	v_mov_b32_e32 v72, v47
	v_pk_add_f32 v[40:41], v[48:49], v[72:73]
	v_pk_add_f32 v[32:33], v[38:39], v[32:33]
	v_pk_mul_f32 v[36:37], v[76:77], v[76:77]
	v_mov_b32_e32 v43, v78
	v_mov_b32_e32 v42, v34
	v_mov_b32_e32 v78, v35
	v_pk_add_f32 v[32:33], v[40:41], v[32:33]
	v_pk_mul_f32 v[38:39], v[74:75], v[74:75]
	v_mov_b32_e32 v45, v76
	v_mov_b32_e32 v44, v36
	v_mov_b32_e32 v76, v37
	v_pk_add_f32 v[34:35], v[42:43], v[78:79]
	v_pk_mul_f32 v[40:41], v[80:81], v[80:81]
	v_mov_b32_e32 v47, v74
	v_mov_b32_e32 v46, v38
	v_mov_b32_e32 v74, v39
	v_pk_add_f32 v[36:37], v[44:45], v[76:77]
	v_pk_add_f32 v[32:33], v[32:33], v[34:35]
	v_mov_b32_e32 v49, v80
	v_mov_b32_e32 v48, v40
	v_mov_b32_e32 v80, v41
	v_pk_add_f32 v[38:39], v[46:47], v[74:75]
	v_pk_add_f32 v[32:33], v[36:37], v[32:33]
	v_pk_add_f32 v[40:41], v[48:49], v[80:81]
	v_pk_add_f32 v[32:33], v[38:39], v[32:33]
	v_pk_mul_f32 v[36:37], v[86:87], v[86:87]
	v_pk_add_f32 v[34:35], v[40:41], v[32:33]
	v_pk_mul_f32 v[32:33], v[90:91], v[90:91]
	v_pk_mul_f32 v[38:39], v[84:85], v[84:85]
	v_mov_b32_e32 v43, v90
	v_mov_b32_e32 v42, v32
	v_mov_b32_e32 v90, v33
	v_pk_mul_f32 v[40:41], v[82:83], v[82:83]
	v_mov_b32_e32 v45, v86
	v_mov_b32_e32 v47, v84
	v_mov_b32_e32 v44, v36
	v_mov_b32_e32 v86, v37
	v_mov_b32_e32 v46, v38
	v_mov_b32_e32 v84, v39
	v_pk_add_f32 v[36:37], v[42:43], v[90:91]
	v_mov_b32_e32 v49, v82
	v_mov_b32_e32 v48, v40
	v_mov_b32_e32 v82, v41
	v_pk_add_f32 v[38:39], v[44:45], v[86:87]
	v_pk_add_f32 v[40:41], v[46:47], v[84:85]
	v_pk_add_f32 v[34:35], v[34:35], v[36:37]
	v_pk_mul_f32 v[36:37], v[94:95], v[94:95]
	v_pk_add_f32 v[34:35], v[38:39], v[34:35]
	v_mov_b32_e32 v39, v96
	v_pk_add_f32 v[34:35], v[40:41], v[34:35]
	v_mov_b32_e32 v41, v94
	v_mov_b32_e32 v40, v36
	v_mov_b32_e32 v94, v37
	v_pk_mul_f32 v[54:55], v[98:99], v[98:99]
	v_pk_add_f32 v[36:37], v[40:41], v[94:95]
	v_mov_b32_e32 v57, v98
	v_mov_b32_e32 v56, v54
	v_mov_b32_e32 v98, v55
	v_pk_add_f32 v[40:41], v[56:57], v[98:99]
	v_mov_b32_e32 v55, v100
	v_mov_b32_e32 v57, v106
	v_mov_b32_e32 v158, s22
	v_pk_mul_f32 v[58:59], v[10:11], v[10:11]
	v_mov_b32_e32 v61, v12
	v_mov_b32_e32 v63, v10
	v_mov_b32_e32 v62, v58
	v_mov_b32_e32 v10, v59
	v_pk_add_f32 v[10:11], v[62:63], v[10:11]
	v_mov_b32_e32 v76, 0
	v_mov_b32_e32 v77, 0
	v_mov_b32_e32 v78, 0
	v_mov_b32_e32 v79, 0
	v_mov_b32_e32 v72, 0
	v_mov_b32_e32 v73, 0
	v_mov_b32_e32 v74, 0
	v_mov_b32_e32 v75, 0
	s_waitcnt vmcnt(1)
	v_mov_b32_e32 v28, v228
	v_mov_b32_e32 v29, v229
	v_mov_b32_e32 v30, v230
	v_mov_b32_e32 v31, v231
	v_lshlrev_b32_e32 v32, 16, v28
	v_and_b32_e32 v33, 0xffff0000, v28
	v_lshlrev_b32_e32 v28, 16, v29
	v_and_b32_e32 v29, 0xffff0000, v29
	v_lshlrev_b32_e32 v42, 16, v30
	v_and_b32_e32 v43, 0xffff0000, v30
	v_lshlrev_b32_e32 v30, 16, v31
	v_and_b32_e32 v31, 0xffff0000, v31
	v_pk_mul_f32 v[44:45], v[32:33], v[32:33]
	v_pk_mul_f32 v[46:47], v[28:29], v[28:29]
	v_pk_mul_f32 v[50:51], v[42:43], v[42:43]
	v_pk_mul_f32 v[52:53], v[30:31], v[30:31]
	v_pk_fma_f32 v[44:45], v[44:45], s[42:43], 1.0 op_sel_hi:[1,0,0]
	v_pk_fma_f32 v[46:47], v[46:47], s[42:43], 1.0 op_sel_hi:[1,0,0]
	v_pk_fma_f32 v[50:51], v[50:51], s[42:43], 1.0 op_sel_hi:[1,0,0]
	v_pk_fma_f32 v[52:53], v[52:53], s[42:43], 1.0 op_sel_hi:[1,0,0]
	v_pk_mul_f32 v[44:45], v[44:45], v[32:33]
	v_pk_mul_f32 v[46:47], v[46:47], v[28:29]
	v_pk_mul_f32 v[50:51], v[50:51], v[42:43]
	v_pk_mul_f32 v[52:53], v[52:53], v[30:31]
	v_pk_mul_f32 v[44:45], v[44:45], s[10:11] op_sel_hi:[1,0]
	v_pk_mul_f32 v[46:47], v[46:47], s[10:11] op_sel_hi:[1,0]
	v_pk_mul_f32 v[50:51], v[50:51], s[10:11] op_sel_hi:[1,0]
	v_pk_mul_f32 v[52:53], v[52:53], s[10:11] op_sel_hi:[1,0]
	v_exp_f32_e32 v44, v44
	v_exp_f32_e32 v45, v45
	v_exp_f32_e32 v46, v46
	v_exp_f32_e32 v47, v47
	v_exp_f32_e32 v50, v50
	v_exp_f32_e32 v51, v51
	v_exp_f32_e32 v52, v52
	v_exp_f32_e32 v53, v53
	v_pk_add_f32 v[44:45], v[44:45], 1.0 op_sel_hi:[1,0]
	v_pk_add_f32 v[46:47], v[46:47], 1.0 op_sel_hi:[1,0]
	v_pk_add_f32 v[50:51], v[50:51], 1.0 op_sel_hi:[1,0]
	v_pk_add_f32 v[52:53], v[52:53], 1.0 op_sel_hi:[1,0]
	v_rcp_f32_e32 v44, v44
	v_rcp_f32_e32 v45, v45
	v_rcp_f32_e32 v46, v46
	v_rcp_f32_e32 v47, v47
	v_rcp_f32_e32 v50, v50
	v_rcp_f32_e32 v51, v51
	v_rcp_f32_e32 v52, v52
	v_rcp_f32_e32 v53, v53
	v_pk_mul_f32 v[44:45], v[44:45], v[32:33]
	v_pk_mul_f32 v[46:47], v[46:47], v[28:29]
	v_pk_mul_f32 v[42:43], v[50:51], v[42:43]
	v_pk_mul_f32 v[50:51], v[52:53], v[30:31]
	v_cvt_pk_bf16_f32 v29, v44, v45
	v_cvt_pk_bf16_f32 v28, v46, v47
	v_cvt_pk_bf16_f32 v27, v42, v43
	v_mov_b32_e32 v53, v92
	v_cvt_pk_bf16_f32 v25, v50, v51
	v_pk_add_f32 v[4:5], v[48:49], v[82:83]
	v_pk_mul_f32 v[48:49], v[92:93], v[92:93]
	v_pk_add_f32 v[4:5], v[4:5], v[34:35]
	v_pk_mul_f32 v[34:35], v[96:97], v[96:97]
	v_mov_b32_e32 v52, v48
	v_mov_b32_e32 v38, v34
	v_mov_b32_e32 v96, v35
	v_pk_add_f32 v[34:35], v[38:39], v[96:97]
	v_mov_b32_e32 v92, v49
	v_pk_add_f32 v[4:5], v[4:5], v[34:35]
	v_pk_add_f32 v[38:39], v[52:53], v[92:93]
	v_pk_add_f32 v[4:5], v[36:37], v[4:5]
	v_pk_mul_f32 v[34:35], v[104:105], v[104:105]
	v_pk_add_f32 v[4:5], v[38:39], v[4:5]
	v_pk_mul_f32 v[36:37], v[102:103], v[102:103]
	v_mov_b32_e32 v49, v104
	v_mov_b32_e32 v48, v34
	v_mov_b32_e32 v104, v35
	v_pk_add_f32 v[4:5], v[40:41], v[4:5]
	v_pk_mul_f32 v[38:39], v[100:101], v[100:101]
	v_mov_b32_e32 v53, v102
	v_mov_b32_e32 v52, v36
	v_mov_b32_e32 v102, v37
	v_pk_add_f32 v[34:35], v[48:49], v[104:105]
	v_pk_mul_f32 v[40:41], v[106:107], v[106:107]
	v_mov_b32_e32 v54, v38
	v_mov_b32_e32 v100, v39
	v_pk_add_f32 v[36:37], v[52:53], v[102:103]
	v_pk_add_f32 v[4:5], v[4:5], v[34:35]
	v_mov_b32_e32 v56, v40
	v_mov_b32_e32 v106, v41
	v_pk_add_f32 v[38:39], v[54:55], v[100:101]
	v_pk_add_f32 v[4:5], v[36:37], v[4:5]
	v_pk_mul_f32 v[34:35], v[8:9], v[8:9]
	v_pk_add_f32 v[40:41], v[56:57], v[106:107]
	v_pk_add_f32 v[4:5], v[38:39], v[4:5]
	v_pk_mul_f32 v[36:37], v[6:7], v[6:7]
	v_mov_b32_e32 v49, v8
	v_mov_b32_e32 v48, v34
	v_mov_b32_e32 v8, v35
	v_pk_add_f32 v[4:5], v[40:41], v[4:5]
	v_pk_mul_f32 v[38:39], v[2:3], v[2:3]
	v_mov_b32_e32 v53, v6
	v_mov_b32_e32 v52, v36
	v_mov_b32_e32 v6, v37
	v_pk_add_f32 v[8:9], v[48:49], v[8:9]
	v_pk_mul_f32 v[40:41], v[0:1], v[0:1]
	v_mov_b32_e32 v55, v2
	v_mov_b32_e32 v54, v38
	v_mov_b32_e32 v2, v39
	v_pk_add_f32 v[6:7], v[52:53], v[6:7]
	v_pk_add_f32 v[4:5], v[4:5], v[8:9]
	v_mov_b32_e32 v57, v0
	v_mov_b32_e32 v56, v40
	v_mov_b32_e32 v0, v41
	v_pk_add_f32 v[2:3], v[54:55], v[2:3]
	v_pk_add_f32 v[4:5], v[6:7], v[4:5]
	v_pk_add_f32 v[0:1], v[56:57], v[0:1]
	v_pk_add_f32 v[2:3], v[2:3], v[4:5]
	v_pk_mul_f32 v[8:9], v[16:17], v[16:17]
	v_pk_add_f32 v[0:1], v[0:1], v[2:3]
	v_mov_b32_e32 v35, v16
	v_pk_mul_f32 v[52:53], v[14:15], v[14:15]
	v_mov_b32_e32 v34, v8
	v_mov_b32_e32 v16, v9
	v_mov_b32_e32 v55, v14
	v_pk_mul_f32 v[56:57], v[12:13], v[12:13]
	v_mov_b32_e32 v54, v52
	v_mov_b32_e32 v14, v53
	v_pk_add_f32 v[8:9], v[34:35], v[16:17]
	v_mov_b32_e32 v60, v56
	v_mov_b32_e32 v12, v57
	v_pk_add_f32 v[14:15], v[54:55], v[14:15]
	v_pk_add_f32 v[0:1], v[0:1], v[8:9]
	v_pk_add_f32 v[12:13], v[60:61], v[12:13]
	v_pk_add_f32 v[0:1], v[14:15], v[0:1]
	v_pk_mul_f32 v[8:9], v[44:45], v[44:45]
	v_pk_add_f32 v[0:1], v[12:13], v[0:1]
	v_mov_b32_e32 v17, v44
	s_waitcnt vmcnt(0)
	v_mov_b32_e32 v30, v232
	v_mov_b32_e32 v31, v233
	v_mov_b32_e32 v32, v234
	v_mov_b32_e32 v33, v235
	v_lshlrev_b32_e32 v2, 16, v30
	v_and_b32_e32 v3, 0xffff0000, v30
	v_lshlrev_b32_e32 v4, 16, v31
	v_and_b32_e32 v5, 0xffff0000, v31
	v_lshlrev_b32_e32 v6, 16, v32
	v_and_b32_e32 v7, 0xffff0000, v32
	v_lshlrev_b32_e32 v30, 16, v33
	v_and_b32_e32 v31, 0xffff0000, v33
	v_pk_mul_f32 v[32:33], v[2:3], v[2:3]
	v_pk_mul_f32 v[36:37], v[4:5], v[4:5]
	v_pk_mul_f32 v[38:39], v[6:7], v[6:7]
	v_pk_mul_f32 v[40:41], v[30:31], v[30:31]
	v_pk_fma_f32 v[32:33], v[32:33], s[42:43], 1.0 op_sel_hi:[1,0,0]
	v_pk_fma_f32 v[36:37], v[36:37], s[42:43], 1.0 op_sel_hi:[1,0,0]
	v_pk_fma_f32 v[38:39], v[38:39], s[42:43], 1.0 op_sel_hi:[1,0,0]
	v_pk_fma_f32 v[40:41], v[40:41], s[42:43], 1.0 op_sel_hi:[1,0,0]
	v_pk_mul_f32 v[32:33], v[32:33], v[2:3]
	v_pk_mul_f32 v[36:37], v[36:37], v[4:5]
	v_pk_mul_f32 v[38:39], v[38:39], v[6:7]
	v_pk_mul_f32 v[40:41], v[40:41], v[30:31]
	v_pk_mul_f32 v[32:33], v[32:33], s[10:11] op_sel_hi:[1,0]
	v_pk_mul_f32 v[36:37], v[36:37], s[10:11] op_sel_hi:[1,0]
	v_pk_mul_f32 v[38:39], v[38:39], s[10:11] op_sel_hi:[1,0]
	v_pk_mul_f32 v[40:41], v[40:41], s[10:11] op_sel_hi:[1,0]
	v_exp_f32_e32 v32, v32
	v_exp_f32_e32 v33, v33
	v_exp_f32_e32 v36, v36
	v_exp_f32_e32 v37, v37
	v_exp_f32_e32 v38, v38
	v_exp_f32_e32 v39, v39
	v_exp_f32_e32 v40, v40
	v_exp_f32_e32 v41, v41
	v_pk_add_f32 v[32:33], v[32:33], 1.0 op_sel_hi:[1,0]
	v_pk_add_f32 v[36:37], v[36:37], 1.0 op_sel_hi:[1,0]
	v_pk_add_f32 v[38:39], v[38:39], 1.0 op_sel_hi:[1,0]
	v_pk_add_f32 v[40:41], v[40:41], 1.0 op_sel_hi:[1,0]
	v_rcp_f32_e32 v32, v32
	v_rcp_f32_e32 v33, v33
	v_rcp_f32_e32 v36, v36
	v_rcp_f32_e32 v37, v37
	v_rcp_f32_e32 v38, v38
	v_rcp_f32_e32 v39, v39
	v_rcp_f32_e32 v40, v40
	v_rcp_f32_e32 v41, v41
	v_pk_mul_f32 v[32:33], v[32:33], v[2:3]
	v_pk_mul_f32 v[36:37], v[36:37], v[4:5]
	v_pk_mul_f32 v[38:39], v[38:39], v[6:7]
	v_pk_mul_f32 v[30:31], v[40:41], v[30:31]
	v_cvt_pk_bf16_f32 v6, v32, v33
	v_cvt_pk_bf16_f32 v5, v36, v37
	v_cvt_pk_bf16_f32 v4, v38, v39
	v_pk_add_f32 v[0:1], v[10:11], v[0:1]
	v_cvt_pk_bf16_f32 v3, v30, v31
	s_waitcnt lgkmcnt(0)
	ds_read_b128 v[172:175], v255 offset:0
	ds_read_b128 v[176:179], v255 offset:16
	ds_read_b128 v[180:183], v255 offset:32
	ds_read_b128 v[184:187], v255 offset:48
	ds_read_b128 v[188:191], v255 offset:64
	ds_read_b128 v[192:195], v255 offset:80
	ds_read_b128 v[196:199], v255 offset:96
	ds_read_b128 v[200:203], v255 offset:112
	ds_read_b128 v[204:207], v255 offset:128
	ds_read_b128 v[208:211], v255 offset:144
	ds_read_b128 v[212:215], v255 offset:160
	ds_read_b128 v[216:219], v255 offset:176
	ds_read_b128 v[220:223], v255 offset:192
	ds_read_b128 v[228:231], v255 offset:208
	ds_read_b128 v[232:235], v255 offset:224
	ds_read_b128 v[236:239], v255 offset:240
	v_pk_mul_f32 v[10:11], v[46:47], v[46:47]
	v_mov_b32_e32 v16, v8
	v_mov_b32_e32 v44, v9
	v_pk_mul_f32 v[12:13], v[42:43], v[42:43]
	v_mov_b32_e32 v35, v46
	v_mov_b32_e32 v34, v10
	v_mov_b32_e32 v46, v11
	v_pk_add_f32 v[8:9], v[16:17], v[44:45]
	v_pk_mul_f32 v[14:15], v[50:51], v[50:51]
	v_mov_b32_e32 v53, v42
	v_mov_b32_e32 v52, v12
	v_mov_b32_e32 v42, v13
	v_pk_add_f32 v[10:11], v[34:35], v[46:47]
	v_pk_add_f32 v[0:1], v[0:1], v[8:9]
	v_mov_b32_e32 v55, v50
	v_mov_b32_e32 v54, v14
	v_mov_b32_e32 v50, v15
	v_pk_add_f32 v[12:13], v[52:53], v[42:43]
	v_pk_add_f32 v[0:1], v[10:11], v[0:1]
	v_pk_mul_f32 v[8:9], v[32:33], v[32:33]
	v_pk_add_f32 v[14:15], v[54:55], v[50:51]
	v_pk_add_f32 v[0:1], v[12:13], v[0:1]
	v_pk_mul_f32 v[10:11], v[36:37], v[36:37]
	v_mov_b32_e32 v17, v32
	v_mov_b32_e32 v16, v8
	v_mov_b32_e32 v32, v9
	v_pk_add_f32 v[0:1], v[14:15], v[0:1]
	v_pk_mul_f32 v[12:13], v[38:39], v[38:39]
	v_mov_b32_e32 v35, v36
	v_mov_b32_e32 v34, v10
	v_mov_b32_e32 v36, v11
	v_pk_add_f32 v[8:9], v[16:17], v[32:33]
	v_pk_mul_f32 v[14:15], v[30:31], v[30:31]
	v_mov_b32_e32 v43, v38
	v_mov_b32_e32 v42, v12
	v_mov_b32_e32 v38, v13
	v_pk_add_f32 v[10:11], v[34:35], v[36:37]
	v_pk_add_f32 v[0:1], v[0:1], v[8:9]
	v_mov_b32_e32 v45, v30
	v_mov_b32_e32 v44, v14
	v_mov_b32_e32 v30, v15
	v_pk_add_f32 v[12:13], v[42:43], v[38:39]
	v_pk_add_f32 v[0:1], v[10:11], v[0:1]
	v_pk_add_f32 v[14:15], v[44:45], v[30:31]
	v_pk_add_f32 v[0:1], v[12:13], v[0:1]
	v_lshlrev_b32_e32 v8, 16, v114
	v_pk_add_f32 v[0:1], v[14:15], v[0:1]
	v_and_b32_e32 v9, 0xffff0000, v114
	v_pk_mul_f32 v[0:1], v[0:1], s[44:45] op_sel_hi:[1,0]
	v_lshlrev_b32_e32 v12, 16, v112
	v_fma_f32 v2, -v1, v1, v0
	v_max_f32_e32 v2, 0, v2
	v_add_f32_e32 v2, 0x3727c5ac, v2
	v_rsq_f32_e32 v2, v2
	v_pk_add_f32 v[8:9], v[8:9], v[0:1] op_sel:[0,1] neg_lo:[0,1] neg_hi:[0,1]
	v_and_b32_e32 v13, 0xffff0000, v112
	s_mul_i32 s45, s45, 0x8a00
	v_pk_mul_f32 v[8:9], v[8:9], v[2:3] op_sel_hi:[1,0]
	v_pk_add_f32 v[12:13], v[12:13], v[0:1] op_sel:[0,1] neg_lo:[0,1] neg_hi:[0,1]
	s_add_i32 s26, s45, 0
	v_pk_mul_f32 v[12:13], v[12:13], v[2:3] op_sel_hi:[1,0]
	v_lshl_add_u32 v7, v109, 1, s26
	s_bfe_u32 s10, s11, 0x10006
	v_and_b32_e32 v15, 0xffff0000, v3
	s_and_b32 s11, 64, s11
	s_cmp_eq_u32 s10, 0
	s_waitcnt lgkmcnt(15)
	v_pk_fma_f32 v[8:9], v[172:173], v[8:9], v[174:175]
	s_nop 0
	v_cvt_pk_bf16_f32 v14, v8, v9
	ds_write_b16 v7, v14
	ds_write_b16_d16_hi v7, v14 offset:272
	s_waitcnt lgkmcnt(15)
	v_pk_fma_f32 v[8:9], v[176:177], v[12:13], v[178:179]
	s_nop 0
	v_cvt_pk_bf16_f32 v14, v8, v9
	v_lshlrev_b32_e32 v12, 16, v111
	v_and_b32_e32 v13, 0xffff0000, v111
	v_pk_add_f32 v[12:13], v[12:13], v[0:1] op_sel:[0,1] neg_lo:[0,1] neg_hi:[0,1]
	ds_write_b16 v7, v14 offset:544
	ds_write_b16_d16_hi v7, v14 offset:816
	v_pk_mul_f32 v[12:13], v[12:13], v[2:3] op_sel_hi:[1,0]
	s_waitcnt lgkmcnt(15)
	v_pk_fma_f32 v[8:9], v[180:181], v[12:13], v[182:183]
	s_nop 0
	v_cvt_pk_bf16_f32 v14, v8, v9
	v_lshlrev_b32_e32 v12, 16, v110
	v_and_b32_e32 v13, 0xffff0000, v110
	v_pk_add_f32 v[12:13], v[12:13], v[0:1] op_sel:[0,1] neg_lo:[0,1] neg_hi:[0,1]
	ds_write_b16 v7, v14 offset:1088
	ds_write_b16_d16_hi v7, v14 offset:1360
	v_pk_mul_f32 v[12:13], v[12:13], v[2:3] op_sel_hi:[1,0]
	s_waitcnt lgkmcnt(15)
	v_pk_fma_f32 v[8:9], v[184:185], v[12:13], v[186:187]
	s_nop 0
	v_cvt_pk_bf16_f32 v14, v8, v9
	v_lshlrev_b32_e32 v12, 16, v117
	v_and_b32_e32 v13, 0xffff0000, v117
	v_pk_add_f32 v[12:13], v[12:13], v[0:1] op_sel:[0,1] neg_lo:[0,1] neg_hi:[0,1]
	ds_write_b16 v7, v14 offset:1632
	ds_write_b16_d16_hi v7, v14 offset:1904
	v_pk_mul_f32 v[12:13], v[12:13], v[2:3] op_sel_hi:[1,0]
	s_waitcnt lgkmcnt(15)
	v_pk_fma_f32 v[8:9], v[188:189], v[12:13], v[190:191]
	s_nop 0
	v_cvt_pk_bf16_f32 v14, v8, v9
	v_lshlrev_b32_e32 v12, 16, v116
	v_and_b32_e32 v13, 0xffff0000, v116
	v_pk_add_f32 v[12:13], v[12:13], v[0:1] op_sel:[0,1] neg_lo:[0,1] neg_hi:[0,1]
	ds_write_b16 v7, v14 offset:2176
	ds_write_b16_d16_hi v7, v14 offset:2448
	v_pk_mul_f32 v[12:13], v[12:13], v[2:3] op_sel_hi:[1,0]
	s_waitcnt lgkmcnt(15)
	v_pk_fma_f32 v[8:9], v[12:13], v[192:193], v[194:195]
	s_nop 0
	v_cvt_pk_bf16_f32 v14, v8, v9
	v_lshlrev_b32_e32 v12, 16, v115
	v_and_b32_e32 v13, 0xffff0000, v115
	v_pk_add_f32 v[12:13], v[12:13], v[0:1] op_sel:[0,1] neg_lo:[0,1] neg_hi:[0,1]
	ds_write_b16 v7, v14 offset:2720
	ds_write_b16_d16_hi v7, v14 offset:2992
	v_pk_mul_f32 v[12:13], v[12:13], v[2:3] op_sel_hi:[1,0]
	v_bfe_u32 v115, v108, 5, 1
	v_lshlrev_b32_e32 v88, 5, v115
	s_waitcnt lgkmcnt(15)
	v_pk_fma_f32 v[8:9], v[12:13], v[196:197], v[198:199]
	s_nop 0
	v_cvt_pk_bf16_f32 v14, v8, v9
	v_lshlrev_b32_e32 v12, 16, v113
	v_and_b32_e32 v13, 0xffff0000, v113
	v_pk_add_f32 v[12:13], v[12:13], v[0:1] op_sel:[0,1] neg_lo:[0,1] neg_hi:[0,1]
	ds_write_b16 v7, v14 offset:3264
	ds_write_b16_d16_hi v7, v14 offset:3536
	v_pk_mul_f32 v[12:13], v[12:13], v[2:3] op_sel_hi:[1,0]
	s_waitcnt lgkmcnt(15)
	v_pk_fma_f32 v[8:9], v[12:13], v[200:201], v[202:203]
	s_nop 0
	v_cvt_pk_bf16_f32 v14, v8, v9
	ds_read_b128 v[172:175], v255 offset:256
	ds_read_b128 v[176:179], v255 offset:272
	ds_read_b128 v[180:183], v255 offset:288
	ds_read_b128 v[184:187], v255 offset:304
	ds_read_b128 v[188:191], v255 offset:320
	ds_read_b128 v[192:195], v255 offset:336
	ds_read_b128 v[196:199], v255 offset:352
	ds_read_b128 v[200:203], v255 offset:368
	v_lshlrev_b32_e32 v12, 16, v122
	v_and_b32_e32 v13, 0xffff0000, v122
	v_pk_add_f32 v[12:13], v[12:13], v[0:1] op_sel:[0,1] neg_lo:[0,1] neg_hi:[0,1]
	ds_write_b16 v7, v14 offset:3808
	ds_write_b16_d16_hi v7, v14 offset:4080
	v_pk_mul_f32 v[12:13], v[12:13], v[2:3] op_sel_hi:[1,0]
	s_waitcnt lgkmcnt(15)
	v_pk_fma_f32 v[8:9], v[12:13], v[204:205], v[206:207]
	s_nop 0
	v_cvt_pk_bf16_f32 v14, v8, v9
	v_lshlrev_b32_e32 v12, 16, v120
	v_and_b32_e32 v13, 0xffff0000, v120
	v_pk_add_f32 v[12:13], v[12:13], v[0:1] op_sel:[0,1] neg_lo:[0,1] neg_hi:[0,1]
	ds_write_b16 v7, v14 offset:4352
	ds_write_b16_d16_hi v7, v14 offset:4624
	v_pk_mul_f32 v[12:13], v[12:13], v[2:3] op_sel_hi:[1,0]
	s_waitcnt lgkmcnt(15)
	v_pk_fma_f32 v[8:9], v[12:13], v[208:209], v[210:211]
	s_nop 0
	v_cvt_pk_bf16_f32 v14, v8, v9
	v_lshlrev_b32_e32 v12, 16, v119
	v_and_b32_e32 v13, 0xffff0000, v119
	v_pk_add_f32 v[12:13], v[12:13], v[0:1] op_sel:[0,1] neg_lo:[0,1] neg_hi:[0,1]
	ds_write_b16 v7, v14 offset:4896
	ds_write_b16_d16_hi v7, v14 offset:5168
	v_pk_mul_f32 v[12:13], v[12:13], v[2:3] op_sel_hi:[1,0]
	s_waitcnt lgkmcnt(15)
	v_pk_fma_f32 v[8:9], v[12:13], v[212:213], v[214:215]
	s_nop 0
	v_cvt_pk_bf16_f32 v14, v8, v9
	v_lshlrev_b32_e32 v12, 16, v118
	v_and_b32_e32 v13, 0xffff0000, v118
	v_pk_add_f32 v[12:13], v[12:13], v[0:1] op_sel:[0,1] neg_lo:[0,1] neg_hi:[0,1]
	ds_write_b16 v7, v14 offset:5440
	ds_write_b16_d16_hi v7, v14 offset:5712
	v_pk_mul_f32 v[12:13], v[12:13], v[2:3] op_sel_hi:[1,0]
	v_and_b32_e32 v118, 31, v108
	s_waitcnt lgkmcnt(15)
	v_pk_fma_f32 v[8:9], v[12:13], v[216:217], v[218:219]
	s_nop 0
	v_cvt_pk_bf16_f32 v14, v8, v9
	v_lshlrev_b32_e32 v12, 16, v126
	v_and_b32_e32 v13, 0xffff0000, v126
	v_pk_add_f32 v[12:13], v[12:13], v[0:1] op_sel:[0,1] neg_lo:[0,1] neg_hi:[0,1]
	ds_write_b16 v7, v14 offset:5984
	ds_write_b16_d16_hi v7, v14 offset:6256
	v_pk_mul_f32 v[12:13], v[12:13], v[2:3] op_sel_hi:[1,0]
	s_waitcnt lgkmcnt(15)
	v_pk_fma_f32 v[8:9], v[12:13], v[220:221], v[222:223]
	s_nop 0
	v_cvt_pk_bf16_f32 v14, v8, v9
	v_lshlrev_b32_e32 v12, 16, v124
	v_and_b32_e32 v13, 0xffff0000, v124
	v_pk_add_f32 v[12:13], v[12:13], v[0:1] op_sel:[0,1] neg_lo:[0,1] neg_hi:[0,1]
	ds_write_b16 v7, v14 offset:6528
	ds_write_b16_d16_hi v7, v14 offset:6800
	v_pk_mul_f32 v[12:13], v[12:13], v[2:3] op_sel_hi:[1,0]
	v_lshl_or_b32 v124, s10, 5, v118
	s_waitcnt lgkmcnt(15)
	v_pk_fma_f32 v[8:9], v[12:13], v[228:229], v[230:231]
	s_nop 0
	v_cvt_pk_bf16_f32 v14, v8, v9
	v_lshlrev_b32_e32 v12, 16, v123
	v_and_b32_e32 v13, 0xffff0000, v123
	v_pk_add_f32 v[12:13], v[12:13], v[0:1] op_sel:[0,1] neg_lo:[0,1] neg_hi:[0,1]
	ds_write_b16 v7, v14 offset:7072
	ds_write_b16_d16_hi v7, v14 offset:7344
	v_pk_mul_f32 v[12:13], v[12:13], v[2:3] op_sel_hi:[1,0]
	s_waitcnt lgkmcnt(15)
	v_pk_fma_f32 v[8:9], v[12:13], v[232:233], v[234:235]
	s_nop 0
	v_cvt_pk_bf16_f32 v14, v8, v9
	v_lshlrev_b32_e32 v12, 16, v121
	v_and_b32_e32 v13, 0xffff0000, v121
	v_pk_add_f32 v[12:13], v[12:13], v[0:1] op_sel:[0,1] neg_lo:[0,1] neg_hi:[0,1]
	ds_write_b16 v7, v14 offset:7616
	ds_write_b16_d16_hi v7, v14 offset:7888
	v_pk_mul_f32 v[12:13], v[12:13], v[2:3] op_sel_hi:[1,0]
	s_waitcnt lgkmcnt(15)
	v_pk_fma_f32 v[8:9], v[12:13], v[236:237], v[238:239]
	s_nop 0
	v_cvt_pk_bf16_f32 v14, v8, v9
	ds_read_b128 v[204:207], v255 offset:384
	ds_read_b128 v[208:211], v255 offset:400
	ds_read_b128 v[212:215], v255 offset:416
	ds_read_b128 v[216:219], v255 offset:432
	ds_read_b128 v[220:223], v255 offset:448
	ds_read_b128 v[228:231], v255 offset:464
	ds_read_b128 v[232:235], v255 offset:480
	ds_read_b128 v[236:239], v255 offset:496
	v_lshlrev_b32_e32 v12, 16, v129
	v_and_b32_e32 v13, 0xffff0000, v129
	v_pk_add_f32 v[12:13], v[12:13], v[0:1] op_sel:[0,1] neg_lo:[0,1] neg_hi:[0,1]
	ds_write_b16 v7, v14 offset:8160
	ds_write_b16_d16_hi v7, v14 offset:8432
	v_pk_mul_f32 v[12:13], v[12:13], v[2:3] op_sel_hi:[1,0]
	s_waitcnt lgkmcnt(15)
	v_pk_fma_f32 v[8:9], v[12:13], v[172:173], v[174:175]
	s_nop 0
	v_cvt_pk_bf16_f32 v14, v8, v9
	v_lshlrev_b32_e32 v12, 16, v128
	v_and_b32_e32 v13, 0xffff0000, v128
	v_pk_add_f32 v[12:13], v[12:13], v[0:1] op_sel:[0,1] neg_lo:[0,1] neg_hi:[0,1]
	ds_write_b16 v7, v14 offset:8704
	ds_write_b16_d16_hi v7, v14 offset:8976
	v_pk_mul_f32 v[12:13], v[12:13], v[2:3] op_sel_hi:[1,0]
	s_waitcnt lgkmcnt(15)
	v_pk_fma_f32 v[8:9], v[12:13], v[176:177], v[178:179]
	s_nop 0
	v_cvt_pk_bf16_f32 v14, v8, v9
	v_lshlrev_b32_e32 v12, 16, v127
	v_and_b32_e32 v13, 0xffff0000, v127
	v_pk_add_f32 v[12:13], v[12:13], v[0:1] op_sel:[0,1] neg_lo:[0,1] neg_hi:[0,1]
	ds_write_b16 v7, v14 offset:9248
	ds_write_b16_d16_hi v7, v14 offset:9520
	v_pk_mul_f32 v[12:13], v[12:13], v[2:3] op_sel_hi:[1,0]
	s_waitcnt lgkmcnt(15)
	v_pk_fma_f32 v[8:9], v[12:13], v[180:181], v[182:183]
	s_nop 0
	v_cvt_pk_bf16_f32 v14, v8, v9
	v_lshlrev_b32_e32 v12, 16, v125
	v_and_b32_e32 v13, 0xffff0000, v125
	v_pk_add_f32 v[12:13], v[12:13], v[0:1] op_sel:[0,1] neg_lo:[0,1] neg_hi:[0,1]
	ds_write_b16 v7, v14 offset:9792
	ds_write_b16_d16_hi v7, v14 offset:10064
	v_pk_mul_f32 v[12:13], v[12:13], v[2:3] op_sel_hi:[1,0]
	s_waitcnt lgkmcnt(15)
	v_pk_fma_f32 v[8:9], v[12:13], v[184:185], v[186:187]
	s_nop 0
	v_cvt_pk_bf16_f32 v14, v8, v9
	v_lshlrev_b32_e32 v12, 16, v134
	v_and_b32_e32 v13, 0xffff0000, v134
	v_pk_add_f32 v[12:13], v[12:13], v[0:1] op_sel:[0,1] neg_lo:[0,1] neg_hi:[0,1]
	ds_write_b16 v7, v14 offset:10336
	ds_write_b16_d16_hi v7, v14 offset:10608
	v_pk_mul_f32 v[12:13], v[12:13], v[2:3] op_sel_hi:[1,0]
	s_waitcnt lgkmcnt(15)
	v_pk_fma_f32 v[8:9], v[12:13], v[188:189], v[190:191]
	s_nop 0
	v_cvt_pk_bf16_f32 v14, v8, v9
	v_lshlrev_b32_e32 v12, 16, v132
	v_and_b32_e32 v13, 0xffff0000, v132
	v_pk_add_f32 v[12:13], v[12:13], v[0:1] op_sel:[0,1] neg_lo:[0,1] neg_hi:[0,1]
	ds_write_b16 v7, v14 offset:10880
	ds_write_b16_d16_hi v7, v14 offset:11152
	v_pk_mul_f32 v[12:13], v[12:13], v[2:3] op_sel_hi:[1,0]
	s_waitcnt lgkmcnt(15)
	v_pk_fma_f32 v[8:9], v[12:13], v[192:193], v[194:195]
	s_nop 0
	v_cvt_pk_bf16_f32 v14, v8, v9
	v_lshlrev_b32_e32 v12, 16, v131
	v_and_b32_e32 v13, 0xffff0000, v131
	v_pk_add_f32 v[12:13], v[12:13], v[0:1] op_sel:[0,1] neg_lo:[0,1] neg_hi:[0,1]
	ds_write_b16 v7, v14 offset:11424
	ds_write_b16_d16_hi v7, v14 offset:11696
	v_pk_mul_f32 v[12:13], v[12:13], v[2:3] op_sel_hi:[1,0]
	s_waitcnt lgkmcnt(15)
	v_pk_fma_f32 v[8:9], v[12:13], v[196:197], v[198:199]
	s_nop 0
	v_cvt_pk_bf16_f32 v14, v8, v9
	v_lshlrev_b32_e32 v12, 16, v130
	v_and_b32_e32 v13, 0xffff0000, v130
	v_pk_add_f32 v[12:13], v[12:13], v[0:1] op_sel:[0,1] neg_lo:[0,1] neg_hi:[0,1]
	ds_write_b16 v7, v14 offset:11968
	ds_write_b16_d16_hi v7, v14 offset:12240
	v_pk_mul_f32 v[12:13], v[12:13], v[2:3] op_sel_hi:[1,0]
	s_waitcnt lgkmcnt(15)
	v_pk_fma_f32 v[8:9], v[12:13], v[200:201], v[202:203]
	s_nop 0
	v_cvt_pk_bf16_f32 v14, v8, v9
	ds_read_b128 v[172:175], v255 offset:512
	ds_read_b128 v[176:179], v255 offset:528
	ds_read_b128 v[180:183], v255 offset:544
	ds_read_b128 v[184:187], v255 offset:560
	ds_read_b128 v[188:191], v255 offset:576
	ds_read_b128 v[192:195], v255 offset:592
	ds_read_b128 v[196:199], v255 offset:608
	ds_read_b128 v[200:203], v255 offset:624
	v_lshlrev_b32_e32 v12, 16, v137
	v_and_b32_e32 v13, 0xffff0000, v137
	v_pk_add_f32 v[12:13], v[12:13], v[0:1] op_sel:[0,1] neg_lo:[0,1] neg_hi:[0,1]
	ds_write_b16 v7, v14 offset:12512
	ds_write_b16_d16_hi v7, v14 offset:12784
	v_pk_mul_f32 v[12:13], v[12:13], v[2:3] op_sel_hi:[1,0]
	s_waitcnt lgkmcnt(15)
	v_pk_fma_f32 v[8:9], v[12:13], v[204:205], v[206:207]
	s_nop 0
	v_cvt_pk_bf16_f32 v14, v8, v9
	v_lshlrev_b32_e32 v12, 16, v136
	v_and_b32_e32 v13, 0xffff0000, v136
	v_pk_add_f32 v[12:13], v[12:13], v[0:1] op_sel:[0,1] neg_lo:[0,1] neg_hi:[0,1]
	ds_write_b16 v7, v14 offset:13056
	ds_write_b16_d16_hi v7, v14 offset:13328
	v_pk_mul_f32 v[12:13], v[12:13], v[2:3] op_sel_hi:[1,0]
	s_waitcnt lgkmcnt(15)
	v_pk_fma_f32 v[8:9], v[12:13], v[208:209], v[210:211]
	s_nop 0
	v_cvt_pk_bf16_f32 v14, v8, v9
	v_lshlrev_b32_e32 v12, 16, v135
	v_and_b32_e32 v13, 0xffff0000, v135
	v_pk_add_f32 v[12:13], v[12:13], v[0:1] op_sel:[0,1] neg_lo:[0,1] neg_hi:[0,1]
	ds_write_b16 v7, v14 offset:13600
	ds_write_b16_d16_hi v7, v14 offset:13872
	v_pk_mul_f32 v[12:13], v[12:13], v[2:3] op_sel_hi:[1,0]
	s_waitcnt lgkmcnt(15)
	v_pk_fma_f32 v[8:9], v[12:13], v[212:213], v[214:215]
	s_nop 0
	v_cvt_pk_bf16_f32 v14, v8, v9
	v_lshlrev_b32_e32 v12, 16, v133
	v_and_b32_e32 v13, 0xffff0000, v133
	v_pk_add_f32 v[12:13], v[12:13], v[0:1] op_sel:[0,1] neg_lo:[0,1] neg_hi:[0,1]
	ds_write_b16 v7, v14 offset:14144
	ds_write_b16_d16_hi v7, v14 offset:14416
	v_pk_mul_f32 v[12:13], v[12:13], v[2:3] op_sel_hi:[1,0]
	s_waitcnt lgkmcnt(15)
	v_pk_fma_f32 v[8:9], v[12:13], v[216:217], v[218:219]
	s_nop 0
	v_cvt_pk_bf16_f32 v14, v8, v9
	v_lshlrev_b32_e32 v12, 16, v142
	v_and_b32_e32 v13, 0xffff0000, v142
	v_pk_add_f32 v[12:13], v[12:13], v[0:1] op_sel:[0,1] neg_lo:[0,1] neg_hi:[0,1]
	ds_write_b16 v7, v14 offset:14688
	ds_write_b16_d16_hi v7, v14 offset:14960
	v_pk_mul_f32 v[12:13], v[12:13], v[2:3] op_sel_hi:[1,0]
	s_waitcnt lgkmcnt(15)
	v_pk_fma_f32 v[8:9], v[12:13], v[220:221], v[222:223]
	s_nop 0
	v_cvt_pk_bf16_f32 v14, v8, v9
	v_lshlrev_b32_e32 v12, 16, v140
	v_and_b32_e32 v13, 0xffff0000, v140
	v_pk_add_f32 v[12:13], v[12:13], v[0:1] op_sel:[0,1] neg_lo:[0,1] neg_hi:[0,1]
	ds_write_b16 v7, v14 offset:15232
	ds_write_b16_d16_hi v7, v14 offset:15504
	v_pk_mul_f32 v[12:13], v[12:13], v[2:3] op_sel_hi:[1,0]
	s_waitcnt lgkmcnt(15)
	v_pk_fma_f32 v[8:9], v[12:13], v[228:229], v[230:231]
	s_nop 0
	v_cvt_pk_bf16_f32 v14, v8, v9
	v_lshlrev_b32_e32 v12, 16, v139
	v_and_b32_e32 v13, 0xffff0000, v139
	v_pk_add_f32 v[12:13], v[12:13], v[0:1] op_sel:[0,1] neg_lo:[0,1] neg_hi:[0,1]
	ds_write_b16 v7, v14 offset:15776
	ds_write_b16_d16_hi v7, v14 offset:16048
	v_pk_mul_f32 v[12:13], v[12:13], v[2:3] op_sel_hi:[1,0]
	s_waitcnt lgkmcnt(15)
	v_pk_fma_f32 v[8:9], v[12:13], v[232:233], v[234:235]
	s_nop 0
	v_cvt_pk_bf16_f32 v14, v8, v9
	v_lshlrev_b32_e32 v12, 16, v138
	v_and_b32_e32 v13, 0xffff0000, v138
	v_pk_add_f32 v[12:13], v[12:13], v[0:1] op_sel:[0,1] neg_lo:[0,1] neg_hi:[0,1]
	ds_write_b16 v7, v14 offset:16320
	ds_write_b16_d16_hi v7, v14 offset:16592
	v_pk_mul_f32 v[12:13], v[12:13], v[2:3] op_sel_hi:[1,0]
	s_waitcnt lgkmcnt(15)
	v_pk_fma_f32 v[8:9], v[12:13], v[236:237], v[238:239]
	s_nop 0
	v_cvt_pk_bf16_f32 v14, v8, v9
	ds_read_b128 v[204:207], v255 offset:640
	ds_read_b128 v[208:211], v255 offset:656
	ds_read_b128 v[212:215], v255 offset:672
	ds_read_b128 v[216:219], v255 offset:688
	ds_read_b128 v[220:223], v255 offset:704
	ds_read_b128 v[228:231], v255 offset:720
	ds_read_b128 v[232:235], v255 offset:736
	ds_read_b128 v[236:239], v255 offset:752
	v_lshlrev_b32_e32 v12, 16, v146
	v_and_b32_e32 v13, 0xffff0000, v146
	v_pk_add_f32 v[12:13], v[12:13], v[0:1] op_sel:[0,1] neg_lo:[0,1] neg_hi:[0,1]
	ds_write_b16 v7, v14 offset:16864
	ds_write_b16_d16_hi v7, v14 offset:17136
	v_pk_mul_f32 v[12:13], v[12:13], v[2:3] op_sel_hi:[1,0]
	s_waitcnt lgkmcnt(15)
	v_pk_fma_f32 v[8:9], v[12:13], v[172:173], v[174:175]
	s_nop 0
	v_cvt_pk_bf16_f32 v14, v8, v9
	v_lshlrev_b32_e32 v12, 16, v144
	v_and_b32_e32 v13, 0xffff0000, v144
	v_pk_add_f32 v[12:13], v[12:13], v[0:1] op_sel:[0,1] neg_lo:[0,1] neg_hi:[0,1]
	ds_write_b16 v7, v14 offset:17408
	ds_write_b16_d16_hi v7, v14 offset:17680
	v_pk_mul_f32 v[12:13], v[12:13], v[2:3] op_sel_hi:[1,0]
	s_waitcnt lgkmcnt(15)
	v_pk_fma_f32 v[8:9], v[12:13], v[176:177], v[178:179]
	s_nop 0
	v_cvt_pk_bf16_f32 v14, v8, v9
	v_lshlrev_b32_e32 v12, 16, v143
	v_and_b32_e32 v13, 0xffff0000, v143
	v_pk_add_f32 v[12:13], v[12:13], v[0:1] op_sel:[0,1] neg_lo:[0,1] neg_hi:[0,1]
	ds_write_b16 v7, v14 offset:17952
	ds_write_b16_d16_hi v7, v14 offset:18224
	v_pk_mul_f32 v[12:13], v[12:13], v[2:3] op_sel_hi:[1,0]
	s_waitcnt lgkmcnt(15)
	v_pk_fma_f32 v[8:9], v[12:13], v[180:181], v[182:183]
	s_nop 0
	v_cvt_pk_bf16_f32 v14, v8, v9
	v_lshlrev_b32_e32 v12, 16, v141
	v_and_b32_e32 v13, 0xffff0000, v141
	v_pk_add_f32 v[12:13], v[12:13], v[0:1] op_sel:[0,1] neg_lo:[0,1] neg_hi:[0,1]
	ds_write_b16 v7, v14 offset:18496
	ds_write_b16_d16_hi v7, v14 offset:18768
	v_pk_mul_f32 v[12:13], v[12:13], v[2:3] op_sel_hi:[1,0]
	s_waitcnt lgkmcnt(15)
	v_pk_fma_f32 v[8:9], v[12:13], v[184:185], v[186:187]
	s_nop 0
	v_cvt_pk_bf16_f32 v14, v8, v9
	v_lshlrev_b32_e32 v12, 16, v149
	v_and_b32_e32 v13, 0xffff0000, v149
	v_pk_add_f32 v[12:13], v[12:13], v[0:1] op_sel:[0,1] neg_lo:[0,1] neg_hi:[0,1]
	ds_write_b16 v7, v14 offset:19040
	ds_write_b16_d16_hi v7, v14 offset:19312
	v_pk_mul_f32 v[12:13], v[12:13], v[2:3] op_sel_hi:[1,0]
	s_waitcnt lgkmcnt(15)
	v_pk_fma_f32 v[8:9], v[12:13], v[188:189], v[190:191]
	s_nop 0
	v_cvt_pk_bf16_f32 v14, v8, v9
	v_lshlrev_b32_e32 v12, 16, v148
	v_and_b32_e32 v13, 0xffff0000, v148
	v_pk_add_f32 v[12:13], v[12:13], v[0:1] op_sel:[0,1] neg_lo:[0,1] neg_hi:[0,1]
	ds_write_b16 v7, v14 offset:19584
	ds_write_b16_d16_hi v7, v14 offset:19856
	v_pk_mul_f32 v[12:13], v[12:13], v[2:3] op_sel_hi:[1,0]
	s_waitcnt lgkmcnt(15)
	v_pk_fma_f32 v[8:9], v[12:13], v[192:193], v[194:195]
	s_nop 0
	v_cvt_pk_bf16_f32 v14, v8, v9
	v_lshlrev_b32_e32 v12, 16, v147
	v_and_b32_e32 v13, 0xffff0000, v147
	v_pk_add_f32 v[12:13], v[12:13], v[0:1] op_sel:[0,1] neg_lo:[0,1] neg_hi:[0,1]
	ds_write_b16 v7, v14 offset:20128
	ds_write_b16_d16_hi v7, v14 offset:20400
	v_pk_mul_f32 v[12:13], v[12:13], v[2:3] op_sel_hi:[1,0]
	s_waitcnt lgkmcnt(15)
	v_pk_fma_f32 v[8:9], v[12:13], v[196:197], v[198:199]
	s_nop 0
	v_cvt_pk_bf16_f32 v14, v8, v9
	v_lshlrev_b32_e32 v12, 16, v145
	v_and_b32_e32 v13, 0xffff0000, v145
	v_pk_add_f32 v[12:13], v[12:13], v[0:1] op_sel:[0,1] neg_lo:[0,1] neg_hi:[0,1]
	ds_write_b16 v7, v14 offset:20672
	ds_write_b16_d16_hi v7, v14 offset:20944
	v_pk_mul_f32 v[12:13], v[12:13], v[2:3] op_sel_hi:[1,0]
	s_waitcnt lgkmcnt(15)
	v_pk_fma_f32 v[8:9], v[12:13], v[200:201], v[202:203]
	s_nop 0
	v_cvt_pk_bf16_f32 v14, v8, v9
	ds_read_b128 v[172:175], v255 offset:768
	ds_read_b128 v[176:179], v255 offset:784
	ds_read_b128 v[180:183], v255 offset:800
	ds_read_b128 v[184:187], v255 offset:816
	ds_read_b128 v[188:191], v255 offset:832
	ds_read_b128 v[192:195], v255 offset:848
	ds_read_b128 v[196:199], v255 offset:864
	ds_read_b128 v[200:203], v255 offset:880
	v_lshlrev_b32_e32 v12, 16, v154
	v_and_b32_e32 v13, 0xffff0000, v154
	v_pk_add_f32 v[12:13], v[12:13], v[0:1] op_sel:[0,1] neg_lo:[0,1] neg_hi:[0,1]
	ds_write_b16 v7, v14 offset:21216
	ds_write_b16_d16_hi v7, v14 offset:21488
	v_pk_mul_f32 v[12:13], v[12:13], v[2:3] op_sel_hi:[1,0]
	s_waitcnt lgkmcnt(15)
	v_pk_fma_f32 v[8:9], v[12:13], v[204:205], v[206:207]
	s_nop 0
	v_cvt_pk_bf16_f32 v14, v8, v9
	v_lshlrev_b32_e32 v12, 16, v152
	v_and_b32_e32 v13, 0xffff0000, v152
	v_pk_add_f32 v[12:13], v[12:13], v[0:1] op_sel:[0,1] neg_lo:[0,1] neg_hi:[0,1]
	ds_write_b16 v7, v14 offset:21760
	ds_write_b16_d16_hi v7, v14 offset:22032
	v_pk_mul_f32 v[12:13], v[12:13], v[2:3] op_sel_hi:[1,0]
	s_waitcnt lgkmcnt(15)
	v_pk_fma_f32 v[8:9], v[12:13], v[208:209], v[210:211]
	s_nop 0
	v_cvt_pk_bf16_f32 v14, v8, v9
	v_lshlrev_b32_e32 v12, 16, v151
	v_and_b32_e32 v13, 0xffff0000, v151
	v_pk_add_f32 v[12:13], v[12:13], v[0:1] op_sel:[0,1] neg_lo:[0,1] neg_hi:[0,1]
	ds_write_b16 v7, v14 offset:22304
	ds_write_b16_d16_hi v7, v14 offset:22576
	v_pk_mul_f32 v[12:13], v[12:13], v[2:3] op_sel_hi:[1,0]
	s_waitcnt lgkmcnt(15)
	v_pk_fma_f32 v[8:9], v[12:13], v[212:213], v[214:215]
	s_nop 0
	v_cvt_pk_bf16_f32 v14, v8, v9
	v_lshlrev_b32_e32 v12, 16, v150
	v_and_b32_e32 v13, 0xffff0000, v150
	v_pk_add_f32 v[12:13], v[12:13], v[0:1] op_sel:[0,1] neg_lo:[0,1] neg_hi:[0,1]
	ds_write_b16 v7, v14 offset:22848
	ds_write_b16_d16_hi v7, v14 offset:23120
	v_pk_mul_f32 v[12:13], v[12:13], v[2:3] op_sel_hi:[1,0]
	s_waitcnt lgkmcnt(15)
	v_pk_fma_f32 v[8:9], v[12:13], v[216:217], v[218:219]
	s_nop 0
	v_cvt_pk_bf16_f32 v14, v8, v9
	v_lshlrev_b32_e32 v12, 16, v157
	v_and_b32_e32 v13, 0xffff0000, v157
	v_pk_add_f32 v[12:13], v[12:13], v[0:1] op_sel:[0,1] neg_lo:[0,1] neg_hi:[0,1]
	ds_write_b16 v7, v14 offset:23392
	ds_write_b16_d16_hi v7, v14 offset:23664
	v_pk_mul_f32 v[12:13], v[12:13], v[2:3] op_sel_hi:[1,0]
	s_waitcnt lgkmcnt(15)
	v_pk_fma_f32 v[8:9], v[12:13], v[220:221], v[222:223]
	s_nop 0
	v_cvt_pk_bf16_f32 v14, v8, v9
	v_lshlrev_b32_e32 v12, 16, v156
	v_and_b32_e32 v13, 0xffff0000, v156
	v_pk_add_f32 v[12:13], v[12:13], v[0:1] op_sel:[0,1] neg_lo:[0,1] neg_hi:[0,1]
	ds_write_b16 v7, v14 offset:23936
	ds_write_b16_d16_hi v7, v14 offset:24208
	v_pk_mul_f32 v[12:13], v[12:13], v[2:3] op_sel_hi:[1,0]
	s_waitcnt lgkmcnt(15)
	v_pk_fma_f32 v[8:9], v[12:13], v[228:229], v[230:231]
	s_nop 0
	v_cvt_pk_bf16_f32 v14, v8, v9
	v_lshlrev_b32_e32 v12, 16, v155
	v_and_b32_e32 v13, 0xffff0000, v155
	v_pk_add_f32 v[12:13], v[12:13], v[0:1] op_sel:[0,1] neg_lo:[0,1] neg_hi:[0,1]
	ds_write_b16 v7, v14 offset:24480
	ds_write_b16_d16_hi v7, v14 offset:24752
	v_pk_mul_f32 v[12:13], v[12:13], v[2:3] op_sel_hi:[1,0]
	s_waitcnt lgkmcnt(15)
	v_pk_fma_f32 v[8:9], v[12:13], v[232:233], v[234:235]
	s_nop 0
	v_cvt_pk_bf16_f32 v14, v8, v9
	v_lshlrev_b32_e32 v12, 16, v153
	v_and_b32_e32 v13, 0xffff0000, v153
	v_pk_add_f32 v[12:13], v[12:13], v[0:1] op_sel:[0,1] neg_lo:[0,1] neg_hi:[0,1]
	ds_write_b16 v7, v14 offset:25024
	ds_write_b16_d16_hi v7, v14 offset:25296
	v_pk_mul_f32 v[12:13], v[12:13], v[2:3] op_sel_hi:[1,0]
	s_waitcnt lgkmcnt(15)
	v_pk_fma_f32 v[8:9], v[12:13], v[236:237], v[238:239]
	s_nop 0
	v_cvt_pk_bf16_f32 v14, v8, v9
	ds_read_b128 v[204:207], v255 offset:896
	ds_read_b128 v[208:211], v255 offset:912
	ds_read_b128 v[212:215], v255 offset:928
	ds_read_b128 v[216:219], v255 offset:944
	ds_read_b128 v[220:223], v255 offset:960
	ds_read_b128 v[228:231], v255 offset:976
	ds_read_b128 v[232:235], v255 offset:992
	ds_read_b128 v[236:239], v255 offset:1008
	v_lshlrev_b32_e32 v12, 16, v22
	v_and_b32_e32 v13, 0xffff0000, v22
	v_pk_add_f32 v[12:13], v[12:13], v[0:1] op_sel:[0,1] neg_lo:[0,1] neg_hi:[0,1]
	ds_write_b16 v7, v14 offset:25568
	ds_write_b16_d16_hi v7, v14 offset:25840
	v_pk_mul_f32 v[12:13], v[12:13], v[2:3] op_sel_hi:[1,0]
	s_waitcnt lgkmcnt(15)
	v_pk_fma_f32 v[8:9], v[12:13], v[172:173], v[174:175]
	s_nop 0
	v_cvt_pk_bf16_f32 v14, v8, v9
	v_lshlrev_b32_e32 v12, 16, v20
	v_and_b32_e32 v13, 0xffff0000, v20
	v_pk_add_f32 v[12:13], v[12:13], v[0:1] op_sel:[0,1] neg_lo:[0,1] neg_hi:[0,1]
	ds_write_b16 v7, v14 offset:26112
	ds_write_b16_d16_hi v7, v14 offset:26384
	v_pk_mul_f32 v[12:13], v[12:13], v[2:3] op_sel_hi:[1,0]
	s_waitcnt lgkmcnt(15)
	v_pk_fma_f32 v[8:9], v[12:13], v[176:177], v[178:179]
	s_nop 0
	v_cvt_pk_bf16_f32 v14, v8, v9
	v_lshlrev_b32_e32 v12, 16, v19
	v_and_b32_e32 v13, 0xffff0000, v19
	v_pk_add_f32 v[12:13], v[12:13], v[0:1] op_sel:[0,1] neg_lo:[0,1] neg_hi:[0,1]
	ds_write_b16 v7, v14 offset:26656
	ds_write_b16_d16_hi v7, v14 offset:26928
	v_pk_mul_f32 v[12:13], v[12:13], v[2:3] op_sel_hi:[1,0]
	s_waitcnt lgkmcnt(15)
	v_pk_fma_f32 v[8:9], v[12:13], v[180:181], v[182:183]
	s_nop 0
	v_cvt_pk_bf16_f32 v14, v8, v9
	v_lshlrev_b32_e32 v12, 16, v18
	v_and_b32_e32 v13, 0xffff0000, v18
	v_pk_add_f32 v[12:13], v[12:13], v[0:1] op_sel:[0,1] neg_lo:[0,1] neg_hi:[0,1]
	ds_write_b16 v7, v14 offset:27200
	ds_write_b16_d16_hi v7, v14 offset:27472
	v_pk_mul_f32 v[12:13], v[12:13], v[2:3] op_sel_hi:[1,0]
	s_waitcnt lgkmcnt(15)
	v_pk_fma_f32 v[8:9], v[12:13], v[184:185], v[186:187]
	s_nop 0
	v_cvt_pk_bf16_f32 v14, v8, v9
	v_lshlrev_b32_e32 v12, 16, v26
	v_and_b32_e32 v13, 0xffff0000, v26
	v_pk_add_f32 v[12:13], v[12:13], v[0:1] op_sel:[0,1] neg_lo:[0,1] neg_hi:[0,1]
	ds_write_b16 v7, v14 offset:27744
	ds_write_b16_d16_hi v7, v14 offset:28016
	v_pk_mul_f32 v[12:13], v[12:13], v[2:3] op_sel_hi:[1,0]
	s_waitcnt lgkmcnt(15)
	v_pk_fma_f32 v[8:9], v[12:13], v[188:189], v[190:191]
	s_nop 0
	v_cvt_pk_bf16_f32 v14, v8, v9
	v_lshlrev_b32_e32 v12, 16, v24
	v_and_b32_e32 v13, 0xffff0000, v24
	v_pk_add_f32 v[12:13], v[12:13], v[0:1] op_sel:[0,1] neg_lo:[0,1] neg_hi:[0,1]
	ds_write_b16 v7, v14 offset:28288
	ds_write_b16_d16_hi v7, v14 offset:28560
	v_pk_mul_f32 v[12:13], v[12:13], v[2:3] op_sel_hi:[1,0]
	s_waitcnt lgkmcnt(15)
	v_pk_fma_f32 v[8:9], v[12:13], v[192:193], v[194:195]
	s_nop 0
	v_cvt_pk_bf16_f32 v14, v8, v9
	v_lshlrev_b32_e32 v12, 16, v23
	v_and_b32_e32 v13, 0xffff0000, v23
	v_pk_add_f32 v[12:13], v[12:13], v[0:1] op_sel:[0,1] neg_lo:[0,1] neg_hi:[0,1]
	ds_write_b16 v7, v14 offset:28832
	ds_write_b16_d16_hi v7, v14 offset:29104
	v_pk_mul_f32 v[12:13], v[12:13], v[2:3] op_sel_hi:[1,0]
	s_waitcnt lgkmcnt(15)
	v_pk_fma_f32 v[8:9], v[12:13], v[196:197], v[198:199]
	s_nop 0
	v_cvt_pk_bf16_f32 v14, v8, v9
	v_lshlrev_b32_e32 v12, 16, v21
	v_and_b32_e32 v13, 0xffff0000, v21
	v_pk_add_f32 v[12:13], v[12:13], v[0:1] op_sel:[0,1] neg_lo:[0,1] neg_hi:[0,1]
	ds_write_b16 v7, v14 offset:29376
	ds_write_b16_d16_hi v7, v14 offset:29648
	v_pk_mul_f32 v[12:13], v[12:13], v[2:3] op_sel_hi:[1,0]
	s_waitcnt lgkmcnt(15)
	v_pk_fma_f32 v[8:9], v[12:13], v[200:201], v[202:203]
	s_nop 0
	v_cvt_pk_bf16_f32 v14, v8, v9
	v_lshlrev_b32_e32 v12, 16, v29
	v_and_b32_e32 v13, 0xffff0000, v29
	v_pk_add_f32 v[12:13], v[12:13], v[0:1] op_sel:[0,1] neg_lo:[0,1] neg_hi:[0,1]
	ds_write_b16 v7, v14 offset:29920
	ds_write_b16_d16_hi v7, v14 offset:30192
	v_pk_mul_f32 v[12:13], v[12:13], v[2:3] op_sel_hi:[1,0]
	s_waitcnt lgkmcnt(15)
	v_pk_fma_f32 v[8:9], v[12:13], v[204:205], v[206:207]
	s_nop 0
	v_cvt_pk_bf16_f32 v14, v8, v9
	v_lshlrev_b32_e32 v12, 16, v28
	v_and_b32_e32 v13, 0xffff0000, v28
	v_pk_add_f32 v[12:13], v[12:13], v[0:1] op_sel:[0,1] neg_lo:[0,1] neg_hi:[0,1]
	ds_write_b16 v7, v14 offset:30464
	ds_write_b16_d16_hi v7, v14 offset:30736
	v_pk_mul_f32 v[12:13], v[12:13], v[2:3] op_sel_hi:[1,0]
	s_waitcnt lgkmcnt(15)
	v_pk_fma_f32 v[8:9], v[12:13], v[208:209], v[210:211]
	s_nop 0
	v_cvt_pk_bf16_f32 v14, v8, v9
	v_lshlrev_b32_e32 v12, 16, v27
	v_and_b32_e32 v13, 0xffff0000, v27
	v_pk_add_f32 v[12:13], v[12:13], v[0:1] op_sel:[0,1] neg_lo:[0,1] neg_hi:[0,1]
	ds_write_b16 v7, v14 offset:31008
	ds_write_b16_d16_hi v7, v14 offset:31280
	v_pk_mul_f32 v[12:13], v[12:13], v[2:3] op_sel_hi:[1,0]
	s_waitcnt lgkmcnt(15)
	v_pk_fma_f32 v[8:9], v[12:13], v[212:213], v[214:215]
	s_nop 0
	v_cvt_pk_bf16_f32 v14, v8, v9
	v_lshlrev_b32_e32 v12, 16, v25
	v_and_b32_e32 v13, 0xffff0000, v25
	v_pk_add_f32 v[12:13], v[12:13], v[0:1] op_sel:[0,1] neg_lo:[0,1] neg_hi:[0,1]
	ds_write_b16 v7, v14 offset:31552
	ds_write_b16_d16_hi v7, v14 offset:31824
	v_pk_mul_f32 v[12:13], v[12:13], v[2:3] op_sel_hi:[1,0]
	s_waitcnt lgkmcnt(15)
	v_pk_fma_f32 v[8:9], v[12:13], v[216:217], v[218:219]
	s_nop 0
	v_cvt_pk_bf16_f32 v14, v8, v9
	v_lshlrev_b32_e32 v12, 16, v6
	v_and_b32_e32 v13, 0xffff0000, v6
	v_pk_add_f32 v[12:13], v[12:13], v[0:1] op_sel:[0,1] neg_lo:[0,1] neg_hi:[0,1]
	ds_write_b16 v7, v14 offset:32096
	ds_write_b16_d16_hi v7, v14 offset:32368
	v_pk_mul_f32 v[12:13], v[12:13], v[2:3] op_sel_hi:[1,0]
	v_lshlrev_b32_e32 v14, 16, v3
	s_waitcnt lgkmcnt(15)
	v_pk_fma_f32 v[8:9], v[12:13], v[220:221], v[222:223]
	s_nop 0
	v_cvt_pk_bf16_f32 v6, v8, v9
	v_lshlrev_b32_e32 v12, 16, v5
	v_and_b32_e32 v13, 0xffff0000, v5
	v_pk_add_f32 v[12:13], v[12:13], v[0:1] op_sel:[0,1] neg_lo:[0,1] neg_hi:[0,1]
	ds_write_b16 v7, v6 offset:32640
	ds_write_b16_d16_hi v7, v6 offset:32912
	v_pk_mul_f32 v[12:13], v[12:13], v[2:3] op_sel_hi:[1,0]
	s_waitcnt lgkmcnt(15)
	v_pk_fma_f32 v[8:9], v[12:13], v[228:229], v[230:231]
	s_nop 0
	v_cvt_pk_bf16_f32 v6, v8, v9
	v_lshlrev_b32_e32 v12, 16, v4
	v_and_b32_e32 v13, 0xffff0000, v4
	v_pk_add_f32 v[4:5], v[12:13], v[0:1] op_sel:[0,1] neg_lo:[0,1] neg_hi:[0,1]
	ds_write_b16 v7, v6 offset:33184
	ds_write_b16_d16_hi v7, v6 offset:33456
	v_pk_mul_f32 v[4:5], v[4:5], v[2:3] op_sel_hi:[1,0]
	v_pk_add_f32 v[0:1], v[14:15], v[0:1] op_sel:[0,1] neg_lo:[0,1] neg_hi:[0,1]
	s_waitcnt lgkmcnt(15)
	v_pk_fma_f32 v[4:5], v[4:5], v[232:233], v[234:235]
	s_nop 0
	v_cvt_pk_bf16_f32 v6, v4, v5
	s_mov_b64 s[12:13], 0x40000
	v_or_b32_e32 v10, s43, v124
	v_lshl_add_u64 v[8:9], s[16:17], 0, v[88:89]
	v_pk_mul_f32 v[0:1], v[0:1], v[2:3] op_sel_hi:[1,0]
	v_lshlrev_b32_e32 v88, 9, v10
	v_lshl_add_u64 v[90:91], v[8:9], 0, s[12:13]
	v_lshl_add_u64 v[8:9], v[90:91], 0, v[88:89]
	ds_write_b16 v7, v6 offset:33728
	ds_write_b16_d16_hi v7, v6 offset:34000
	s_cselect_b64 s[14:15], -1, 0
	s_cmp_lg_u32 s11, 0
	s_cselect_b64 s[12:13], -1, 0
	s_and_b64 vcc, exec, s[14:15]
	s_waitcnt lgkmcnt(15)
	v_pk_fma_f32 v[0:1], v[0:1], v[236:237], v[238:239]
	s_nop 0
	v_cvt_pk_bf16_f32 v0, v0, v1
	ds_write_b16 v7, v0 offset:34272
	ds_write_b16_d16_hi v7, v0 offset:34544
	s_waitcnt lgkmcnt(0)
	s_barrier
	global_load_dwordx4 v[0:3], v[8:9], off offset:16
	global_load_dwordx4 v[4:7], v[8:9], off
	global_load_dwordx4 v[80:83], v[8:9], off offset:80
	global_load_dwordx4 v[84:87], v[8:9], off offset:64
	s_cbranch_vccnz .LBB0_1274
	global_load_dwordx4 v[76:79], v[8:9], off offset:128
	global_load_dwordx4 v[72:75], v[8:9], off offset:144
